# K-loop tail SALU and per-segment pointer adds moved into the MFMA runs (on v12)
# baseline (speedup 1.0000x reference)
.LBB0_232:
	ds_read_b128 v[158:161], v152
	ds_read_b128 v[162:165], v152 offset:1024
	ds_read_b128 v[166:169], v152 offset:2048
	ds_read_b128 v[170:173], v152 offset:3072
	s_mov_b32 m0, s47
	v_lshl_add_u64 v[206:207], v[142:143], 0, s[34:35]
	ds_read_b128 v[174:177], v153
	ds_read_b128 v[178:181], v153 offset:1024
	ds_read_b128 v[182:185], v153 offset:2048
	ds_read_b128 v[186:189], v153 offset:3072
	ds_read_b128 v[190:193], v153 offset:4096
	ds_read_b128 v[194:197], v153 offset:5120
	ds_read_b128 v[198:201], v153 offset:6144
	ds_read_b128 v[202:205], v153 offset:7168
	global_load_lds_dwordx4 v[206:207], off
	s_mov_b32 m0, s48
	v_lshl_add_u64 v[206:207], v[144:145], 0, s[34:35]
	global_load_lds_dwordx4 v[206:207], off
	s_waitcnt lgkmcnt(8)
	s_barrier
	s_waitcnt lgkmcnt(0)
	v_mfma_f32_16x16x32_bf16 v[120:123], v[158:161], v[174:177], v[120:123]
	s_add_i32 s61, s34, 0xfffc0080
	v_mfma_f32_16x16x32_bf16 v[112:115], v[166:169], v[174:177], v[112:115]
	s_cmp_eq_u32 s19, 12
	v_mfma_f32_16x16x32_bf16 v[104:107], v[158:161], v[182:185], v[104:107]
	s_cselect_b64 s[36:37], -1, 0
	v_mfma_f32_16x16x32_bf16 v[96:99], v[166:169], v[182:185], v[96:99]
	s_and_b64 s[62:63], s[36:37], exec
	v_mfma_f32_16x16x32_bf16 v[88:91], v[158:161], v[190:193], v[88:91]
	s_cselect_b32 s61, 0, s61
	v_mfma_f32_16x16x32_bf16 v[80:83], v[166:169], v[190:193], v[80:83]
	s_and_b64 s[36:37], s[30:31], s[36:37]
	v_mfma_f32_16x16x32_bf16 v[72:75], v[158:161], v[198:201], v[72:75]
	s_and_b64 s[36:37], s[36:37], exec
	v_mfma_f32_16x16x32_bf16 v[60:63], v[166:169], v[198:201], v[60:63]
	s_cselect_b32 s63, s21, s27
	v_mfma_f32_16x16x32_bf16 v[120:123], v[162:165], v[178:181], v[120:123]
	s_cselect_b32 s62, s20, s26
	v_mfma_f32_16x16x32_bf16 v[112:115], v[170:173], v[178:181], v[112:115]
	s_cselect_b32 s37, s23, s29
	v_mfma_f32_16x16x32_bf16 v[104:107], v[162:165], v[186:189], v[104:107]
	s_cselect_b32 s36, s22, s28
	v_mfma_f32_16x16x32_bf16 v[96:99], v[170:173], v[186:189], v[96:99]
	v_mfma_f32_16x16x32_bf16 v[88:91], v[162:165], v[194:197], v[88:91]
	v_mfma_f32_16x16x32_bf16 v[80:83], v[170:173], v[194:197], v[80:83]
	s_add_u32 s36, s36, s61
	v_mfma_f32_16x16x32_bf16 v[72:75], v[162:165], v[202:205], v[72:75]
	s_addc_u32 s37, s37, 0
	v_mfma_f32_16x16x32_bf16 v[60:63], v[170:173], v[202:205], v[60:63]
	s_barrier
	s_mov_b32 m0, s49
	v_lshl_add_u64 v[218:219], s[36:37], 0, v[134:135]
	ds_read_b128 v[206:209], v154
	ds_read_b128 v[210:213], v154 offset:1024
	ds_read_b128 v[214:217], v154 offset:2048
	ds_read_b128 v[222:225], v154 offset:3072
	global_load_lds_dwordx4 v[218:219], off
	s_mov_b32 m0, s50
	v_lshl_add_u64 v[226:227], s[36:37], 0, v[130:131]
	global_load_lds_dwordx4 v[226:227], off
	s_barrier
	s_waitcnt lgkmcnt(0)
	v_mfma_f32_16x16x32_bf16 v[124:127], v[206:209], v[174:177], v[124:127]
	v_mfma_f32_16x16x32_bf16 v[116:119], v[214:217], v[174:177], v[116:119]
	v_mfma_f32_16x16x32_bf16 v[108:111], v[206:209], v[182:185], v[108:111]
	v_mfma_f32_16x16x32_bf16 v[100:103], v[214:217], v[182:185], v[100:103]
	v_mfma_f32_16x16x32_bf16 v[92:95], v[206:209], v[190:193], v[92:95]
	v_mfma_f32_16x16x32_bf16 v[84:87], v[214:217], v[190:193], v[84:87]
	v_mfma_f32_16x16x32_bf16 v[76:79], v[206:209], v[198:201], v[76:79]
	v_mfma_f32_16x16x32_bf16 v[64:67], v[214:217], v[198:201], v[64:67]
	v_mfma_f32_16x16x32_bf16 v[124:127], v[210:213], v[178:181], v[124:127]
	v_mfma_f32_16x16x32_bf16 v[116:119], v[222:225], v[178:181], v[116:119]
	v_mfma_f32_16x16x32_bf16 v[108:111], v[210:213], v[186:189], v[108:111]
	v_mfma_f32_16x16x32_bf16 v[100:103], v[222:225], v[186:189], v[100:103]
	v_mfma_f32_16x16x32_bf16 v[92:95], v[210:213], v[194:197], v[92:95]
	v_mfma_f32_16x16x32_bf16 v[84:87], v[222:225], v[194:197], v[84:87]
	s_add_u32 s62, s62, s61
	v_mfma_f32_16x16x32_bf16 v[76:79], v[210:213], v[202:205], v[76:79]
	s_addc_u32 s63, s63, 0
	v_mfma_f32_16x16x32_bf16 v[64:67], v[222:225], v[202:205], v[64:67]
	s_mov_b32 m0, s25
	v_lshl_add_u64 v[228:229], s[62:63], 0, v[136:137]
	s_barrier
	ds_read_b128 v[174:177], v153 offset:16384
	ds_read_b128 v[178:181], v153 offset:17408
	ds_read_b128 v[182:185], v153 offset:18432
	ds_read_b128 v[186:189], v153 offset:19456
	ds_read_b128 v[190:193], v153 offset:20480
	ds_read_b128 v[194:197], v153 offset:21504
	ds_read_b128 v[198:201], v153 offset:22528
	ds_read_b128 v[202:205], v153 offset:23552
	global_load_lds_dwordx4 v[228:229], off
	s_mov_b32 m0, s41
	v_lshl_add_u64 v[230:231], s[62:63], 0, v[132:133]
	global_load_lds_dwordx4 v[230:231], off
	s_barrier
	s_waitcnt lgkmcnt(0)
	v_mfma_f32_16x16x32_bf16 v[56:59], v[158:161], v[174:177], v[56:59]
	v_mfma_f32_16x16x32_bf16 v[48:51], v[166:169], v[174:177], v[48:51]
	v_mfma_f32_16x16x32_bf16 v[40:43], v[158:161], v[182:185], v[40:43]
	v_mfma_f32_16x16x32_bf16 v[32:35], v[166:169], v[182:185], v[32:35]
	v_mfma_f32_16x16x32_bf16 v[24:27], v[158:161], v[190:193], v[24:27]
	v_mfma_f32_16x16x32_bf16 v[16:19], v[166:169], v[190:193], v[16:19]
	v_mfma_f32_16x16x32_bf16 v[8:11], v[158:161], v[198:201], v[8:11]
	v_mfma_f32_16x16x32_bf16 v[0:3], v[166:169], v[198:201], v[0:3]
	v_mfma_f32_16x16x32_bf16 v[56:59], v[162:165], v[178:181], v[56:59]
	v_mfma_f32_16x16x32_bf16 v[48:51], v[170:173], v[178:181], v[48:51]
	v_mfma_f32_16x16x32_bf16 v[40:43], v[162:165], v[186:189], v[40:43]
	v_mfma_f32_16x16x32_bf16 v[32:35], v[170:173], v[186:189], v[32:35]
	v_mfma_f32_16x16x32_bf16 v[24:27], v[162:165], v[194:197], v[24:27]
	v_mfma_f32_16x16x32_bf16 v[16:19], v[170:173], v[194:197], v[16:19]
	s_add_u32 s64, s36, 0x40000
	v_mfma_f32_16x16x32_bf16 v[8:11], v[162:165], v[202:205], v[8:11]
	s_addc_u32 s65, s37, 0
	v_mfma_f32_16x16x32_bf16 v[0:3], v[170:173], v[202:205], v[0:3]
	s_barrier
	s_mov_b32 m0, s55
	v_lshl_add_u64 v[158:159], s[64:65], 0, v[134:135]
	global_load_lds_dwordx4 v[158:159], off
	s_mov_b32 m0, s56
	v_lshl_add_u64 v[158:159], s[64:65], 0, v[130:131]
	global_load_lds_dwordx4 v[158:159], off
	s_waitcnt vmcnt(6)
	s_barrier
	v_mfma_f32_16x16x32_bf16 v[68:71], v[206:209], v[174:177], v[68:71]
	v_mfma_f32_16x16x32_bf16 v[52:55], v[214:217], v[174:177], v[52:55]
	v_mfma_f32_16x16x32_bf16 v[44:47], v[206:209], v[182:185], v[44:47]
	v_mfma_f32_16x16x32_bf16 v[36:39], v[214:217], v[182:185], v[36:39]
	v_mfma_f32_16x16x32_bf16 v[28:31], v[206:209], v[190:193], v[28:31]
	v_mfma_f32_16x16x32_bf16 v[20:23], v[214:217], v[190:193], v[20:23]
	v_mfma_f32_16x16x32_bf16 v[12:15], v[206:209], v[198:201], v[12:15]
	v_mfma_f32_16x16x32_bf16 v[4:7], v[214:217], v[198:201], v[4:7]
	v_mfma_f32_16x16x32_bf16 v[68:71], v[210:213], v[178:181], v[68:71]
	v_mfma_f32_16x16x32_bf16 v[52:55], v[222:225], v[178:181], v[52:55]
	v_mfma_f32_16x16x32_bf16 v[44:47], v[210:213], v[186:189], v[44:47]
	v_mfma_f32_16x16x32_bf16 v[36:39], v[222:225], v[186:189], v[36:39]
	v_mfma_f32_16x16x32_bf16 v[28:31], v[210:213], v[194:197], v[28:31]
	v_mfma_f32_16x16x32_bf16 v[20:23], v[222:225], v[194:197], v[20:23]
	s_add_u32 s62, s62, 0x40000
	v_mfma_f32_16x16x32_bf16 v[12:15], v[210:213], v[202:205], v[12:15]
	s_addc_u32 s63, s63, 0
	v_mfma_f32_16x16x32_bf16 v[4:7], v[222:225], v[202:205], v[4:7]
	s_barrier
	ds_read_b128 v[158:161], v155
	ds_read_b128 v[162:165], v155 offset:1024
	ds_read_b128 v[166:169], v155 offset:2048
	ds_read_b128 v[170:173], v155 offset:3072
	s_mov_b32 m0, s42
	v_lshl_add_u64 v[206:207], s[62:63], 0, v[136:137]
	ds_read_b128 v[174:177], v153 offset:32768
	ds_read_b128 v[178:181], v153 offset:33792
	ds_read_b128 v[182:185], v153 offset:34816
	ds_read_b128 v[186:189], v153 offset:35840
	ds_read_b128 v[190:193], v153 offset:36864
	ds_read_b128 v[194:197], v153 offset:37888
	ds_read_b128 v[198:201], v153 offset:38912
	ds_read_b128 v[202:205], v153 offset:39936
	global_load_lds_dwordx4 v[206:207], off
	s_mov_b32 m0, s43
	v_lshl_add_u64 v[206:207], s[62:63], 0, v[132:133]
	global_load_lds_dwordx4 v[206:207], off
	s_waitcnt lgkmcnt(8)
	s_barrier
	s_waitcnt lgkmcnt(0)
	v_mfma_f32_16x16x32_bf16 v[120:123], v[158:161], v[174:177], v[120:123]
	v_mfma_f32_16x16x32_bf16 v[112:115], v[166:169], v[174:177], v[112:115]
	v_mfma_f32_16x16x32_bf16 v[104:107], v[158:161], v[182:185], v[104:107]
	v_mfma_f32_16x16x32_bf16 v[96:99], v[166:169], v[182:185], v[96:99]
	v_mfma_f32_16x16x32_bf16 v[88:91], v[158:161], v[190:193], v[88:91]
	v_mfma_f32_16x16x32_bf16 v[80:83], v[166:169], v[190:193], v[80:83]
	v_mfma_f32_16x16x32_bf16 v[72:75], v[158:161], v[198:201], v[72:75]
	v_mfma_f32_16x16x32_bf16 v[60:63], v[166:169], v[198:201], v[60:63]
	v_mfma_f32_16x16x32_bf16 v[120:123], v[162:165], v[178:181], v[120:123]
	v_mfma_f32_16x16x32_bf16 v[112:115], v[170:173], v[178:181], v[112:115]
	v_mfma_f32_16x16x32_bf16 v[104:107], v[162:165], v[186:189], v[104:107]
	v_mfma_f32_16x16x32_bf16 v[96:99], v[170:173], v[186:189], v[96:99]
	v_mfma_f32_16x16x32_bf16 v[88:91], v[162:165], v[194:197], v[88:91]
	v_mfma_f32_16x16x32_bf16 v[80:83], v[170:173], v[194:197], v[80:83]
	v_mfma_f32_16x16x32_bf16 v[72:75], v[162:165], v[202:205], v[72:75]
	v_mfma_f32_16x16x32_bf16 v[60:63], v[170:173], v[202:205], v[60:63]
	s_barrier
	s_mov_b32 m0, s57
	v_lshl_add_u64 v[218:219], v[218:219], 0, s[6:7]
	ds_read_b128 v[206:209], v156
	ds_read_b128 v[210:213], v156 offset:1024
	ds_read_b128 v[214:217], v156 offset:2048
	ds_read_b128 v[222:225], v156 offset:3072
	global_load_lds_dwordx4 v[218:219], off
	s_mov_b32 m0, s58
	v_lshl_add_u64 v[218:219], v[226:227], 0, s[6:7]
	global_load_lds_dwordx4 v[218:219], off
	s_barrier
	s_waitcnt lgkmcnt(0)
	v_mfma_f32_16x16x32_bf16 v[124:127], v[206:209], v[174:177], v[124:127]
	v_mfma_f32_16x16x32_bf16 v[116:119], v[214:217], v[174:177], v[116:119]
	v_mfma_f32_16x16x32_bf16 v[108:111], v[206:209], v[182:185], v[108:111]
	v_mfma_f32_16x16x32_bf16 v[100:103], v[214:217], v[182:185], v[100:103]
	v_mfma_f32_16x16x32_bf16 v[92:95], v[206:209], v[190:193], v[92:95]
	v_mfma_f32_16x16x32_bf16 v[84:87], v[214:217], v[190:193], v[84:87]
	v_mfma_f32_16x16x32_bf16 v[76:79], v[206:209], v[198:201], v[76:79]
	v_mfma_f32_16x16x32_bf16 v[64:67], v[214:217], v[198:201], v[64:67]
	v_mfma_f32_16x16x32_bf16 v[124:127], v[210:213], v[178:181], v[124:127]
	v_mfma_f32_16x16x32_bf16 v[116:119], v[222:225], v[178:181], v[116:119]
	v_mfma_f32_16x16x32_bf16 v[108:111], v[210:213], v[186:189], v[108:111]
	v_mfma_f32_16x16x32_bf16 v[100:103], v[222:225], v[186:189], v[100:103]
	v_mfma_f32_16x16x32_bf16 v[92:95], v[210:213], v[194:197], v[92:95]
	v_mfma_f32_16x16x32_bf16 v[84:87], v[222:225], v[194:197], v[84:87]
	v_mfma_f32_16x16x32_bf16 v[76:79], v[210:213], v[202:205], v[76:79]
	v_mfma_f32_16x16x32_bf16 v[64:67], v[222:225], v[202:205], v[64:67]
	s_mov_b32 m0, s44
	v_lshl_add_u64 v[218:219], v[228:229], 0, s[6:7]
	s_barrier
	ds_read_b128 v[174:177], v153 offset:49152
	ds_read_b128 v[178:181], v153 offset:50176
	ds_read_b128 v[182:185], v153 offset:51200
	ds_read_b128 v[186:189], v153 offset:52224
	ds_read_b128 v[190:193], v153 offset:53248
	ds_read_b128 v[194:197], v153 offset:54272
	ds_read_b128 v[198:201], v153 offset:55296
	ds_read_b128 v[202:205], v153 offset:56320
	global_load_lds_dwordx4 v[218:219], off
	s_mov_b32 m0, s45
	v_lshl_add_u64 v[218:219], v[230:231], 0, s[6:7]
	global_load_lds_dwordx4 v[218:219], off
	s_barrier
; __device__ __forceinline__ unsigned pk2(float lo, float hi) { unsigned r; asm volatile("v_cvt_pk_bf16_f32 %0, %1, %2" : "=v"(r) : "v"(lo), "v"(hi)); return r; }
; __device__ __forceinline__ unsigned pk2(float lo, float hi) { return f2bf(lo) | (f2bf(hi) << 16); }
;     ...
;         G_PAIR(0, 1);
; #pragma unroll 1
;         for (int t = 2; t < nt; t += 2) G_PAIR(t, 0);
;     __device__ __forceinline__ void epi(const f32x4 (&acc)[2][2][4][2], const Unit& u, int wr, int wc, int fr, int fq) const {
;     ...
;         for (int ai = 0; ai < 2; ++ai)
; #pragma unroll
;             for (int m = 0; m < 4; ++m) {
;                 const int row = row0 + ai * 128 + m * 16; const float rs = rs_lds[((u.pm >> 3) & 1) * 256 + (row & 255)];
;                 const float rs2 = rs * -1.4426950408889634f, rsq = rs * rs;
;                 f32x2 v[4];
; #pragma unroll
;                 for (int n = 0; n < 2; ++n)
; #pragma unroll
;                     for (int jp = 0; jp < 2; ++jp) {
;                         const f32x2 gg = (f32x2){acc[ai][0][m][n][2 * jp], acc[ai][0][m][n][2 * jp + 1]}, uu = (f32x2){acc[ai][1][m][n][2 * jp], acc[ai][1][m][n][2 * jp + 1]};
;                         const f32x2 t = gg * rs2; f32x2 e; e.x = __builtin_amdgcn_exp2f(t.x); e.y = __builtin_amdgcn_exp2f(t.y);
;                         const f32x2 d = e + 1.0f; f32x2 r; r.x = __builtin_amdgcn_rcpf(d.x); r.y = __builtin_amdgcn_rcpf(d.y);
;                         v[n * 2 + jp] = (gg * uu) * (r * rsq);
;                     }
;                 u32x4 w; w.x = pk2(v[0].x, v[0].y); w.y = pk2(v[1].x, v[1].y); w.z = pk2(v[2].x, v[2].y); w.w = pk2(v[3].x, v[3].y);
;                 *(u32x4*)(H + (size_t)row * FF + col0) = w;
	s_waitcnt lgkmcnt(0)
	v_mfma_f32_16x16x32_bf16 v[56:59], v[158:161], v[174:177], v[56:59]
	v_mfma_f32_16x16x32_bf16 v[48:51], v[166:169], v[174:177], v[48:51]
	v_mfma_f32_16x16x32_bf16 v[40:43], v[158:161], v[182:185], v[40:43]
	v_mfma_f32_16x16x32_bf16 v[32:35], v[166:169], v[182:185], v[32:35]
	v_mfma_f32_16x16x32_bf16 v[24:27], v[158:161], v[190:193], v[24:27]
	v_mfma_f32_16x16x32_bf16 v[16:19], v[166:169], v[190:193], v[16:19]
	v_mfma_f32_16x16x32_bf16 v[8:11], v[158:161], v[198:201], v[8:11]
	v_mfma_f32_16x16x32_bf16 v[0:3], v[166:169], v[198:201], v[0:3]
	v_mfma_f32_16x16x32_bf16 v[56:59], v[162:165], v[178:181], v[56:59]
	v_mfma_f32_16x16x32_bf16 v[48:51], v[170:173], v[178:181], v[48:51]
	v_mfma_f32_16x16x32_bf16 v[40:43], v[162:165], v[186:189], v[40:43]
	v_mfma_f32_16x16x32_bf16 v[32:35], v[170:173], v[186:189], v[32:35]
	v_mfma_f32_16x16x32_bf16 v[24:27], v[162:165], v[194:197], v[24:27]
	v_mfma_f32_16x16x32_bf16 v[16:19], v[170:173], v[194:197], v[16:19]
	s_add_u32 s36, s36, 0x40080
	v_mfma_f32_16x16x32_bf16 v[8:11], v[162:165], v[202:205], v[8:11]
	s_addc_u32 s37, s37, 0
	v_mfma_f32_16x16x32_bf16 v[0:3], v[170:173], v[202:205], v[0:3]
	s_barrier
	s_mov_b32 m0, s59
	v_lshl_add_u64 v[158:159], s[36:37], 0, v[134:135]
	global_load_lds_dwordx4 v[158:159], off
	s_mov_b32 m0, s17
	v_lshl_add_u64 v[158:159], s[36:37], 0, v[130:131]
	global_load_lds_dwordx4 v[158:159], off
	s_waitcnt vmcnt(6)
	s_barrier
	v_mfma_f32_16x16x32_bf16 v[68:71], v[206:209], v[174:177], v[68:71]
	v_mfma_f32_16x16x32_bf16 v[52:55], v[214:217], v[174:177], v[52:55]
	v_mfma_f32_16x16x32_bf16 v[44:47], v[206:209], v[182:185], v[44:47]
	v_mfma_f32_16x16x32_bf16 v[36:39], v[214:217], v[182:185], v[36:39]
	v_mfma_f32_16x16x32_bf16 v[28:31], v[206:209], v[190:193], v[28:31]
	v_mfma_f32_16x16x32_bf16 v[20:23], v[214:217], v[190:193], v[20:23]
	v_mfma_f32_16x16x32_bf16 v[12:15], v[206:209], v[198:201], v[12:15]
	v_mfma_f32_16x16x32_bf16 v[4:7], v[214:217], v[198:201], v[4:7]
	v_mfma_f32_16x16x32_bf16 v[68:71], v[210:213], v[178:181], v[68:71]
	v_mfma_f32_16x16x32_bf16 v[52:55], v[222:225], v[178:181], v[52:55]
	v_mfma_f32_16x16x32_bf16 v[44:47], v[210:213], v[186:189], v[44:47]
	v_mfma_f32_16x16x32_bf16 v[36:39], v[222:225], v[186:189], v[36:39]
	s_add_i32 s19, s19, 2
	v_mfma_f32_16x16x32_bf16 v[28:31], v[210:213], v[194:197], v[28:31]
	s_add_u32 s34, s34, 0x100
	v_mfma_f32_16x16x32_bf16 v[20:23], v[222:225], v[194:197], v[20:23]
	s_addc_u32 s35, s35, 0
	v_mfma_f32_16x16x32_bf16 v[12:15], v[210:213], v[202:205], v[12:15]
	s_cmp_gt_u32 s19, 13
	v_mfma_f32_16x16x32_bf16 v[4:7], v[222:225], v[202:205], v[4:7]
	s_cbranch_scc0 .Lrot_232
	s_barrier
	s_lshl_b32 s17, s24, 7
	s_and_b32 s17, s17, 0x400
	s_add_i32 s17, s17, 0x20000
	v_lshl_add_u32 v142, v151, 2, s17
	ds_read_b32 v143, v142
	s_waitcnt lgkmcnt(0)
	v_mul_f32_e32 v144, 0xbfb8aa3b, v143
	v_mul_f32_e32 v164, v143, v143
	ds_read_b32 v143, v142 offset:64
	v_pk_mul_f32 v[160:161], v[120:121], v[144:145] op_sel_hi:[1,0]
	v_pk_mul_f32 v[162:163], v[122:123], v[144:145] op_sel_hi:[1,0]
	v_exp_f32_e32 v160, v160
	v_exp_f32_e32 v161, v161
	v_exp_f32_e32 v162, v162
	v_exp_f32_e32 v163, v163
	v_pk_mul_f32 v[120:121], v[120:121], v[124:125]
	v_pk_add_f32 v[160:161], v[160:161], 1.0 op_sel_hi:[1,0]
	v_pk_mul_f32 v[122:123], v[122:123], v[126:127]
	v_pk_add_f32 v[162:163], v[162:163], 1.0 op_sel_hi:[1,0]
	v_rcp_f32_e32 v160, v160
	v_rcp_f32_e32 v161, v161
	v_rcp_f32_e32 v162, v162
	v_rcp_f32_e32 v163, v163
	v_pk_mul_f32 v[160:161], v[164:165], v[160:161] op_sel_hi:[0,1]
	v_pk_mul_f32 v[120:121], v[120:121], v[160:161]
	v_pk_mul_f32 v[162:163], v[164:165], v[162:163] op_sel_hi:[0,1]
	v_pk_mul_f32 v[122:123], v[122:123], v[162:163]
	v_pk_mul_f32 v[160:161], v[112:113], v[144:145] op_sel_hi:[1,0]
	v_pk_mul_f32 v[162:163], v[114:115], v[144:145] op_sel_hi:[1,0]
	v_exp_f32_e32 v160, v160
	v_exp_f32_e32 v161, v161
	v_exp_f32_e32 v162, v162
	v_exp_f32_e32 v163, v163
	v_pk_mul_f32 v[112:113], v[112:113], v[116:117]
	v_pk_add_f32 v[160:161], v[160:161], 1.0 op_sel_hi:[1,0]
	v_pk_mul_f32 v[114:115], v[114:115], v[118:119]
	v_pk_add_f32 v[162:163], v[162:163], 1.0 op_sel_hi:[1,0]
	v_rcp_f32_e32 v160, v160
	v_rcp_f32_e32 v161, v161
	v_rcp_f32_e32 v162, v162
	v_rcp_f32_e32 v163, v163
	v_pk_mul_f32 v[160:161], v[164:165], v[160:161] op_sel_hi:[0,1]
	v_pk_mul_f32 v[112:113], v[112:113], v[160:161]
	v_pk_mul_f32 v[162:163], v[164:165], v[162:163] op_sel_hi:[0,1]
	v_pk_mul_f32 v[114:115], v[114:115], v[162:163]
	v_cvt_pk_bf16_f32 v124, v120, v121
	v_cvt_pk_bf16_f32 v125, v122, v123
	v_cvt_pk_bf16_f32 v126, v112, v113
	v_cvt_pk_bf16_f32 v127, v114, v115
	v_lshl_add_u32 v112, s24, 8, v129
	v_lshl_or_b32 v114, s60, 7, v150
	v_mov_b64_e32 v[116:117], s[2:3]
	v_ashrrev_i32_e32 v115, 31, v114
	v_mad_i64_i32 v[118:119], s[26:27], v112, s51, v[116:117]
	v_lshlrev_b64 v[114:115], 1, v[114:115]
	v_mov_b32_e32 v112, 0xb0000
	v_mov_b32_e32 v113, 0
	v_lshl_add_u64 v[118:119], v[118:119], 0, v[114:115]
	v_mov_b32_e32 v120, 0x16000
	v_mov_b32_e32 v121, 0
	v_lshl_add_u64 v[122:123], v[118:119], 0, v[112:113]
	s_mov_b32 s60, s16
	s_mov_b32 s24, s18
	global_store_dwordx4 v[118:119], v[124:127], off
	s_waitcnt lgkmcnt(0)
; __device__ __forceinline__ unsigned pk2(float lo, float hi) { unsigned r; asm volatile("v_cvt_pk_bf16_f32 %0, %1, %2" : "=v"(r) : "v"(lo), "v"(hi)); return r; }
; __device__ __forceinline__ unsigned pk2(float lo, float hi) { return f2bf(lo) | (f2bf(hi) << 16); }
;     __device__ __forceinline__ void epi(const f32x4 (&acc)[2][2][4][2], const Unit& u, int wr, int wc, int fr, int fq) const {
;     ...
;             for (int m = 0; m < 4; ++m) {
;                 const int row = row0 + ai * 128 + m * 16; const float rs = rs_lds[((u.pm >> 3) & 1) * 256 + (row & 255)];
;                 const float rs2 = rs * -1.4426950408889634f, rsq = rs * rs;
;                 f32x2 v[4];
; #pragma unroll
;                 for (int n = 0; n < 2; ++n)
; #pragma unroll
;                     for (int jp = 0; jp < 2; ++jp) {
;                         const f32x2 gg = (f32x2){acc[ai][0][m][n][2 * jp], acc[ai][0][m][n][2 * jp + 1]}, uu = (f32x2){acc[ai][1][m][n][2 * jp], acc[ai][1][m][n][2 * jp + 1]};
;                         const f32x2 t = gg * rs2; f32x2 e; e.x = __builtin_amdgcn_exp2f(t.x); e.y = __builtin_amdgcn_exp2f(t.y);
;                         const f32x2 d = e + 1.0f; f32x2 r; r.x = __builtin_amdgcn_rcpf(d.x); r.y = __builtin_amdgcn_rcpf(d.y);
;                         v[n * 2 + jp] = (gg * uu) * (r * rsq);
;                     }
;                 u32x4 w; w.x = pk2(v[0].x, v[0].y); w.y = pk2(v[1].x, v[1].y); w.z = pk2(v[2].x, v[2].y); w.w = pk2(v[3].x, v[3].y);
;                 *(u32x4*)(H + (size_t)row * FF + col0) = w;
	v_mul_f32_e32 v144, 0xbfb8aa3b, v143
	v_mul_f32_e32 v164, v143, v143
	ds_read_b32 v143, v142 offset:128
	v_pk_mul_f32 v[160:161], v[104:105], v[144:145] op_sel_hi:[1,0]
	v_pk_mul_f32 v[162:163], v[106:107], v[144:145] op_sel_hi:[1,0]
	v_exp_f32_e32 v160, v160
	v_exp_f32_e32 v161, v161
	v_exp_f32_e32 v162, v162
	v_exp_f32_e32 v163, v163
	v_pk_mul_f32 v[104:105], v[104:105], v[108:109]
	v_pk_add_f32 v[160:161], v[160:161], 1.0 op_sel_hi:[1,0]
	v_pk_mul_f32 v[106:107], v[106:107], v[110:111]
	v_pk_add_f32 v[162:163], v[162:163], 1.0 op_sel_hi:[1,0]
	v_rcp_f32_e32 v160, v160
	v_rcp_f32_e32 v161, v161
	v_rcp_f32_e32 v162, v162
	v_rcp_f32_e32 v163, v163
	v_pk_mul_f32 v[160:161], v[164:165], v[160:161] op_sel_hi:[0,1]
	v_pk_mul_f32 v[104:105], v[104:105], v[160:161]
	v_pk_mul_f32 v[162:163], v[164:165], v[162:163] op_sel_hi:[0,1]
	v_pk_mul_f32 v[106:107], v[106:107], v[162:163]
	v_pk_mul_f32 v[160:161], v[96:97], v[144:145] op_sel_hi:[1,0]
	v_pk_mul_f32 v[162:163], v[98:99], v[144:145] op_sel_hi:[1,0]
	v_exp_f32_e32 v160, v160
	v_exp_f32_e32 v161, v161
	v_exp_f32_e32 v162, v162
	v_exp_f32_e32 v163, v163
	v_pk_mul_f32 v[96:97], v[96:97], v[100:101]
	v_pk_add_f32 v[160:161], v[160:161], 1.0 op_sel_hi:[1,0]
	v_pk_mul_f32 v[98:99], v[98:99], v[102:103]
	v_pk_add_f32 v[162:163], v[162:163], 1.0 op_sel_hi:[1,0]
	v_rcp_f32_e32 v160, v160
	v_rcp_f32_e32 v161, v161
	v_rcp_f32_e32 v162, v162
	v_rcp_f32_e32 v163, v163
	v_pk_mul_f32 v[160:161], v[164:165], v[160:161] op_sel_hi:[0,1]
	v_pk_mul_f32 v[96:97], v[96:97], v[160:161]
	v_pk_mul_f32 v[162:163], v[164:165], v[162:163] op_sel_hi:[0,1]
	v_pk_mul_f32 v[98:99], v[98:99], v[162:163]
	v_cvt_pk_bf16_f32 v108, v104, v105
	v_cvt_pk_bf16_f32 v109, v106, v107
	v_cvt_pk_bf16_f32 v110, v96, v97
	v_cvt_pk_bf16_f32 v111, v98, v99
	v_lshl_add_u64 v[118:119], v[118:119], 0, v[120:121]
	global_store_dwordx4 v[118:119], v[108:111], off
	s_waitcnt lgkmcnt(0)
	v_mul_f32_e32 v144, 0xbfb8aa3b, v143
	v_mul_f32_e32 v164, v143, v143
	ds_read_b32 v143, v142 offset:192
	v_pk_mul_f32 v[160:161], v[88:89], v[144:145] op_sel_hi:[1,0]
	v_pk_mul_f32 v[162:163], v[90:91], v[144:145] op_sel_hi:[1,0]
	v_exp_f32_e32 v160, v160
	v_exp_f32_e32 v161, v161
	v_exp_f32_e32 v162, v162
	v_exp_f32_e32 v163, v163
	v_pk_mul_f32 v[88:89], v[88:89], v[92:93]
	v_pk_add_f32 v[160:161], v[160:161], 1.0 op_sel_hi:[1,0]
	v_pk_mul_f32 v[90:91], v[90:91], v[94:95]
	v_pk_add_f32 v[162:163], v[162:163], 1.0 op_sel_hi:[1,0]
	v_rcp_f32_e32 v160, v160
	v_rcp_f32_e32 v161, v161
	v_rcp_f32_e32 v162, v162
	v_rcp_f32_e32 v163, v163
	v_pk_mul_f32 v[160:161], v[164:165], v[160:161] op_sel_hi:[0,1]
	v_pk_mul_f32 v[88:89], v[88:89], v[160:161]
	v_pk_mul_f32 v[162:163], v[164:165], v[162:163] op_sel_hi:[0,1]
	v_pk_mul_f32 v[90:91], v[90:91], v[162:163]
	v_pk_mul_f32 v[160:161], v[80:81], v[144:145] op_sel_hi:[1,0]
	v_pk_mul_f32 v[162:163], v[82:83], v[144:145] op_sel_hi:[1,0]
	v_exp_f32_e32 v160, v160
	v_exp_f32_e32 v161, v161
	v_exp_f32_e32 v162, v162
	v_exp_f32_e32 v163, v163
	v_pk_mul_f32 v[80:81], v[80:81], v[84:85]
	v_pk_add_f32 v[160:161], v[160:161], 1.0 op_sel_hi:[1,0]
	v_pk_mul_f32 v[82:83], v[82:83], v[86:87]
	v_pk_add_f32 v[162:163], v[162:163], 1.0 op_sel_hi:[1,0]
	v_rcp_f32_e32 v160, v160
	v_rcp_f32_e32 v161, v161
	v_rcp_f32_e32 v162, v162
	v_rcp_f32_e32 v163, v163
	v_pk_mul_f32 v[160:161], v[164:165], v[160:161] op_sel_hi:[0,1]
	v_pk_mul_f32 v[80:81], v[80:81], v[160:161]
	v_pk_mul_f32 v[162:163], v[164:165], v[162:163] op_sel_hi:[0,1]
	v_pk_mul_f32 v[82:83], v[82:83], v[162:163]
	v_cvt_pk_bf16_f32 v92, v88, v89
	v_cvt_pk_bf16_f32 v93, v90, v91
	v_cvt_pk_bf16_f32 v94, v80, v81
	v_cvt_pk_bf16_f32 v95, v82, v83
	v_lshl_add_u64 v[118:119], v[118:119], 0, v[120:121]
	global_store_dwordx4 v[118:119], v[92:95], off
	s_waitcnt lgkmcnt(0)
	v_mul_f32_e32 v144, 0xbfb8aa3b, v143
	v_mul_f32_e32 v164, v143, v143
	ds_read_b32 v143, v142 offset:512
	v_pk_mul_f32 v[160:161], v[72:73], v[144:145] op_sel_hi:[1,0]
	v_pk_mul_f32 v[162:163], v[74:75], v[144:145] op_sel_hi:[1,0]
	v_exp_f32_e32 v160, v160
	v_exp_f32_e32 v161, v161
	v_exp_f32_e32 v162, v162
	v_exp_f32_e32 v163, v163
	v_pk_mul_f32 v[72:73], v[72:73], v[76:77]
	v_pk_add_f32 v[160:161], v[160:161], 1.0 op_sel_hi:[1,0]
	v_pk_mul_f32 v[74:75], v[74:75], v[78:79]
	v_pk_add_f32 v[162:163], v[162:163], 1.0 op_sel_hi:[1,0]
	v_rcp_f32_e32 v160, v160
	v_rcp_f32_e32 v161, v161
	v_rcp_f32_e32 v162, v162
	v_rcp_f32_e32 v163, v163
	v_pk_mul_f32 v[160:161], v[164:165], v[160:161] op_sel_hi:[0,1]
	v_pk_mul_f32 v[72:73], v[72:73], v[160:161]
	v_pk_mul_f32 v[162:163], v[164:165], v[162:163] op_sel_hi:[0,1]
	v_pk_mul_f32 v[74:75], v[74:75], v[162:163]
	v_pk_mul_f32 v[160:161], v[60:61], v[144:145] op_sel_hi:[1,0]
	v_pk_mul_f32 v[162:163], v[62:63], v[144:145] op_sel_hi:[1,0]
	v_exp_f32_e32 v160, v160
	v_exp_f32_e32 v161, v161
	v_exp_f32_e32 v162, v162
	v_exp_f32_e32 v163, v163
	v_pk_mul_f32 v[60:61], v[60:61], v[64:65]
	v_pk_add_f32 v[160:161], v[160:161], 1.0 op_sel_hi:[1,0]
	v_pk_mul_f32 v[62:63], v[62:63], v[66:67]
	v_pk_add_f32 v[162:163], v[162:163], 1.0 op_sel_hi:[1,0]
	v_rcp_f32_e32 v160, v160
	v_rcp_f32_e32 v161, v161
	v_rcp_f32_e32 v162, v162
	v_rcp_f32_e32 v163, v163
	v_pk_mul_f32 v[160:161], v[164:165], v[160:161] op_sel_hi:[0,1]
	v_pk_mul_f32 v[60:61], v[60:61], v[160:161]
	v_pk_mul_f32 v[162:163], v[164:165], v[162:163] op_sel_hi:[0,1]
	v_pk_mul_f32 v[62:63], v[62:63], v[162:163]
	v_cvt_pk_bf16_f32 v76, v72, v73
	v_cvt_pk_bf16_f32 v77, v74, v75
	v_cvt_pk_bf16_f32 v78, v60, v61
	v_cvt_pk_bf16_f32 v79, v62, v63
	v_lshl_add_u64 v[118:119], v[118:119], 0, v[120:121]
	global_store_dwordx4 v[118:119], v[76:79], off
	s_waitcnt lgkmcnt(0)
; __device__ __forceinline__ unsigned pk2(float lo, float hi) { unsigned r; asm volatile("v_cvt_pk_bf16_f32 %0, %1, %2" : "=v"(r) : "v"(lo), "v"(hi)); return r; }
; __device__ __forceinline__ unsigned pk2(float lo, float hi) { return f2bf(lo) | (f2bf(hi) << 16); }
;     __device__ __forceinline__ void epi(const f32x4 (&acc)[2][2][4][2], const Unit& u, int wr, int wc, int fr, int fq) const {
;     ...
;             for (int m = 0; m < 4; ++m) {
;                 const int row = row0 + ai * 128 + m * 16; const float rs = rs_lds[((u.pm >> 3) & 1) * 256 + (row & 255)];
;                 const float rs2 = rs * -1.4426950408889634f, rsq = rs * rs;
;                 f32x2 v[4];
; #pragma unroll
;                 for (int n = 0; n < 2; ++n)
; #pragma unroll
;                     for (int jp = 0; jp < 2; ++jp) {
;                         const f32x2 gg = (f32x2){acc[ai][0][m][n][2 * jp], acc[ai][0][m][n][2 * jp + 1]}, uu = (f32x2){acc[ai][1][m][n][2 * jp], acc[ai][1][m][n][2 * jp + 1]};
;                         const f32x2 t = gg * rs2; f32x2 e; e.x = __builtin_amdgcn_exp2f(t.x); e.y = __builtin_amdgcn_exp2f(t.y);
;                         const f32x2 d = e + 1.0f; f32x2 r; r.x = __builtin_amdgcn_rcpf(d.x); r.y = __builtin_amdgcn_rcpf(d.y);
;                         v[n * 2 + jp] = (gg * uu) * (r * rsq);
;                     }
;                 u32x4 w; w.x = pk2(v[0].x, v[0].y); w.y = pk2(v[1].x, v[1].y); w.z = pk2(v[2].x, v[2].y); w.w = pk2(v[3].x, v[3].y);
;                 *(u32x4*)(H + (size_t)row * FF + col0) = w;
	v_mul_f32_e32 v144, 0xbfb8aa3b, v143
	v_mul_f32_e32 v164, v143, v143
	ds_read_b32 v143, v142 offset:576
	v_pk_mul_f32 v[160:161], v[56:57], v[144:145] op_sel_hi:[1,0]
	v_pk_mul_f32 v[162:163], v[58:59], v[144:145] op_sel_hi:[1,0]
	v_exp_f32_e32 v160, v160
	v_exp_f32_e32 v161, v161
	v_exp_f32_e32 v162, v162
	v_exp_f32_e32 v163, v163
	v_pk_mul_f32 v[56:57], v[56:57], v[68:69]
	v_pk_add_f32 v[160:161], v[160:161], 1.0 op_sel_hi:[1,0]
	v_pk_mul_f32 v[58:59], v[58:59], v[70:71]
	v_pk_add_f32 v[162:163], v[162:163], 1.0 op_sel_hi:[1,0]
	v_rcp_f32_e32 v160, v160
	v_rcp_f32_e32 v161, v161
	v_rcp_f32_e32 v162, v162
	v_rcp_f32_e32 v163, v163
	v_pk_mul_f32 v[160:161], v[164:165], v[160:161] op_sel_hi:[0,1]
	v_pk_mul_f32 v[56:57], v[56:57], v[160:161]
	v_pk_mul_f32 v[162:163], v[164:165], v[162:163] op_sel_hi:[0,1]
	v_pk_mul_f32 v[58:59], v[58:59], v[162:163]
	v_pk_mul_f32 v[160:161], v[48:49], v[144:145] op_sel_hi:[1,0]
	v_pk_mul_f32 v[162:163], v[50:51], v[144:145] op_sel_hi:[1,0]
	v_exp_f32_e32 v160, v160
	v_exp_f32_e32 v161, v161
	v_exp_f32_e32 v162, v162
	v_exp_f32_e32 v163, v163
	v_pk_mul_f32 v[48:49], v[48:49], v[52:53]
	v_pk_add_f32 v[160:161], v[160:161], 1.0 op_sel_hi:[1,0]
	v_pk_mul_f32 v[50:51], v[50:51], v[54:55]
	v_pk_add_f32 v[162:163], v[162:163], 1.0 op_sel_hi:[1,0]
	v_rcp_f32_e32 v160, v160
	v_rcp_f32_e32 v161, v161
	v_rcp_f32_e32 v162, v162
	v_rcp_f32_e32 v163, v163
	v_pk_mul_f32 v[160:161], v[164:165], v[160:161] op_sel_hi:[0,1]
	v_pk_mul_f32 v[48:49], v[48:49], v[160:161]
	v_pk_mul_f32 v[162:163], v[164:165], v[162:163] op_sel_hi:[0,1]
	v_pk_mul_f32 v[50:51], v[50:51], v[162:163]
	v_cvt_pk_bf16_f32 v68, v56, v57
	v_cvt_pk_bf16_f32 v69, v58, v59
	v_cvt_pk_bf16_f32 v70, v48, v49
	v_cvt_pk_bf16_f32 v71, v50, v51
	v_mov_b64_e32 v[118:119], v[122:123]
	global_store_dwordx4 v[118:119], v[68:71], off
	s_waitcnt lgkmcnt(0)
	v_mul_f32_e32 v144, 0xbfb8aa3b, v143
	v_mul_f32_e32 v164, v143, v143
	ds_read_b32 v143, v142 offset:640
	v_pk_mul_f32 v[160:161], v[40:41], v[144:145] op_sel_hi:[1,0]
	v_pk_mul_f32 v[162:163], v[42:43], v[144:145] op_sel_hi:[1,0]
	v_exp_f32_e32 v160, v160
	v_exp_f32_e32 v161, v161
	v_exp_f32_e32 v162, v162
	v_exp_f32_e32 v163, v163
	v_pk_mul_f32 v[40:41], v[40:41], v[44:45]
	v_pk_add_f32 v[160:161], v[160:161], 1.0 op_sel_hi:[1,0]
	v_pk_mul_f32 v[42:43], v[42:43], v[46:47]
	v_pk_add_f32 v[162:163], v[162:163], 1.0 op_sel_hi:[1,0]
	v_rcp_f32_e32 v160, v160
	v_rcp_f32_e32 v161, v161
	v_rcp_f32_e32 v162, v162
	v_rcp_f32_e32 v163, v163
	v_pk_mul_f32 v[160:161], v[164:165], v[160:161] op_sel_hi:[0,1]
	v_pk_mul_f32 v[40:41], v[40:41], v[160:161]
	v_pk_mul_f32 v[162:163], v[164:165], v[162:163] op_sel_hi:[0,1]
	v_pk_mul_f32 v[42:43], v[42:43], v[162:163]
	v_pk_mul_f32 v[160:161], v[32:33], v[144:145] op_sel_hi:[1,0]
	v_pk_mul_f32 v[162:163], v[34:35], v[144:145] op_sel_hi:[1,0]
	v_exp_f32_e32 v160, v160
	v_exp_f32_e32 v161, v161
	v_exp_f32_e32 v162, v162
	v_exp_f32_e32 v163, v163
	v_pk_mul_f32 v[32:33], v[32:33], v[36:37]
	v_pk_add_f32 v[160:161], v[160:161], 1.0 op_sel_hi:[1,0]
	v_pk_mul_f32 v[34:35], v[34:35], v[38:39]
	v_pk_add_f32 v[162:163], v[162:163], 1.0 op_sel_hi:[1,0]
	v_rcp_f32_e32 v160, v160
	v_rcp_f32_e32 v161, v161
	v_rcp_f32_e32 v162, v162
	v_rcp_f32_e32 v163, v163
	v_pk_mul_f32 v[160:161], v[164:165], v[160:161] op_sel_hi:[0,1]
	v_pk_mul_f32 v[32:33], v[32:33], v[160:161]
	v_pk_mul_f32 v[162:163], v[164:165], v[162:163] op_sel_hi:[0,1]
	v_pk_mul_f32 v[34:35], v[34:35], v[162:163]
	v_cvt_pk_bf16_f32 v44, v40, v41
	v_cvt_pk_bf16_f32 v45, v42, v43
	v_cvt_pk_bf16_f32 v46, v32, v33
	v_cvt_pk_bf16_f32 v47, v34, v35
	v_lshl_add_u64 v[118:119], v[118:119], 0, v[120:121]
	global_store_dwordx4 v[118:119], v[44:47], off
	s_waitcnt lgkmcnt(0)
; __device__ __forceinline__ unsigned pk2(float lo, float hi) { unsigned r; asm volatile("v_cvt_pk_bf16_f32 %0, %1, %2" : "=v"(r) : "v"(lo), "v"(hi)); return r; }
; __device__ __forceinline__ unsigned pk2(float lo, float hi) { return f2bf(lo) | (f2bf(hi) << 16); }
; #define G_WAIT_V(n) asm volatile("s_waitcnt vmcnt(" #n ")" ::: "memory")
; #define G_BAR __builtin_amdgcn_s_barrier()
;     ...
;         p.epi(acc, cur, wr, wc, fr, fq);
;         if (!has_next) break;
;         cur = nxt; cA = nA; cB = nB; cA2 = nA2; cB2 = nB2; ++ui;
;     }
;     G_WAIT_V(0);
;     if (wr == 0) G_BAR;
;     G_BAR;
;     __device__ __forceinline__ void epi(const f32x4 (&acc)[2][2][4][2], const Unit& u, int wr, int wc, int fr, int fq) const {
;     ...
;             for (int m = 0; m < 4; ++m) {
;                 const int row = row0 + ai * 128 + m * 16; const float rs = rs_lds[((u.pm >> 3) & 1) * 256 + (row & 255)];
;                 const float rs2 = rs * -1.4426950408889634f, rsq = rs * rs;
;                 f32x2 v[4];
; #pragma unroll
;                 for (int n = 0; n < 2; ++n)
; #pragma unroll
;                     for (int jp = 0; jp < 2; ++jp) {
;                         const f32x2 gg = (f32x2){acc[ai][0][m][n][2 * jp], acc[ai][0][m][n][2 * jp + 1]}, uu = (f32x2){acc[ai][1][m][n][2 * jp], acc[ai][1][m][n][2 * jp + 1]};
;                         const f32x2 t = gg * rs2; f32x2 e; e.x = __builtin_amdgcn_exp2f(t.x); e.y = __builtin_amdgcn_exp2f(t.y);
;                         const f32x2 d = e + 1.0f; f32x2 r; r.x = __builtin_amdgcn_rcpf(d.x); r.y = __builtin_amdgcn_rcpf(d.y);
;                         v[n * 2 + jp] = (gg * uu) * (r * rsq);
;                     }
;                 u32x4 w; w.x = pk2(v[0].x, v[0].y); w.y = pk2(v[1].x, v[1].y); w.z = pk2(v[2].x, v[2].y); w.w = pk2(v[3].x, v[3].y);
;                 *(u32x4*)(H + (size_t)row * FF + col0) = w;
	v_mul_f32_e32 v144, 0xbfb8aa3b, v143
	v_mul_f32_e32 v164, v143, v143
	ds_read_b32 v143, v142 offset:704
	v_pk_mul_f32 v[160:161], v[24:25], v[144:145] op_sel_hi:[1,0]
	v_pk_mul_f32 v[162:163], v[26:27], v[144:145] op_sel_hi:[1,0]
	v_exp_f32_e32 v160, v160
	v_exp_f32_e32 v161, v161
	v_exp_f32_e32 v162, v162
	v_exp_f32_e32 v163, v163
	v_pk_mul_f32 v[24:25], v[24:25], v[28:29]
	v_pk_add_f32 v[160:161], v[160:161], 1.0 op_sel_hi:[1,0]
	v_pk_mul_f32 v[26:27], v[26:27], v[30:31]
	v_pk_add_f32 v[162:163], v[162:163], 1.0 op_sel_hi:[1,0]
	v_rcp_f32_e32 v160, v160
	v_rcp_f32_e32 v161, v161
	v_rcp_f32_e32 v162, v162
	v_rcp_f32_e32 v163, v163
	v_pk_mul_f32 v[160:161], v[164:165], v[160:161] op_sel_hi:[0,1]
	v_pk_mul_f32 v[24:25], v[24:25], v[160:161]
	v_pk_mul_f32 v[162:163], v[164:165], v[162:163] op_sel_hi:[0,1]
	v_pk_mul_f32 v[26:27], v[26:27], v[162:163]
	v_pk_mul_f32 v[160:161], v[16:17], v[144:145] op_sel_hi:[1,0]
	v_pk_mul_f32 v[162:163], v[18:19], v[144:145] op_sel_hi:[1,0]
	v_exp_f32_e32 v160, v160
	v_exp_f32_e32 v161, v161
	v_exp_f32_e32 v162, v162
	v_exp_f32_e32 v163, v163
	v_pk_mul_f32 v[16:17], v[16:17], v[20:21]
	v_pk_add_f32 v[160:161], v[160:161], 1.0 op_sel_hi:[1,0]
	v_pk_mul_f32 v[18:19], v[18:19], v[22:23]
	v_pk_add_f32 v[162:163], v[162:163], 1.0 op_sel_hi:[1,0]
	v_rcp_f32_e32 v160, v160
	v_rcp_f32_e32 v161, v161
	v_rcp_f32_e32 v162, v162
	v_rcp_f32_e32 v163, v163
	v_pk_mul_f32 v[160:161], v[164:165], v[160:161] op_sel_hi:[0,1]
	v_pk_mul_f32 v[16:17], v[16:17], v[160:161]
	v_pk_mul_f32 v[162:163], v[164:165], v[162:163] op_sel_hi:[0,1]
	v_pk_mul_f32 v[18:19], v[18:19], v[162:163]
	v_cvt_pk_bf16_f32 v28, v24, v25
	v_cvt_pk_bf16_f32 v29, v26, v27
	v_cvt_pk_bf16_f32 v30, v16, v17
	v_cvt_pk_bf16_f32 v31, v18, v19
	v_lshl_add_u64 v[118:119], v[118:119], 0, v[120:121]
	global_store_dwordx4 v[118:119], v[28:31], off
	s_waitcnt lgkmcnt(0)
	v_mul_f32_e32 v144, 0xbfb8aa3b, v143
	v_mul_f32_e32 v164, v143, v143
	v_pk_mul_f32 v[160:161], v[8:9], v[144:145] op_sel_hi:[1,0]
	v_pk_mul_f32 v[162:163], v[10:11], v[144:145] op_sel_hi:[1,0]
	v_exp_f32_e32 v160, v160
	v_exp_f32_e32 v161, v161
	v_exp_f32_e32 v162, v162
	v_exp_f32_e32 v163, v163
	v_pk_mul_f32 v[8:9], v[8:9], v[12:13]
	v_pk_add_f32 v[160:161], v[160:161], 1.0 op_sel_hi:[1,0]
	v_pk_mul_f32 v[10:11], v[10:11], v[14:15]
	v_pk_add_f32 v[162:163], v[162:163], 1.0 op_sel_hi:[1,0]
	v_rcp_f32_e32 v160, v160
	v_rcp_f32_e32 v161, v161
	v_rcp_f32_e32 v162, v162
	v_rcp_f32_e32 v163, v163
	v_pk_mul_f32 v[160:161], v[164:165], v[160:161] op_sel_hi:[0,1]
	v_pk_mul_f32 v[8:9], v[8:9], v[160:161]
	v_pk_mul_f32 v[162:163], v[164:165], v[162:163] op_sel_hi:[0,1]
	v_pk_mul_f32 v[10:11], v[10:11], v[162:163]
	v_pk_mul_f32 v[160:161], v[0:1], v[144:145] op_sel_hi:[1,0]
	v_pk_mul_f32 v[162:163], v[2:3], v[144:145] op_sel_hi:[1,0]
	v_exp_f32_e32 v160, v160
	v_exp_f32_e32 v161, v161
	v_exp_f32_e32 v162, v162
	v_exp_f32_e32 v163, v163
	v_pk_mul_f32 v[0:1], v[0:1], v[4:5]
	v_pk_add_f32 v[160:161], v[160:161], 1.0 op_sel_hi:[1,0]
	v_pk_mul_f32 v[2:3], v[2:3], v[6:7]
	v_pk_add_f32 v[162:163], v[162:163], 1.0 op_sel_hi:[1,0]
	v_rcp_f32_e32 v160, v160
	v_rcp_f32_e32 v161, v161
	v_rcp_f32_e32 v162, v162
	v_rcp_f32_e32 v163, v163
	v_pk_mul_f32 v[160:161], v[164:165], v[160:161] op_sel_hi:[0,1]
	v_pk_mul_f32 v[0:1], v[0:1], v[160:161]
	v_pk_mul_f32 v[162:163], v[164:165], v[162:163] op_sel_hi:[0,1]
	v_pk_mul_f32 v[2:3], v[2:3], v[162:163]
	v_cvt_pk_bf16_f32 v12, v8, v9
	v_cvt_pk_bf16_f32 v13, v10, v11
	v_cvt_pk_bf16_f32 v14, v0, v1
	v_cvt_pk_bf16_f32 v15, v2, v3
	v_lshl_add_u64 v[118:119], v[118:119], 0, v[120:121]
	global_store_dwordx4 v[118:119], v[12:15], off
	s_mov_b64 s[28:29], s[22:23]
	s_mov_b64 s[26:27], s[20:21]
	s_and_b64 vcc, exec, s[14:15]
	s_cbranch_vccz .LBB0_229
	s_waitcnt vmcnt(0)
	s_cmpk_gt_u32 s38, 0xff
	s_cbranch_scc1 .LBB0_236
	s_barrier

.LBB0_357:
	ds_read_b128 v[134:137], v190
	ds_read_b128 v[138:141], v190 offset:1024
	ds_read_b128 v[142:145], v190 offset:2048
	ds_read_b128 v[146:149], v190 offset:3072
	s_mov_b32 m0, s54
	v_lshl_add_u64 v[150:151], v[128:129], 0, s[34:35]
	ds_read_b128 v[166:169], v191
	ds_read_b128 v[170:173], v191 offset:1024
	ds_read_b128 v[174:177], v191 offset:2048
	ds_read_b128 v[178:181], v191 offset:3072
	ds_read_b128 v[194:197], v191 offset:4096
	ds_read_b128 v[198:201], v191 offset:5120
	ds_read_b128 v[202:205], v191 offset:6144
	ds_read_b128 v[206:209], v191 offset:7168
	global_load_lds_dwordx4 v[150:151], off
	s_mov_b32 m0, s55
	v_lshl_add_u64 v[150:151], v[130:131], 0, s[34:35]
	global_load_lds_dwordx4 v[150:151], off
	s_waitcnt lgkmcnt(8)
	s_barrier
	s_waitcnt lgkmcnt(0)
	v_mfma_f32_16x16x32_bf16 v[116:119], v[134:137], v[166:169], v[116:119]
	s_add_i32 s36, s34, 0xfff50080
	v_mfma_f32_16x16x32_bf16 v[112:115], v[142:145], v[166:169], v[112:115]
	s_cmp_eq_u32 s67, 40
	v_mfma_f32_16x16x32_bf16 v[108:111], v[134:137], v[174:177], v[108:111]
	s_cselect_b32 s69, s27, s29
	v_mfma_f32_16x16x32_bf16 v[104:107], v[142:145], v[174:177], v[104:107]
	s_cselect_b32 s68, s26, s28
	v_mfma_f32_16x16x32_bf16 v[92:95], v[134:137], v[194:197], v[92:95]
	s_cselect_b32 s37, s9, s31
	v_mfma_f32_16x16x32_bf16 v[88:91], v[142:145], v[194:197], v[88:91]
	s_cselect_b32 s70, s8, s30
	v_mfma_f32_16x16x32_bf16 v[76:79], v[134:137], v[202:205], v[76:79]
	v_mfma_f32_16x16x32_bf16 v[72:75], v[142:145], v[202:205], v[72:75]
	v_mfma_f32_16x16x32_bf16 v[116:119], v[138:141], v[170:173], v[116:119]
	v_mfma_f32_16x16x32_bf16 v[112:115], v[146:149], v[170:173], v[112:115]
	v_mfma_f32_16x16x32_bf16 v[108:111], v[138:141], v[178:181], v[108:111]
	v_mfma_f32_16x16x32_bf16 v[104:107], v[146:149], v[178:181], v[104:107]
	v_mfma_f32_16x16x32_bf16 v[92:95], v[138:141], v[198:201], v[92:95]
	s_cselect_b32 s71, 0, s36
	v_mfma_f32_16x16x32_bf16 v[88:91], v[146:149], v[198:201], v[88:91]
	s_add_u32 s36, s70, s71
	v_mfma_f32_16x16x32_bf16 v[76:79], v[138:141], v[206:209], v[76:79]
	s_addc_u32 s37, s37, 0
	v_mfma_f32_16x16x32_bf16 v[72:75], v[146:149], v[206:209], v[72:75]
	s_barrier
	s_mov_b32 m0, s56
	v_lshl_add_u64 v[150:151], s[36:37], 0, v[156:157]
	ds_read_b128 v[210:213], v192
	ds_read_b128 v[214:217], v192 offset:1024
	ds_read_b128 v[222:225], v192 offset:2048
	ds_read_b128 v[226:229], v192 offset:3072
	global_load_lds_dwordx4 v[150:151], off
	s_mov_b32 m0, s57
	v_lshl_add_u64 v[182:183], s[36:37], 0, v[160:161]
	global_load_lds_dwordx4 v[182:183], off
	s_barrier
	s_waitcnt lgkmcnt(0)
	v_mfma_f32_16x16x32_bf16 v[124:127], v[210:213], v[166:169], v[124:127]
	v_mfma_f32_16x16x32_bf16 v[120:123], v[222:225], v[166:169], v[120:123]
	v_mfma_f32_16x16x32_bf16 v[100:103], v[210:213], v[174:177], v[100:103]
	v_mfma_f32_16x16x32_bf16 v[96:99], v[222:225], v[174:177], v[96:99]
	v_mfma_f32_16x16x32_bf16 v[84:87], v[210:213], v[194:197], v[84:87]
	v_mfma_f32_16x16x32_bf16 v[80:83], v[222:225], v[194:197], v[80:83]
	v_mfma_f32_16x16x32_bf16 v[68:71], v[210:213], v[202:205], v[68:71]
	v_mfma_f32_16x16x32_bf16 v[64:67], v[222:225], v[202:205], v[64:67]
	v_mfma_f32_16x16x32_bf16 v[124:127], v[214:217], v[170:173], v[124:127]
	v_mfma_f32_16x16x32_bf16 v[120:123], v[226:229], v[170:173], v[120:123]
	v_mfma_f32_16x16x32_bf16 v[100:103], v[214:217], v[178:181], v[100:103]
	v_mfma_f32_16x16x32_bf16 v[96:99], v[226:229], v[178:181], v[96:99]
	v_mfma_f32_16x16x32_bf16 v[84:87], v[214:217], v[198:201], v[84:87]
	v_mfma_f32_16x16x32_bf16 v[80:83], v[226:229], v[198:201], v[80:83]
	s_add_u32 s68, s68, s71
	v_mfma_f32_16x16x32_bf16 v[68:71], v[214:217], v[206:209], v[68:71]
	s_addc_u32 s69, s69, 0
	v_mfma_f32_16x16x32_bf16 v[64:67], v[226:229], v[206:209], v[64:67]
	s_mov_b32 m0, s46
	v_lshl_add_u64 v[218:219], s[68:69], 0, v[154:155]
	s_barrier
	ds_read_b128 v[166:169], v191 offset:16384
	ds_read_b128 v[170:173], v191 offset:17408
	ds_read_b128 v[174:177], v191 offset:18432
	ds_read_b128 v[178:181], v191 offset:19456
	ds_read_b128 v[194:197], v191 offset:20480
	ds_read_b128 v[198:201], v191 offset:21504
	ds_read_b128 v[202:205], v191 offset:22528
	ds_read_b128 v[206:209], v191 offset:23552
	global_load_lds_dwordx4 v[218:219], off
	s_mov_b32 m0, s47
	v_lshl_add_u64 v[230:231], s[68:69], 0, v[158:159]
	global_load_lds_dwordx4 v[230:231], off
	s_barrier
	s_waitcnt lgkmcnt(0)
	v_mfma_f32_16x16x32_bf16 v[52:55], v[134:137], v[166:169], v[52:55]
	v_mfma_f32_16x16x32_bf16 v[48:51], v[142:145], v[166:169], v[48:51]
	v_mfma_f32_16x16x32_bf16 v[44:47], v[134:137], v[174:177], v[44:47]
	v_mfma_f32_16x16x32_bf16 v[36:39], v[142:145], v[174:177], v[36:39]
	v_mfma_f32_16x16x32_bf16 v[28:31], v[134:137], v[194:197], v[28:31]
	v_mfma_f32_16x16x32_bf16 v[20:23], v[142:145], v[194:197], v[20:23]
	v_mfma_f32_16x16x32_bf16 v[12:15], v[134:137], v[202:205], v[12:15]
	v_mfma_f32_16x16x32_bf16 v[4:7], v[142:145], v[202:205], v[4:7]
	v_mfma_f32_16x16x32_bf16 v[52:55], v[138:141], v[170:173], v[52:55]
	v_mfma_f32_16x16x32_bf16 v[48:51], v[146:149], v[170:173], v[48:51]
	v_mfma_f32_16x16x32_bf16 v[44:47], v[138:141], v[178:181], v[44:47]
	v_mfma_f32_16x16x32_bf16 v[36:39], v[146:149], v[178:181], v[36:39]
	v_mfma_f32_16x16x32_bf16 v[28:31], v[138:141], v[198:201], v[28:31]
	v_mfma_f32_16x16x32_bf16 v[20:23], v[146:149], v[198:201], v[20:23]
	s_add_u32 s70, s36, 0xb0000
	v_mfma_f32_16x16x32_bf16 v[12:15], v[138:141], v[206:209], v[12:15]
	s_addc_u32 s71, s37, 0
	v_mfma_f32_16x16x32_bf16 v[4:7], v[146:149], v[206:209], v[4:7]
	s_barrier
	s_mov_b32 m0, s0
	v_lshl_add_u64 v[134:135], s[70:71], 0, v[156:157]
	global_load_lds_dwordx4 v[134:135], off
	s_mov_b32 m0, s62
	v_lshl_add_u64 v[134:135], s[70:71], 0, v[160:161]
	global_load_lds_dwordx4 v[134:135], off
	s_waitcnt vmcnt(6)
	s_barrier
	v_mfma_f32_16x16x32_bf16 v[60:63], v[210:213], v[166:169], v[60:63]
	v_mfma_f32_16x16x32_bf16 v[56:59], v[222:225], v[166:169], v[56:59]
	v_mfma_f32_16x16x32_bf16 v[40:43], v[210:213], v[174:177], v[40:43]
	v_mfma_f32_16x16x32_bf16 v[32:35], v[222:225], v[174:177], v[32:35]
	v_mfma_f32_16x16x32_bf16 v[24:27], v[210:213], v[194:197], v[24:27]
	v_mfma_f32_16x16x32_bf16 v[16:19], v[222:225], v[194:197], v[16:19]
	v_mfma_f32_16x16x32_bf16 v[8:11], v[210:213], v[202:205], v[8:11]
	v_mfma_f32_16x16x32_bf16 v[0:3], v[222:225], v[202:205], v[0:3]
	v_mfma_f32_16x16x32_bf16 v[60:63], v[214:217], v[170:173], v[60:63]
	v_mfma_f32_16x16x32_bf16 v[56:59], v[226:229], v[170:173], v[56:59]
	v_mfma_f32_16x16x32_bf16 v[40:43], v[214:217], v[178:181], v[40:43]
	v_mfma_f32_16x16x32_bf16 v[32:35], v[226:229], v[178:181], v[32:35]
	v_mfma_f32_16x16x32_bf16 v[24:27], v[214:217], v[198:201], v[24:27]
	v_mfma_f32_16x16x32_bf16 v[16:19], v[226:229], v[198:201], v[16:19]
	s_add_u32 s68, s68, 0xb0000
	v_mfma_f32_16x16x32_bf16 v[8:11], v[214:217], v[206:209], v[8:11]
	s_addc_u32 s69, s69, 0
	v_mfma_f32_16x16x32_bf16 v[0:3], v[226:229], v[206:209], v[0:3]
	s_barrier
	ds_read_b128 v[134:137], v132
	ds_read_b128 v[138:141], v132 offset:1024
	ds_read_b128 v[142:145], v132 offset:2048
	ds_read_b128 v[146:149], v132 offset:3072
	s_mov_b32 m0, s48
	v_lshl_add_u64 v[210:211], s[68:69], 0, v[154:155]
	ds_read_b128 v[166:169], v191 offset:32768
	ds_read_b128 v[170:173], v191 offset:33792
	ds_read_b128 v[174:177], v191 offset:34816
	ds_read_b128 v[178:181], v191 offset:35840
	ds_read_b128 v[194:197], v191 offset:36864
	ds_read_b128 v[198:201], v191 offset:37888
	ds_read_b128 v[202:205], v191 offset:38912
	ds_read_b128 v[206:209], v191 offset:39936
	global_load_lds_dwordx4 v[210:211], off
	s_mov_b32 m0, s49
	v_lshl_add_u64 v[210:211], s[68:69], 0, v[158:159]
	global_load_lds_dwordx4 v[210:211], off
	s_waitcnt lgkmcnt(8)
	s_barrier
	s_waitcnt lgkmcnt(0)
	v_mfma_f32_16x16x32_bf16 v[116:119], v[134:137], v[166:169], v[116:119]
	v_mfma_f32_16x16x32_bf16 v[112:115], v[142:145], v[166:169], v[112:115]
	v_mfma_f32_16x16x32_bf16 v[108:111], v[134:137], v[174:177], v[108:111]
	v_mfma_f32_16x16x32_bf16 v[104:107], v[142:145], v[174:177], v[104:107]
	v_mfma_f32_16x16x32_bf16 v[92:95], v[134:137], v[194:197], v[92:95]
	v_mfma_f32_16x16x32_bf16 v[88:91], v[142:145], v[194:197], v[88:91]
	v_mfma_f32_16x16x32_bf16 v[76:79], v[134:137], v[202:205], v[76:79]
	v_mfma_f32_16x16x32_bf16 v[72:75], v[142:145], v[202:205], v[72:75]
	v_mfma_f32_16x16x32_bf16 v[116:119], v[138:141], v[170:173], v[116:119]
	v_mfma_f32_16x16x32_bf16 v[112:115], v[146:149], v[170:173], v[112:115]
	v_mfma_f32_16x16x32_bf16 v[108:111], v[138:141], v[178:181], v[108:111]
	v_mfma_f32_16x16x32_bf16 v[104:107], v[146:149], v[178:181], v[104:107]
	v_mfma_f32_16x16x32_bf16 v[92:95], v[138:141], v[198:201], v[92:95]
	v_mfma_f32_16x16x32_bf16 v[88:91], v[146:149], v[198:201], v[88:91]
	v_mfma_f32_16x16x32_bf16 v[76:79], v[138:141], v[206:209], v[76:79]
	v_mfma_f32_16x16x32_bf16 v[72:75], v[146:149], v[206:209], v[72:75]
	s_barrier
	s_mov_b32 m0, s63
	v_lshl_add_u64 v[150:151], v[150:151], 0, s[10:11]
	ds_read_b128 v[210:213], v133
	ds_read_b128 v[214:217], v133 offset:1024
	ds_read_b128 v[222:225], v133 offset:2048
	ds_read_b128 v[226:229], v133 offset:3072
	global_load_lds_dwordx4 v[150:151], off
	s_mov_b32 m0, s64
	v_lshl_add_u64 v[150:151], v[182:183], 0, s[10:11]
	global_load_lds_dwordx4 v[150:151], off
	s_barrier
	s_waitcnt lgkmcnt(0)
	v_mfma_f32_16x16x32_bf16 v[124:127], v[210:213], v[166:169], v[124:127]
	v_mfma_f32_16x16x32_bf16 v[120:123], v[222:225], v[166:169], v[120:123]
	v_mfma_f32_16x16x32_bf16 v[100:103], v[210:213], v[174:177], v[100:103]
	v_mfma_f32_16x16x32_bf16 v[96:99], v[222:225], v[174:177], v[96:99]
	v_mfma_f32_16x16x32_bf16 v[84:87], v[210:213], v[194:197], v[84:87]
	v_mfma_f32_16x16x32_bf16 v[80:83], v[222:225], v[194:197], v[80:83]
	v_mfma_f32_16x16x32_bf16 v[68:71], v[210:213], v[202:205], v[68:71]
	v_mfma_f32_16x16x32_bf16 v[64:67], v[222:225], v[202:205], v[64:67]
	v_mfma_f32_16x16x32_bf16 v[124:127], v[214:217], v[170:173], v[124:127]
	v_mfma_f32_16x16x32_bf16 v[120:123], v[226:229], v[170:173], v[120:123]
	v_mfma_f32_16x16x32_bf16 v[100:103], v[214:217], v[178:181], v[100:103]
	v_mfma_f32_16x16x32_bf16 v[96:99], v[226:229], v[178:181], v[96:99]
	v_mfma_f32_16x16x32_bf16 v[84:87], v[214:217], v[198:201], v[84:87]
	v_mfma_f32_16x16x32_bf16 v[80:83], v[226:229], v[198:201], v[80:83]
	v_mfma_f32_16x16x32_bf16 v[68:71], v[214:217], v[206:209], v[68:71]
	v_mfma_f32_16x16x32_bf16 v[64:67], v[226:229], v[206:209], v[64:67]
	s_mov_b32 m0, s51
	v_lshl_add_u64 v[150:151], v[218:219], 0, s[10:11]
	s_barrier
	ds_read_b128 v[166:169], v191 offset:49152
	ds_read_b128 v[170:173], v191 offset:50176
	ds_read_b128 v[174:177], v191 offset:51200
	ds_read_b128 v[178:181], v191 offset:52224
	ds_read_b128 v[194:197], v191 offset:53248
	ds_read_b128 v[198:201], v191 offset:54272
	ds_read_b128 v[202:205], v191 offset:55296
	ds_read_b128 v[206:209], v191 offset:56320
	global_load_lds_dwordx4 v[150:151], off
	s_mov_b32 m0, s52
	v_lshl_add_u64 v[150:151], v[230:231], 0, s[10:11]
	global_load_lds_dwordx4 v[150:151], off
	s_barrier
;     ...
;         G_PAIR(0, 1);
; #pragma unroll 1
;         for (int t = 2; t < nt; t += 2) G_PAIR(t, 0);
	s_waitcnt lgkmcnt(0)
	v_mfma_f32_16x16x32_bf16 v[52:55], v[134:137], v[166:169], v[52:55]
	v_mfma_f32_16x16x32_bf16 v[48:51], v[142:145], v[166:169], v[48:51]
	v_mfma_f32_16x16x32_bf16 v[44:47], v[134:137], v[174:177], v[44:47]
	v_mfma_f32_16x16x32_bf16 v[36:39], v[142:145], v[174:177], v[36:39]
	v_mfma_f32_16x16x32_bf16 v[28:31], v[134:137], v[194:197], v[28:31]
	v_mfma_f32_16x16x32_bf16 v[20:23], v[142:145], v[194:197], v[20:23]
	v_mfma_f32_16x16x32_bf16 v[12:15], v[134:137], v[202:205], v[12:15]
	v_mfma_f32_16x16x32_bf16 v[4:7], v[142:145], v[202:205], v[4:7]
	v_mfma_f32_16x16x32_bf16 v[52:55], v[138:141], v[170:173], v[52:55]
	v_mfma_f32_16x16x32_bf16 v[48:51], v[146:149], v[170:173], v[48:51]
	v_mfma_f32_16x16x32_bf16 v[44:47], v[138:141], v[178:181], v[44:47]
	v_mfma_f32_16x16x32_bf16 v[36:39], v[146:149], v[178:181], v[36:39]
	v_mfma_f32_16x16x32_bf16 v[28:31], v[138:141], v[198:201], v[28:31]
	v_mfma_f32_16x16x32_bf16 v[20:23], v[146:149], v[198:201], v[20:23]
	s_add_u32 s36, s36, 0xb0080
	v_mfma_f32_16x16x32_bf16 v[12:15], v[138:141], v[206:209], v[12:15]
	s_addc_u32 s37, s37, 0
	v_mfma_f32_16x16x32_bf16 v[4:7], v[146:149], v[206:209], v[4:7]
	s_barrier
	s_mov_b32 m0, s65
	v_lshl_add_u64 v[134:135], s[36:37], 0, v[156:157]
	global_load_lds_dwordx4 v[134:135], off
	s_mov_b32 m0, s66
	v_lshl_add_u64 v[134:135], s[36:37], 0, v[160:161]
	global_load_lds_dwordx4 v[134:135], off
	s_waitcnt vmcnt(6)
	s_barrier
	v_mfma_f32_16x16x32_bf16 v[60:63], v[210:213], v[166:169], v[60:63]
	v_mfma_f32_16x16x32_bf16 v[56:59], v[222:225], v[166:169], v[56:59]
	v_mfma_f32_16x16x32_bf16 v[40:43], v[210:213], v[174:177], v[40:43]
	v_mfma_f32_16x16x32_bf16 v[32:35], v[222:225], v[174:177], v[32:35]
	v_mfma_f32_16x16x32_bf16 v[24:27], v[210:213], v[194:197], v[24:27]
	v_mfma_f32_16x16x32_bf16 v[16:19], v[222:225], v[194:197], v[16:19]
	v_mfma_f32_16x16x32_bf16 v[8:11], v[210:213], v[202:205], v[8:11]
	v_mfma_f32_16x16x32_bf16 v[0:3], v[222:225], v[202:205], v[0:3]
	v_mfma_f32_16x16x32_bf16 v[60:63], v[214:217], v[170:173], v[60:63]
	v_mfma_f32_16x16x32_bf16 v[56:59], v[226:229], v[170:173], v[56:59]
	v_mfma_f32_16x16x32_bf16 v[40:43], v[214:217], v[178:181], v[40:43]
	v_mfma_f32_16x16x32_bf16 v[32:35], v[226:229], v[178:181], v[32:35]
	s_add_i32 s67, s67, 2
	v_mfma_f32_16x16x32_bf16 v[24:27], v[214:217], v[198:201], v[24:27]
	s_add_u32 s34, s34, 0x100
	v_mfma_f32_16x16x32_bf16 v[16:19], v[226:229], v[198:201], v[16:19]
	s_addc_u32 s35, s35, 0
	v_mfma_f32_16x16x32_bf16 v[8:11], v[214:217], v[206:209], v[8:11]
	s_cmp_gt_u32 s67, 39
	v_mfma_f32_16x16x32_bf16 v[0:3], v[226:229], v[206:209], v[0:3]
	s_cbranch_scc0 .Lrot_357
	s_barrier
	ds_read_b128 v[134:137], v190
	ds_read_b128 v[138:141], v190 offset:1024
	ds_read_b128 v[142:145], v190 offset:2048
	ds_read_b128 v[146:149], v190 offset:3072
	s_mov_b32 m0, s54
	v_lshl_add_u64 v[150:151], v[128:129], 0, s[34:35]
	ds_read_b128 v[166:169], v191
	ds_read_b128 v[170:173], v191 offset:1024
	ds_read_b128 v[174:177], v191 offset:2048
	ds_read_b128 v[178:181], v191 offset:3072
	ds_read_b128 v[194:197], v191 offset:4096
	ds_read_b128 v[198:201], v191 offset:5120
	ds_read_b128 v[202:205], v191 offset:6144
	ds_read_b128 v[206:209], v191 offset:7168
	global_load_lds_dwordx4 v[150:151], off
	s_mov_b32 m0, s55
	v_lshl_add_u64 v[150:151], v[130:131], 0, s[34:35]
	global_load_lds_dwordx4 v[150:151], off
	s_waitcnt lgkmcnt(8)
	s_barrier
	s_waitcnt lgkmcnt(0)
	v_mfma_f32_16x16x32_bf16 v[116:119], v[134:137], v[166:169], v[116:119]
	s_add_i32 s36, s34, 0xfff50080
	v_mfma_f32_16x16x32_bf16 v[112:115], v[142:145], v[166:169], v[112:115]
	s_cmp_eq_u32 s67, 40
	v_mfma_f32_16x16x32_bf16 v[108:111], v[134:137], v[174:177], v[108:111]
	s_cselect_b32 s69, s27, s29
	v_mfma_f32_16x16x32_bf16 v[104:107], v[142:145], v[174:177], v[104:107]
	s_cselect_b32 s68, s26, s28
	v_mfma_f32_16x16x32_bf16 v[92:95], v[134:137], v[194:197], v[92:95]
	s_cselect_b32 s37, s9, s31
	v_mfma_f32_16x16x32_bf16 v[88:91], v[142:145], v[194:197], v[88:91]
	s_cselect_b32 s70, s8, s30
	v_mfma_f32_16x16x32_bf16 v[76:79], v[134:137], v[202:205], v[76:79]
	v_mfma_f32_16x16x32_bf16 v[72:75], v[142:145], v[202:205], v[72:75]
	v_mfma_f32_16x16x32_bf16 v[116:119], v[138:141], v[170:173], v[116:119]
	v_mfma_f32_16x16x32_bf16 v[112:115], v[146:149], v[170:173], v[112:115]
	v_mfma_f32_16x16x32_bf16 v[108:111], v[138:141], v[178:181], v[108:111]
	v_mfma_f32_16x16x32_bf16 v[104:107], v[146:149], v[178:181], v[104:107]
	v_mfma_f32_16x16x32_bf16 v[92:95], v[138:141], v[198:201], v[92:95]
	v_mfma_f32_16x16x32_bf16 v[88:91], v[146:149], v[198:201], v[88:91]
	v_mfma_f32_16x16x32_bf16 v[76:79], v[138:141], v[206:209], v[76:79]
	v_mfma_f32_16x16x32_bf16 v[72:75], v[146:149], v[206:209], v[72:75]
	s_barrier
	s_cselect_b32 s71, 0, s36
	s_add_u32 s36, s70, s71
	s_addc_u32 s37, s37, 0
	s_mov_b32 m0, s56
	v_lshl_add_u64 v[150:151], s[36:37], 0, v[156:157]
	ds_read_b128 v[210:213], v192
	ds_read_b128 v[214:217], v192 offset:1024
	ds_read_b128 v[222:225], v192 offset:2048
	ds_read_b128 v[226:229], v192 offset:3072
	global_load_lds_dwordx4 v[150:151], off
	s_mov_b32 m0, s57
	v_lshl_add_u64 v[182:183], s[36:37], 0, v[160:161]
	global_load_lds_dwordx4 v[182:183], off
	s_barrier
;     __device__ __forceinline__ void epi(const f32x4 (&acc)[2][2][4][2], const Unit& u, int wr, int wc, int fr, int fq) const {
;     ...
;             u32x4 xo[4][2];
; #pragma unroll
;             for (int m = 0; m < 4; ++m)
; #pragma unroll
;                 for (int bj = 0; bj < 2; ++bj) xo[m][bj] = *(const u32x4*)(xb + (size_t)(row0 + ai * 128 + m * 16) * D + col0 + bj * 128);
	s_waitcnt lgkmcnt(0)
	v_mfma_f32_16x16x32_bf16 v[124:127], v[210:213], v[166:169], v[124:127]
	v_mfma_f32_16x16x32_bf16 v[120:123], v[222:225], v[166:169], v[120:123]
	v_mfma_f32_16x16x32_bf16 v[100:103], v[210:213], v[174:177], v[100:103]
	v_mfma_f32_16x16x32_bf16 v[96:99], v[222:225], v[174:177], v[96:99]
	v_mfma_f32_16x16x32_bf16 v[84:87], v[210:213], v[194:197], v[84:87]
	v_mfma_f32_16x16x32_bf16 v[80:83], v[222:225], v[194:197], v[80:83]
	v_mfma_f32_16x16x32_bf16 v[68:71], v[210:213], v[202:205], v[68:71]
	v_mfma_f32_16x16x32_bf16 v[64:67], v[222:225], v[202:205], v[64:67]
	v_mfma_f32_16x16x32_bf16 v[124:127], v[214:217], v[170:173], v[124:127]
	v_mfma_f32_16x16x32_bf16 v[120:123], v[226:229], v[170:173], v[120:123]
	v_mfma_f32_16x16x32_bf16 v[100:103], v[214:217], v[178:181], v[100:103]
	v_mfma_f32_16x16x32_bf16 v[96:99], v[226:229], v[178:181], v[96:99]
	v_mfma_f32_16x16x32_bf16 v[84:87], v[214:217], v[198:201], v[84:87]
	v_mfma_f32_16x16x32_bf16 v[80:83], v[226:229], v[198:201], v[80:83]
	v_mfma_f32_16x16x32_bf16 v[68:71], v[214:217], v[206:209], v[68:71]
	v_mfma_f32_16x16x32_bf16 v[64:67], v[226:229], v[206:209], v[64:67]
	s_add_u32 s68, s68, s71
	s_addc_u32 s69, s69, 0
	s_mov_b32 m0, s46
	v_lshl_add_u64 v[218:219], s[68:69], 0, v[154:155]
	s_barrier
	ds_read_b128 v[166:169], v191 offset:16384
	ds_read_b128 v[170:173], v191 offset:17408
	ds_read_b128 v[174:177], v191 offset:18432
	ds_read_b128 v[178:181], v191 offset:19456
	ds_read_b128 v[194:197], v191 offset:20480
	ds_read_b128 v[198:201], v191 offset:21504
	ds_read_b128 v[202:205], v191 offset:22528
	ds_read_b128 v[206:209], v191 offset:23552
	global_load_lds_dwordx4 v[218:219], off
	s_mov_b32 m0, s47
	v_lshl_add_u64 v[230:231], s[68:69], 0, v[158:159]
	global_load_lds_dwordx4 v[230:231], off
	s_barrier
	s_waitcnt lgkmcnt(0)
	v_mfma_f32_16x16x32_bf16 v[52:55], v[134:137], v[166:169], v[52:55]
	v_mfma_f32_16x16x32_bf16 v[48:51], v[142:145], v[166:169], v[48:51]
	v_mfma_f32_16x16x32_bf16 v[44:47], v[134:137], v[174:177], v[44:47]
	v_mfma_f32_16x16x32_bf16 v[36:39], v[142:145], v[174:177], v[36:39]
	v_mfma_f32_16x16x32_bf16 v[28:31], v[134:137], v[194:197], v[28:31]
	v_mfma_f32_16x16x32_bf16 v[20:23], v[142:145], v[194:197], v[20:23]
	v_mfma_f32_16x16x32_bf16 v[12:15], v[134:137], v[202:205], v[12:15]
	v_mfma_f32_16x16x32_bf16 v[4:7], v[142:145], v[202:205], v[4:7]
	v_mfma_f32_16x16x32_bf16 v[52:55], v[138:141], v[170:173], v[52:55]
	v_mfma_f32_16x16x32_bf16 v[48:51], v[146:149], v[170:173], v[48:51]
	v_mfma_f32_16x16x32_bf16 v[44:47], v[138:141], v[178:181], v[44:47]
	v_mfma_f32_16x16x32_bf16 v[36:39], v[146:149], v[178:181], v[36:39]
	v_mfma_f32_16x16x32_bf16 v[28:31], v[138:141], v[198:201], v[28:31]
	v_mfma_f32_16x16x32_bf16 v[20:23], v[146:149], v[198:201], v[20:23]
	v_mfma_f32_16x16x32_bf16 v[12:15], v[138:141], v[206:209], v[12:15]
	v_mfma_f32_16x16x32_bf16 v[4:7], v[146:149], v[206:209], v[4:7]
	s_barrier
	s_add_u32 s70, s36, 0xb0000
	s_addc_u32 s71, s37, 0
	s_mov_b32 m0, s0
	v_lshl_add_u64 v[134:135], s[70:71], 0, v[156:157]
	global_load_lds_dwordx4 v[134:135], off
	s_mov_b32 m0, s62
	v_lshl_add_u64 v[134:135], s[70:71], 0, v[160:161]
	global_load_lds_dwordx4 v[134:135], off
	s_waitcnt vmcnt(6)
	s_barrier
	v_mfma_f32_16x16x32_bf16 v[60:63], v[210:213], v[166:169], v[60:63]
	v_lshl_or_b32 v248, s40, 8, v189
	v_mfma_f32_16x16x32_bf16 v[56:59], v[222:225], v[166:169], v[56:59]
	v_lshl_add_u32 v250, s61, 8, v153
	v_mfma_f32_16x16x32_bf16 v[40:43], v[210:213], v[174:177], v[40:43]
	v_ashrrev_i32_e32 v249, 31, v248
	v_mfma_f32_16x16x32_bf16 v[32:35], v[222:225], v[174:177], v[32:35]
	v_lshlrev_b64 v[248:249], 1, v[248:249]
	v_mfma_f32_16x16x32_bf16 v[24:27], v[210:213], v[194:197], v[24:27]
	v_ashrrev_i32_e32 v251, 31, v250
	v_mfma_f32_16x16x32_bf16 v[16:19], v[222:225], v[194:197], v[16:19]
	v_lshl_add_u64 v[248:249], s[20:21], 0, v[248:249]
	v_mfma_f32_16x16x32_bf16 v[8:11], v[210:213], v[202:205], v[8:11]
	v_lshlrev_b64 v[250:251], 11, v[250:251]
	v_mfma_f32_16x16x32_bf16 v[0:3], v[222:225], v[202:205], v[0:3]
	v_lshl_add_u64 v[252:253], v[248:249], 0, v[250:251]
	v_mfma_f32_16x16x32_bf16 v[60:63], v[214:217], v[170:173], v[60:63]
	global_load_dwordx4 v[232:235], v[252:253], off
	v_mfma_f32_16x16x32_bf16 v[56:59], v[226:229], v[170:173], v[56:59]
	global_load_dwordx4 v[236:239], v[252:253], off offset:256
	v_mfma_f32_16x16x32_bf16 v[40:43], v[214:217], v[178:181], v[40:43]
	v_mov_b32_e32 v250, 0x8000
	v_mfma_f32_16x16x32_bf16 v[32:35], v[226:229], v[178:181], v[32:35]
	v_mov_b32_e32 v251, 0
	v_mfma_f32_16x16x32_bf16 v[24:27], v[214:217], v[198:201], v[24:27]
	v_lshl_add_u64 v[250:251], v[252:253], 0, v[250:251]
	v_mfma_f32_16x16x32_bf16 v[16:19], v[226:229], v[198:201], v[16:19]
	global_load_dwordx4 v[240:243], v[250:251], off
	v_mfma_f32_16x16x32_bf16 v[8:11], v[214:217], v[206:209], v[8:11]
	global_load_dwordx4 v[244:247], v[250:251], off offset:256
	v_mfma_f32_16x16x32_bf16 v[0:3], v[226:229], v[206:209], v[0:3]
	s_barrier
	ds_read_b128 v[134:137], v132
	ds_read_b128 v[138:141], v132 offset:1024
	ds_read_b128 v[142:145], v132 offset:2048
	ds_read_b128 v[146:149], v132 offset:3072
	s_add_u32 s68, s68, 0xb0000
	s_addc_u32 s69, s69, 0
	s_mov_b32 m0, s48
	v_lshl_add_u64 v[210:211], s[68:69], 0, v[154:155]
	ds_read_b128 v[166:169], v191 offset:32768
	ds_read_b128 v[170:173], v191 offset:33792
	ds_read_b128 v[174:177], v191 offset:34816
	ds_read_b128 v[178:181], v191 offset:35840
	ds_read_b128 v[194:197], v191 offset:36864
	ds_read_b128 v[198:201], v191 offset:37888
	ds_read_b128 v[202:205], v191 offset:38912
	ds_read_b128 v[206:209], v191 offset:39936
	global_load_lds_dwordx4 v[210:211], off
	s_mov_b32 m0, s49
	v_lshl_add_u64 v[210:211], s[68:69], 0, v[158:159]
	global_load_lds_dwordx4 v[210:211], off
	s_waitcnt lgkmcnt(8)
	s_barrier
	s_waitcnt lgkmcnt(0)
	v_mfma_f32_16x16x32_bf16 v[116:119], v[134:137], v[166:169], v[116:119]
	v_mfma_f32_16x16x32_bf16 v[112:115], v[142:145], v[166:169], v[112:115]
	v_mfma_f32_16x16x32_bf16 v[108:111], v[134:137], v[174:177], v[108:111]
	v_mfma_f32_16x16x32_bf16 v[104:107], v[142:145], v[174:177], v[104:107]
	v_mfma_f32_16x16x32_bf16 v[92:95], v[134:137], v[194:197], v[92:95]
	v_mfma_f32_16x16x32_bf16 v[88:91], v[142:145], v[194:197], v[88:91]
	v_mfma_f32_16x16x32_bf16 v[76:79], v[134:137], v[202:205], v[76:79]
	v_mfma_f32_16x16x32_bf16 v[72:75], v[142:145], v[202:205], v[72:75]
	v_mfma_f32_16x16x32_bf16 v[116:119], v[138:141], v[170:173], v[116:119]
	v_mfma_f32_16x16x32_bf16 v[112:115], v[146:149], v[170:173], v[112:115]
	v_mfma_f32_16x16x32_bf16 v[108:111], v[138:141], v[178:181], v[108:111]
	v_mfma_f32_16x16x32_bf16 v[104:107], v[146:149], v[178:181], v[104:107]
	v_mfma_f32_16x16x32_bf16 v[92:95], v[138:141], v[198:201], v[92:95]
	v_mfma_f32_16x16x32_bf16 v[88:91], v[146:149], v[198:201], v[88:91]
	v_mfma_f32_16x16x32_bf16 v[76:79], v[138:141], v[206:209], v[76:79]
	v_mfma_f32_16x16x32_bf16 v[72:75], v[146:149], v[206:209], v[72:75]
	s_barrier
	s_mov_b32 m0, s63
	v_lshl_add_u64 v[150:151], v[150:151], 0, s[10:11]
	ds_read_b128 v[210:213], v133
	ds_read_b128 v[214:217], v133 offset:1024
	ds_read_b128 v[222:225], v133 offset:2048
	ds_read_b128 v[226:229], v133 offset:3072
	global_load_lds_dwordx4 v[150:151], off
	s_mov_b32 m0, s64
	v_lshl_add_u64 v[150:151], v[182:183], 0, s[10:11]
	global_load_lds_dwordx4 v[150:151], off
	s_barrier
	s_waitcnt lgkmcnt(0)
	v_mfma_f32_16x16x32_bf16 v[124:127], v[210:213], v[166:169], v[124:127]
	v_mfma_f32_16x16x32_bf16 v[120:123], v[222:225], v[166:169], v[120:123]
	v_mfma_f32_16x16x32_bf16 v[100:103], v[210:213], v[174:177], v[100:103]
	v_mfma_f32_16x16x32_bf16 v[96:99], v[222:225], v[174:177], v[96:99]
	v_mfma_f32_16x16x32_bf16 v[84:87], v[210:213], v[194:197], v[84:87]
	v_mfma_f32_16x16x32_bf16 v[80:83], v[222:225], v[194:197], v[80:83]
	v_mfma_f32_16x16x32_bf16 v[68:71], v[210:213], v[202:205], v[68:71]
	v_mfma_f32_16x16x32_bf16 v[64:67], v[222:225], v[202:205], v[64:67]
	v_mfma_f32_16x16x32_bf16 v[124:127], v[214:217], v[170:173], v[124:127]
	v_mfma_f32_16x16x32_bf16 v[120:123], v[226:229], v[170:173], v[120:123]
	v_mfma_f32_16x16x32_bf16 v[100:103], v[214:217], v[178:181], v[100:103]
	v_mfma_f32_16x16x32_bf16 v[96:99], v[226:229], v[178:181], v[96:99]
	v_mfma_f32_16x16x32_bf16 v[84:87], v[214:217], v[198:201], v[84:87]
	v_mfma_f32_16x16x32_bf16 v[80:83], v[226:229], v[198:201], v[80:83]
	v_mfma_f32_16x16x32_bf16 v[68:71], v[214:217], v[206:209], v[68:71]
	v_mfma_f32_16x16x32_bf16 v[64:67], v[226:229], v[206:209], v[64:67]
	s_mov_b32 m0, s51
	v_lshl_add_u64 v[150:151], v[218:219], 0, s[10:11]
	s_barrier
	ds_read_b128 v[166:169], v191 offset:49152
	ds_read_b128 v[170:173], v191 offset:50176
	ds_read_b128 v[174:177], v191 offset:51200
	ds_read_b128 v[178:181], v191 offset:52224
	ds_read_b128 v[194:197], v191 offset:53248
	ds_read_b128 v[198:201], v191 offset:54272
	ds_read_b128 v[202:205], v191 offset:55296
	ds_read_b128 v[206:209], v191 offset:56320
	global_load_lds_dwordx4 v[150:151], off
	s_mov_b32 m0, s52
	v_lshl_add_u64 v[150:151], v[230:231], 0, s[10:11]
	global_load_lds_dwordx4 v[150:151], off
	s_barrier
	s_waitcnt lgkmcnt(0)
	v_mfma_f32_16x16x32_bf16 v[52:55], v[134:137], v[166:169], v[52:55]
	v_mfma_f32_16x16x32_bf16 v[48:51], v[142:145], v[166:169], v[48:51]
	v_mfma_f32_16x16x32_bf16 v[44:47], v[134:137], v[174:177], v[44:47]
	v_mfma_f32_16x16x32_bf16 v[36:39], v[142:145], v[174:177], v[36:39]
	v_mfma_f32_16x16x32_bf16 v[28:31], v[134:137], v[194:197], v[28:31]
	v_mfma_f32_16x16x32_bf16 v[20:23], v[142:145], v[194:197], v[20:23]
	v_mfma_f32_16x16x32_bf16 v[12:15], v[134:137], v[202:205], v[12:15]
	v_mfma_f32_16x16x32_bf16 v[4:7], v[142:145], v[202:205], v[4:7]
	v_mfma_f32_16x16x32_bf16 v[52:55], v[138:141], v[170:173], v[52:55]
	v_mfma_f32_16x16x32_bf16 v[48:51], v[146:149], v[170:173], v[48:51]
	v_mfma_f32_16x16x32_bf16 v[44:47], v[138:141], v[178:181], v[44:47]
	v_mfma_f32_16x16x32_bf16 v[36:39], v[146:149], v[178:181], v[36:39]
	v_mfma_f32_16x16x32_bf16 v[28:31], v[138:141], v[198:201], v[28:31]
	v_mfma_f32_16x16x32_bf16 v[20:23], v[146:149], v[198:201], v[20:23]
	v_mfma_f32_16x16x32_bf16 v[12:15], v[138:141], v[206:209], v[12:15]
	v_mfma_f32_16x16x32_bf16 v[4:7], v[146:149], v[206:209], v[4:7]
	s_barrier
	s_add_u32 s36, s36, 0xb0080
	s_addc_u32 s37, s37, 0
	s_mov_b32 m0, s65
	v_lshl_add_u64 v[134:135], s[36:37], 0, v[156:157]
	global_load_lds_dwordx4 v[134:135], off
	s_mov_b32 m0, s66
	v_lshl_add_u64 v[134:135], s[36:37], 0, v[160:161]
	global_load_lds_dwordx4 v[134:135], off
	s_waitcnt vmcnt(6)
	s_barrier
	v_mfma_f32_16x16x32_bf16 v[60:63], v[210:213], v[166:169], v[60:63]
	v_mfma_f32_16x16x32_bf16 v[56:59], v[222:225], v[166:169], v[56:59]
	v_mfma_f32_16x16x32_bf16 v[40:43], v[210:213], v[174:177], v[40:43]
	v_mfma_f32_16x16x32_bf16 v[32:35], v[222:225], v[174:177], v[32:35]
	v_mfma_f32_16x16x32_bf16 v[24:27], v[210:213], v[194:197], v[24:27]
	v_mfma_f32_16x16x32_bf16 v[16:19], v[222:225], v[194:197], v[16:19]
	v_mfma_f32_16x16x32_bf16 v[8:11], v[210:213], v[202:205], v[8:11]
	v_mfma_f32_16x16x32_bf16 v[0:3], v[222:225], v[202:205], v[0:3]
	v_mfma_f32_16x16x32_bf16 v[60:63], v[214:217], v[170:173], v[60:63]
	v_mfma_f32_16x16x32_bf16 v[56:59], v[226:229], v[170:173], v[56:59]
	v_mfma_f32_16x16x32_bf16 v[40:43], v[214:217], v[178:181], v[40:43]
	v_mfma_f32_16x16x32_bf16 v[32:35], v[226:229], v[178:181], v[32:35]
	v_mfma_f32_16x16x32_bf16 v[24:27], v[214:217], v[198:201], v[24:27]
	v_mfma_f32_16x16x32_bf16 v[16:19], v[226:229], v[198:201], v[16:19]
	v_mfma_f32_16x16x32_bf16 v[8:11], v[214:217], v[206:209], v[8:11]
	v_mfma_f32_16x16x32_bf16 v[0:3], v[226:229], v[206:209], v[0:3]
	s_add_i32 s67, s67, 2
	s_add_u32 s34, s34, 0x100
	s_addc_u32 s35, s35, 0
	s_cmp_gt_u32 s67, 41
	s_barrier
; __device__ __forceinline__ unsigned pk2(float lo, float hi) { unsigned r; asm volatile("v_cvt_pk_bf16_f32 %0, %1, %2" : "=v"(r) : "v"(lo), "v"(hi)); return r; }
; __device__ __forceinline__ unsigned pk2(float lo, float hi) { return f2bf(lo) | (f2bf(hi) << 16); }
;     __device__ __forceinline__ void epi(const f32x4 (&acc)[2][2][4][2], const Unit& u, int wr, int wc, int fr, int fq) const {
;     ...
;             u32x4 xo[4][2];
; #pragma unroll
;             for (int m = 0; m < 4; ++m)
; #pragma unroll
;                 for (int bj = 0; bj < 2; ++bj) xo[m][bj] = *(const u32x4*)(xb + (size_t)(row0 + ai * 128 + m * 16) * D + col0 + bj * 128);
; #pragma unroll
;             for (int m = 0; m < 4; ++m) {
;                 const int row = row0 + ai * 128 + m * 16; const size_t off = (size_t)row * D + col0; float ss = 0.f;
; #pragma unroll
;                 for (int bj = 0; bj < 2; ++bj) {
;                     const u32x4 o = xo[m][bj]; const f32x4 a0v = acc[ai][bj][m][0], a1v = acc[ai][bj][m][1];
;                     const float v0 = bf_lo(o.x) + coef * a0v[0], v1 = bf_hi(o.x) + coef * a0v[1], v2 = bf_lo(o.y) + coef * a0v[2], v3 = bf_hi(o.y) + coef * a0v[3];
;                     const float v4 = bf_lo(o.z) + coef * a1v[0], v5 = bf_hi(o.z) + coef * a1v[1], v6 = bf_lo(o.w) + coef * a1v[2], v7 = bf_hi(o.w) + coef * a1v[3];
;                     u32x4 w; w.x = pk2(v0, v1); w.y = pk2(v2, v3); w.z = pk2(v4, v5); w.w = pk2(v6, v7);
;                     *(u32x4*)(xb + off + bj * 128) = w;
;                     ss += ((v0 * v0 + v1 * v1) + (v2 * v2 + v3 * v3)) + ((v4 * v4 + v5 * v5) + (v6 * v6 + v7 * v7));
;                 }
;                 ss += __shfl_xor(ss, 16); ss += __shfl_xor(ss, 32);
;                 if (fq == 0) rowss[(size_t)row * 32 + u.pn * 4 + wc] = ss;
;             }
	v_lshl_or_b32 v166, s40, 8, v189
	v_lshl_add_u32 v170, s61, 8, v153
	v_ashrrev_i32_e32 v167, 31, v166
	v_lshlrev_b64 v[202:203], 1, v[166:167]
	v_ashrrev_i32_e32 v171, 31, v170
	v_lshl_add_u64 v[168:169], s[20:21], 0, v[202:203]
	v_lshlrev_b64 v[204:205], 11, v[170:171]
	v_lshl_add_u64 v[128:129], v[168:169], 0, v[204:205]
	v_mov_b32_e32 v218, 0x40000
	v_mov_b32_e32 v219, 0
	v_lshl_add_u64 v[216:217], v[128:129], 0, v[218:219]
	v_mov_b32_e32 v218, 0x8000
	s_waitcnt vmcnt(8)
	v_mov_b64_e32 v[194:195], v[232:233]
	v_mov_b64_e32 v[196:197], v[234:235]
	v_mov_b64_e32 v[198:199], v[236:237]
	v_mov_b64_e32 v[200:201], v[238:239]
	v_or_b32_e32 v180, 16, v170
	v_or_b32_e32 v176, 32, v170
	v_or_b32_e32 v172, 48, v170
	v_ashrrev_i32_e32 v181, 31, v180
	v_ashrrev_i32_e32 v177, 31, v176
	v_ashrrev_i32_e32 v173, 31, v172
	v_lshlrev_b64 v[182:183], 11, v[180:181]
	v_lshlrev_b64 v[178:179], 11, v[176:177]
	v_lshlrev_b64 v[174:175], 11, v[172:173]
	v_lshl_add_u64 v[128:129], v[168:169], 0, v[182:183]
	v_lshl_add_u64 v[130:131], v[168:169], 0, v[178:179]
	v_lshl_add_u64 v[206:207], v[168:169], 0, v[174:175]
	v_mov_b64_e32 v[148:149], v[240:241]
	v_mov_b64_e32 v[150:151], v[242:243]
	v_mov_b64_e32 v[144:145], v[244:245]
	v_mov_b64_e32 v[146:147], v[246:247]
	global_load_dwordx4 v[140:143], v[130:131], off
	global_load_dwordx4 v[136:139], v[130:131], off offset:256
	global_load_dwordx4 v[132:135], v[206:207], off
	s_nop 0
	global_load_dwordx4 v[128:131], v[206:207], off offset:256
	global_load_dwordx4 v[222:225], v[216:217], off
	global_load_dwordx4 v[226:229], v[216:217], off offset:256
	v_lshl_add_u64 v[216:217], v[216:217], 0, v[218:219]
	global_load_dwordx4 v[230:233], v[216:217], off
	global_load_dwordx4 v[234:237], v[216:217], off offset:256
	v_lshl_add_u64 v[216:217], v[216:217], 0, v[218:219]
	global_load_dwordx4 v[238:241], v[216:217], off
	global_load_dwordx4 v[242:245], v[216:217], off offset:256
	v_lshl_add_u64 v[216:217], v[216:217], 0, v[218:219]
	global_load_dwordx4 v[246:249], v[216:217], off
	global_load_dwordx4 v[250:253], v[216:217], off offset:256
	v_and_b32_e32 v206, 64, v193
	v_xor_b32_e32 v208, 16, v193
	v_add_u32_e32 v206, 64, v206
	v_cmp_lt_i32_e32 vcc, v208, v206
	v_lshlrev_b32_e32 v209, 16, v195
	v_cndmask_b32_e32 v207, v193, v208, vcc
	v_lshlrev_b32_e32 v208, 16, v194
	v_and_b32_e32 v194, 0xffff0000, v194
	v_and_b32_e32 v195, 0xffff0000, v195
	v_lshlrev_b32_e32 v210, 16, v196
	v_and_b32_e32 v196, 0xffff0000, v196
	v_lshlrev_b32_e32 v211, 16, v197
	v_and_b32_e32 v197, 0xffff0000, v197
	v_lshlrev_b32_e32 v212, 16, v198
	v_and_b32_e32 v198, 0xffff0000, v198
	v_lshlrev_b32_e32 v213, 16, v199
	v_and_b32_e32 v199, 0xffff0000, v199
	v_lshlrev_b32_e32 v214, 16, v200
	v_and_b32_e32 v200, 0xffff0000, v200
	v_lshlrev_b32_e32 v215, 16, v201
	v_and_b32_e32 v201, 0xffff0000, v201
	v_fmac_f32_e32 v194, 0.5, v117
	v_fmac_f32_e32 v195, 0.5, v119
	v_fmac_f32_e32 v196, 0.5, v113
	v_fmac_f32_e32 v197, 0.5, v115
	v_fmac_f32_e32 v198, 0.5, v125
	v_fmac_f32_e32 v199, 0.5, v127
	v_fmac_f32_e32 v200, 0.5, v121
	v_fmac_f32_e32 v201, 0.5, v123
	v_fmac_f32_e32 v208, 0.5, v116
	v_fmac_f32_e32 v209, 0.5, v118
	v_fmac_f32_e32 v210, 0.5, v112
	v_fmac_f32_e32 v211, 0.5, v114
	v_fmac_f32_e32 v212, 0.5, v124
	v_fmac_f32_e32 v213, 0.5, v126
	v_fmac_f32_e32 v214, 0.5, v120
	v_fmac_f32_e32 v215, 0.5, v122
	v_mul_f32_e32 v112, v194, v194
	v_mul_f32_e32 v113, v195, v195
	v_mul_f32_e32 v118, v196, v196
	v_mul_f32_e32 v119, v197, v197
	v_mul_f32_e32 v120, v198, v198
	v_mul_f32_e32 v121, v199, v199
	v_mul_f32_e32 v122, v200, v200
	v_mul_f32_e32 v123, v201, v201
	v_fmac_f32_e32 v112, v208, v208
	v_fmac_f32_e32 v113, v209, v209
	v_fmac_f32_e32 v118, v210, v210
	v_fmac_f32_e32 v119, v211, v211
	v_fmac_f32_e32 v120, v212, v212
	v_fmac_f32_e32 v121, v213, v213
	v_fmac_f32_e32 v122, v214, v214
	v_fmac_f32_e32 v123, v215, v215
	v_add_f32_e32 v112, v112, v113
	v_add_f32_e32 v113, v118, v119
	v_add_f32_e32 v118, v120, v121
	v_add_f32_e32 v119, v122, v123
	v_add_f32_e32 v112, v112, v113
	v_add_f32_e32 v113, v118, v119
	v_add_f32_e32 v113, v112, v113
	v_lshlrev_b32_e32 v112, 2, v207
	ds_bpermute_b32 v122, v112, v113
	v_lshl_add_u64 v[118:119], s[20:21], 0, v[204:205]
	v_cvt_pk_bf16_f32 v114, v208, v194
	v_lshl_add_u64 v[120:121], v[118:119], 0, v[202:203]
	v_cvt_pk_bf16_f32 v115, v209, v195
	v_cvt_pk_bf16_f32 v116, v210, v196
	v_cvt_pk_bf16_f32 v117, v211, v197
	global_store_dwordx4 v[120:121], v[114:117], off
	s_waitcnt lgkmcnt(0)
	s_nop 0
	v_add_f32_e32 v114, v113, v122
	v_xor_b32_e32 v113, 32, v193
	v_cmp_lt_i32_e32 vcc, v113, v206
	v_cvt_pk_bf16_f32 v116, v212, v198
	v_cvt_pk_bf16_f32 v117, v213, v199
	v_cvt_pk_bf16_f32 v118, v214, v200
	v_cvt_pk_bf16_f32 v119, v215, v201
	global_store_dwordx4 v[120:121], v[116:119], off offset:256
	s_nop 0
	v_cndmask_b32_e32 v113, v193, v113, vcc
	v_lshlrev_b32_e32 v113, 2, v113
	ds_bpermute_b32 v115, v113, v114
	s_and_saveexec_b64 s[28:29], s[6:7]
	s_cbranch_execz .LBB0_360
	s_waitcnt lgkmcnt(0)
	v_add_f32_e32 v116, v114, v115
	s_lshl_b32 s30, s40, 2
	v_lshlrev_b64 v[114:115], 7, v[170:171]
	s_ashr_i32 s31, s30, 31
	v_lshl_add_u64 v[114:115], s[2:3], 0, v[114:115]
	v_lshl_add_u64 v[114:115], s[30:31], 2, v[114:115]
	s_lshl_b32 s0, s50, 2
	v_lshl_add_u64 v[114:115], v[114:115], 0, s[0:1]
	global_store_dword v[114:115], v116, off

.LBB0_580:
	ds_read_b128 v[150:153], v144
	ds_read_b128 v[154:157], v144 offset:1024
	ds_read_b128 v[158:161], v144 offset:2048
	ds_read_b128 v[162:165], v144 offset:3072
	s_mov_b32 m0, s1
	v_lshl_add_u64 v[198:199], v[138:139], 0, s[44:45]
	ds_read_b128 v[166:169], v145
	ds_read_b128 v[170:173], v145 offset:1024
	ds_read_b128 v[174:177], v145 offset:2048
	ds_read_b128 v[178:181], v145 offset:3072
	ds_read_b128 v[182:185], v145 offset:4096
	ds_read_b128 v[186:189], v145 offset:5120
	ds_read_b128 v[190:193], v145 offset:6144
	ds_read_b128 v[194:197], v145 offset:7168
	global_load_lds_dwordx4 v[198:199], off
	s_mov_b32 m0, s12
	v_lshl_add_u64 v[198:199], v[140:141], 0, s[44:45]
	global_load_lds_dwordx4 v[198:199], off
	s_waitcnt lgkmcnt(8)
	s_barrier
	s_waitcnt lgkmcnt(0)
	v_mfma_f32_16x16x32_bf16 v[28:31], v[150:153], v[166:169], v[28:31]
	s_add_i32 s81, s44, 0xfffc0080
	v_mfma_f32_16x16x32_bf16 v[24:27], v[158:161], v[166:169], v[24:27]
	s_cmp_eq_u32 s80, 4
	v_mfma_f32_16x16x32_bf16 v[20:23], v[150:153], v[174:177], v[20:23]
	s_cselect_b64 s[46:47], -1, 0
	v_mfma_f32_16x16x32_bf16 v[16:19], v[158:161], v[174:177], v[16:19]
	s_and_b64 s[82:83], s[46:47], exec
	v_mfma_f32_16x16x32_bf16 v[12:15], v[150:153], v[182:185], v[12:15]
	s_cselect_b32 s83, s39, s5
	v_mfma_f32_16x16x32_bf16 v[8:11], v[158:161], v[182:185], v[8:11]
	s_cselect_b32 s82, s38, s4
	v_mfma_f32_16x16x32_bf16 v[4:7], v[150:153], v[190:193], v[4:7]
	s_cselect_b32 s81, 0, s81
	v_mfma_f32_16x16x32_bf16 v[0:3], v[158:161], v[190:193], v[0:3]
	s_and_b64 s[46:47], s[42:43], s[46:47]
	v_mfma_f32_16x16x32_bf16 v[28:31], v[154:157], v[170:173], v[28:31]
	s_and_b64 s[46:47], s[46:47], exec
	v_mfma_f32_16x16x32_bf16 v[24:27], v[162:165], v[170:173], v[24:27]
	s_cselect_b32 s47, s41, s7
	v_mfma_f32_16x16x32_bf16 v[20:23], v[154:157], v[178:181], v[20:23]
	s_cselect_b32 s46, s40, s6
	v_mfma_f32_16x16x32_bf16 v[16:19], v[162:165], v[178:181], v[16:19]
	v_mfma_f32_16x16x32_bf16 v[12:15], v[154:157], v[186:189], v[12:15]
	v_mfma_f32_16x16x32_bf16 v[8:11], v[162:165], v[186:189], v[8:11]
	s_add_u32 s46, s46, s81
	v_mfma_f32_16x16x32_bf16 v[4:7], v[154:157], v[194:197], v[4:7]
	s_addc_u32 s47, s47, 0
	v_mfma_f32_16x16x32_bf16 v[0:3], v[162:165], v[194:197], v[0:3]
	s_barrier
	s_mov_b32 m0, s35
	v_lshl_add_u64 v[214:215], s[46:47], 0, v[130:131]
	ds_read_b128 v[198:201], v146
	ds_read_b128 v[202:205], v146 offset:1024
	ds_read_b128 v[206:209], v146 offset:2048
	ds_read_b128 v[210:213], v146 offset:3072
	global_load_lds_dwordx4 v[214:215], off
	s_mov_b32 m0, s73
	v_lshl_add_u64 v[216:217], s[46:47], 0, v[128:129]
	global_load_lds_dwordx4 v[216:217], off
	s_barrier
	s_waitcnt lgkmcnt(0)
	v_mfma_f32_16x16x32_bf16 v[92:95], v[198:201], v[166:169], v[92:95]
	v_mfma_f32_16x16x32_bf16 v[88:91], v[206:209], v[166:169], v[88:91]
	v_mfma_f32_16x16x32_bf16 v[76:79], v[198:201], v[174:177], v[76:79]
	v_mfma_f32_16x16x32_bf16 v[72:75], v[206:209], v[174:177], v[72:75]
	v_mfma_f32_16x16x32_bf16 v[60:63], v[198:201], v[182:185], v[60:63]
	v_mfma_f32_16x16x32_bf16 v[56:59], v[206:209], v[182:185], v[56:59]
	v_mfma_f32_16x16x32_bf16 v[44:47], v[198:201], v[190:193], v[44:47]
	v_mfma_f32_16x16x32_bf16 v[40:43], v[206:209], v[190:193], v[40:43]
	v_mfma_f32_16x16x32_bf16 v[92:95], v[202:205], v[170:173], v[92:95]
	v_mfma_f32_16x16x32_bf16 v[88:91], v[210:213], v[170:173], v[88:91]
	v_mfma_f32_16x16x32_bf16 v[76:79], v[202:205], v[178:181], v[76:79]
	v_mfma_f32_16x16x32_bf16 v[72:75], v[210:213], v[178:181], v[72:75]
	v_mfma_f32_16x16x32_bf16 v[60:63], v[202:205], v[186:189], v[60:63]
	v_mfma_f32_16x16x32_bf16 v[56:59], v[210:213], v[186:189], v[56:59]
	s_add_u32 s82, s82, s81
	v_mfma_f32_16x16x32_bf16 v[44:47], v[202:205], v[194:197], v[44:47]
	s_addc_u32 s83, s83, 0
	v_mfma_f32_16x16x32_bf16 v[40:43], v[210:213], v[194:197], v[40:43]
	s_mov_b32 m0, s52
	v_lshl_add_u64 v[218:219], s[82:83], 0, v[130:131]
	s_barrier
	ds_read_b128 v[166:169], v145 offset:16384
	ds_read_b128 v[170:173], v145 offset:17408
	ds_read_b128 v[174:177], v145 offset:18432
	ds_read_b128 v[178:181], v145 offset:19456
	ds_read_b128 v[182:185], v145 offset:20480
	ds_read_b128 v[186:189], v145 offset:21504
	ds_read_b128 v[190:193], v145 offset:22528
	ds_read_b128 v[194:197], v145 offset:23552
	global_load_lds_dwordx4 v[218:219], off
	s_mov_b32 m0, s55
	v_lshl_add_u64 v[222:223], s[82:83], 0, v[128:129]
	global_load_lds_dwordx4 v[222:223], off
	s_barrier
	s_waitcnt lgkmcnt(0)
	v_mfma_f32_16x16x32_bf16 v[84:87], v[150:153], v[166:169], v[84:87]
	v_mfma_f32_16x16x32_bf16 v[80:83], v[158:161], v[166:169], v[80:83]
	v_mfma_f32_16x16x32_bf16 v[68:71], v[150:153], v[174:177], v[68:71]
	v_mfma_f32_16x16x32_bf16 v[64:67], v[158:161], v[174:177], v[64:67]
	v_mfma_f32_16x16x32_bf16 v[52:55], v[150:153], v[182:185], v[52:55]
	v_mfma_f32_16x16x32_bf16 v[48:51], v[158:161], v[182:185], v[48:51]
	v_mfma_f32_16x16x32_bf16 v[36:39], v[150:153], v[190:193], v[36:39]
	v_mfma_f32_16x16x32_bf16 v[32:35], v[158:161], v[190:193], v[32:35]
	v_mfma_f32_16x16x32_bf16 v[84:87], v[154:157], v[170:173], v[84:87]
	v_mfma_f32_16x16x32_bf16 v[80:83], v[162:165], v[170:173], v[80:83]
	v_mfma_f32_16x16x32_bf16 v[68:71], v[154:157], v[178:181], v[68:71]
	v_mfma_f32_16x16x32_bf16 v[64:67], v[162:165], v[178:181], v[64:67]
	v_mfma_f32_16x16x32_bf16 v[52:55], v[154:157], v[186:189], v[52:55]
	v_mfma_f32_16x16x32_bf16 v[48:51], v[162:165], v[186:189], v[48:51]
	s_add_u32 s84, s46, 0x40000
	v_mfma_f32_16x16x32_bf16 v[36:39], v[154:157], v[194:197], v[36:39]
	s_addc_u32 s85, s47, 0
	v_mfma_f32_16x16x32_bf16 v[32:35], v[162:165], v[194:197], v[32:35]
	s_barrier
	s_mov_b32 m0, s74
	v_lshl_add_u64 v[150:151], s[84:85], 0, v[130:131]
	global_load_lds_dwordx4 v[150:151], off
	s_mov_b32 m0, s75
	v_lshl_add_u64 v[150:151], s[84:85], 0, v[128:129]
	global_load_lds_dwordx4 v[150:151], off
	s_waitcnt vmcnt(6)
	s_barrier
	v_mfma_f32_16x16x32_bf16 v[124:127], v[198:201], v[166:169], v[124:127]
	v_mfma_f32_16x16x32_bf16 v[120:123], v[206:209], v[166:169], v[120:123]
	v_mfma_f32_16x16x32_bf16 v[116:119], v[198:201], v[174:177], v[116:119]
	v_mfma_f32_16x16x32_bf16 v[112:115], v[206:209], v[174:177], v[112:115]
	v_mfma_f32_16x16x32_bf16 v[108:111], v[198:201], v[182:185], v[108:111]
	v_mfma_f32_16x16x32_bf16 v[104:107], v[206:209], v[182:185], v[104:107]
	v_mfma_f32_16x16x32_bf16 v[100:103], v[198:201], v[190:193], v[100:103]
	v_mfma_f32_16x16x32_bf16 v[96:99], v[206:209], v[190:193], v[96:99]
	v_mfma_f32_16x16x32_bf16 v[124:127], v[202:205], v[170:173], v[124:127]
	v_mfma_f32_16x16x32_bf16 v[120:123], v[210:213], v[170:173], v[120:123]
	v_mfma_f32_16x16x32_bf16 v[116:119], v[202:205], v[178:181], v[116:119]
	v_mfma_f32_16x16x32_bf16 v[112:115], v[210:213], v[178:181], v[112:115]
	v_mfma_f32_16x16x32_bf16 v[108:111], v[202:205], v[186:189], v[108:111]
	v_mfma_f32_16x16x32_bf16 v[104:107], v[210:213], v[186:189], v[104:107]
	s_add_u32 s82, s82, 0x40000
	v_mfma_f32_16x16x32_bf16 v[100:103], v[202:205], v[194:197], v[100:103]
	s_addc_u32 s83, s83, 0
	v_mfma_f32_16x16x32_bf16 v[96:99], v[210:213], v[194:197], v[96:99]
	s_barrier
	ds_read_b128 v[150:153], v147
	ds_read_b128 v[154:157], v147 offset:1024
	ds_read_b128 v[158:161], v147 offset:2048
	ds_read_b128 v[162:165], v147 offset:3072
	s_mov_b32 m0, s56
	v_lshl_add_u64 v[198:199], s[82:83], 0, v[130:131]
	ds_read_b128 v[166:169], v145 offset:32768
	ds_read_b128 v[170:173], v145 offset:33792
	ds_read_b128 v[174:177], v145 offset:34816
	ds_read_b128 v[178:181], v145 offset:35840
	ds_read_b128 v[182:185], v145 offset:36864
	ds_read_b128 v[186:189], v145 offset:37888
	ds_read_b128 v[190:193], v145 offset:38912
	ds_read_b128 v[194:197], v145 offset:39936
	global_load_lds_dwordx4 v[198:199], off
	s_mov_b32 m0, s57
	v_lshl_add_u64 v[198:199], s[82:83], 0, v[128:129]
	global_load_lds_dwordx4 v[198:199], off
	s_waitcnt lgkmcnt(8)
	s_barrier
	s_waitcnt lgkmcnt(0)
	v_mfma_f32_16x16x32_bf16 v[28:31], v[150:153], v[166:169], v[28:31]
	v_mfma_f32_16x16x32_bf16 v[24:27], v[158:161], v[166:169], v[24:27]
	v_mfma_f32_16x16x32_bf16 v[20:23], v[150:153], v[174:177], v[20:23]
	v_mfma_f32_16x16x32_bf16 v[16:19], v[158:161], v[174:177], v[16:19]
	v_mfma_f32_16x16x32_bf16 v[12:15], v[150:153], v[182:185], v[12:15]
	v_mfma_f32_16x16x32_bf16 v[8:11], v[158:161], v[182:185], v[8:11]
	v_mfma_f32_16x16x32_bf16 v[4:7], v[150:153], v[190:193], v[4:7]
	v_mfma_f32_16x16x32_bf16 v[0:3], v[158:161], v[190:193], v[0:3]
	v_mfma_f32_16x16x32_bf16 v[28:31], v[154:157], v[170:173], v[28:31]
	v_mfma_f32_16x16x32_bf16 v[24:27], v[162:165], v[170:173], v[24:27]
	v_mfma_f32_16x16x32_bf16 v[20:23], v[154:157], v[178:181], v[20:23]
	v_mfma_f32_16x16x32_bf16 v[16:19], v[162:165], v[178:181], v[16:19]
	v_mfma_f32_16x16x32_bf16 v[12:15], v[154:157], v[186:189], v[12:15]
	v_mfma_f32_16x16x32_bf16 v[8:11], v[162:165], v[186:189], v[8:11]
	v_mfma_f32_16x16x32_bf16 v[4:7], v[154:157], v[194:197], v[4:7]
	v_mfma_f32_16x16x32_bf16 v[0:3], v[162:165], v[194:197], v[0:3]
	s_barrier
	s_mov_b32 m0, s76
	v_lshl_add_u64 v[214:215], v[214:215], 0, s[2:3]
	ds_read_b128 v[198:201], v148
	ds_read_b128 v[202:205], v148 offset:1024
	ds_read_b128 v[206:209], v148 offset:2048
	ds_read_b128 v[210:213], v148 offset:3072
	global_load_lds_dwordx4 v[214:215], off
	s_mov_b32 m0, s77
	v_lshl_add_u64 v[214:215], v[216:217], 0, s[2:3]
	global_load_lds_dwordx4 v[214:215], off
	s_barrier
	s_waitcnt lgkmcnt(0)
	v_mfma_f32_16x16x32_bf16 v[92:95], v[198:201], v[166:169], v[92:95]
	v_mfma_f32_16x16x32_bf16 v[88:91], v[206:209], v[166:169], v[88:91]
	v_mfma_f32_16x16x32_bf16 v[76:79], v[198:201], v[174:177], v[76:79]
	v_mfma_f32_16x16x32_bf16 v[72:75], v[206:209], v[174:177], v[72:75]
	v_mfma_f32_16x16x32_bf16 v[60:63], v[198:201], v[182:185], v[60:63]
	v_mfma_f32_16x16x32_bf16 v[56:59], v[206:209], v[182:185], v[56:59]
	v_mfma_f32_16x16x32_bf16 v[44:47], v[198:201], v[190:193], v[44:47]
	v_mfma_f32_16x16x32_bf16 v[40:43], v[206:209], v[190:193], v[40:43]
	v_mfma_f32_16x16x32_bf16 v[92:95], v[202:205], v[170:173], v[92:95]
	v_mfma_f32_16x16x32_bf16 v[88:91], v[210:213], v[170:173], v[88:91]
	v_mfma_f32_16x16x32_bf16 v[76:79], v[202:205], v[178:181], v[76:79]
	v_mfma_f32_16x16x32_bf16 v[72:75], v[210:213], v[178:181], v[72:75]
	v_mfma_f32_16x16x32_bf16 v[60:63], v[202:205], v[186:189], v[60:63]
	v_mfma_f32_16x16x32_bf16 v[56:59], v[210:213], v[186:189], v[56:59]
	v_mfma_f32_16x16x32_bf16 v[44:47], v[202:205], v[194:197], v[44:47]
	v_mfma_f32_16x16x32_bf16 v[40:43], v[210:213], v[194:197], v[40:43]
	s_mov_b32 m0, s61
	v_lshl_add_u64 v[214:215], v[218:219], 0, s[2:3]
	s_barrier
	ds_read_b128 v[166:169], v145 offset:49152
	ds_read_b128 v[170:173], v145 offset:50176
	ds_read_b128 v[174:177], v145 offset:51200
	ds_read_b128 v[178:181], v145 offset:52224
	ds_read_b128 v[182:185], v145 offset:53248
	ds_read_b128 v[186:189], v145 offset:54272
	ds_read_b128 v[190:193], v145 offset:55296
	ds_read_b128 v[194:197], v145 offset:56320
	global_load_lds_dwordx4 v[214:215], off
	s_mov_b32 m0, s62
	v_lshl_add_u64 v[214:215], v[222:223], 0, s[2:3]
	global_load_lds_dwordx4 v[214:215], off
	s_barrier
;     ...
;         G_PAIR(0, 1);
; #pragma unroll 1
;         for (int t = 2; t < nt; t += 2) G_PAIR(t, 0);
;         p.epi(acc, cur, wr, wc, fr, fq);
;         if (!has_next) break;
;     __device__ __forceinline__ void epi(const f32x4 (&acc)[2][2][4][2], const Unit& u, int wr, int wc, int fr, int fq) const {
;         const int row0 = u.pm * 256 + wr * 64 + fr, col0 = wc * 32 + 4 * fq;
; #pragma unroll
;         for (int ai = 0; ai < 2; ++ai)
; #pragma unroll
;             for (int m = 0; m < 4; ++m) {
;                 float* rowp = Send + (size_t)u.pn * NG * NCH * 256 + ((size_t)u.g * NCH + row0 + ai * 128 + m * 16) * 256 + col0;
; #pragma unroll
;                 for (int bj = 0; bj < 2; ++bj)
; #pragma unroll
;                     for (int n = 0; n < 2; ++n) *(f32x4*)(rowp + bj * 128 + n * 16) = acc[ai][bj][m][n];
;             }
	s_waitcnt lgkmcnt(0)
	v_mfma_f32_16x16x32_bf16 v[84:87], v[150:153], v[166:169], v[84:87]
	v_mfma_f32_16x16x32_bf16 v[80:83], v[158:161], v[166:169], v[80:83]
	v_mfma_f32_16x16x32_bf16 v[68:71], v[150:153], v[174:177], v[68:71]
	v_mfma_f32_16x16x32_bf16 v[64:67], v[158:161], v[174:177], v[64:67]
	v_mfma_f32_16x16x32_bf16 v[52:55], v[150:153], v[182:185], v[52:55]
	v_mfma_f32_16x16x32_bf16 v[48:51], v[158:161], v[182:185], v[48:51]
	v_mfma_f32_16x16x32_bf16 v[36:39], v[150:153], v[190:193], v[36:39]
	v_mfma_f32_16x16x32_bf16 v[32:35], v[158:161], v[190:193], v[32:35]
	v_mfma_f32_16x16x32_bf16 v[84:87], v[154:157], v[170:173], v[84:87]
	v_mfma_f32_16x16x32_bf16 v[80:83], v[162:165], v[170:173], v[80:83]
	v_mfma_f32_16x16x32_bf16 v[68:71], v[154:157], v[178:181], v[68:71]
	v_mfma_f32_16x16x32_bf16 v[64:67], v[162:165], v[178:181], v[64:67]
	v_mfma_f32_16x16x32_bf16 v[52:55], v[154:157], v[186:189], v[52:55]
	v_mfma_f32_16x16x32_bf16 v[48:51], v[162:165], v[186:189], v[48:51]
	s_add_u32 s46, s46, 0x40080
	v_mfma_f32_16x16x32_bf16 v[36:39], v[154:157], v[194:197], v[36:39]
	s_addc_u32 s47, s47, 0
	v_mfma_f32_16x16x32_bf16 v[32:35], v[162:165], v[194:197], v[32:35]
	s_barrier
	s_mov_b32 m0, s78
	v_lshl_add_u64 v[150:151], s[46:47], 0, v[130:131]
	global_load_lds_dwordx4 v[150:151], off
	s_mov_b32 m0, s79
	v_lshl_add_u64 v[150:151], s[46:47], 0, v[128:129]
	global_load_lds_dwordx4 v[150:151], off
	s_waitcnt vmcnt(6)
	s_barrier
	v_mfma_f32_16x16x32_bf16 v[124:127], v[198:201], v[166:169], v[124:127]
	v_mfma_f32_16x16x32_bf16 v[120:123], v[206:209], v[166:169], v[120:123]
	v_mfma_f32_16x16x32_bf16 v[116:119], v[198:201], v[174:177], v[116:119]
	v_mfma_f32_16x16x32_bf16 v[112:115], v[206:209], v[174:177], v[112:115]
	v_mfma_f32_16x16x32_bf16 v[108:111], v[198:201], v[182:185], v[108:111]
	v_mfma_f32_16x16x32_bf16 v[104:107], v[206:209], v[182:185], v[104:107]
	v_mfma_f32_16x16x32_bf16 v[100:103], v[198:201], v[190:193], v[100:103]
	v_mfma_f32_16x16x32_bf16 v[96:99], v[206:209], v[190:193], v[96:99]
	v_mfma_f32_16x16x32_bf16 v[124:127], v[202:205], v[170:173], v[124:127]
	v_mfma_f32_16x16x32_bf16 v[120:123], v[210:213], v[170:173], v[120:123]
	v_mfma_f32_16x16x32_bf16 v[116:119], v[202:205], v[178:181], v[116:119]
	v_mfma_f32_16x16x32_bf16 v[112:115], v[210:213], v[178:181], v[112:115]
	s_add_i32 s80, s80, 2
	v_mfma_f32_16x16x32_bf16 v[108:111], v[202:205], v[186:189], v[108:111]
	s_add_u32 s44, s44, 0x100
	v_mfma_f32_16x16x32_bf16 v[104:107], v[210:213], v[186:189], v[104:107]
	s_addc_u32 s45, s45, 0
	v_mfma_f32_16x16x32_bf16 v[100:103], v[202:205], v[194:197], v[100:103]
	s_cmp_gt_u32 s80, 5
	v_mfma_f32_16x16x32_bf16 v[96:99], v[210:213], v[194:197], v[96:99]
	s_cbranch_scc0 .Lrot_580
	s_barrier
	s_lshl_b32 s1, s53, 25
	s_add_u32 s4, s59, s1
	s_addc_u32 s5, s60, 0
	s_ashr_i32 s1, s0, 31
	v_lshl_add_u32 v138, s54, 8, v142
	s_lshl_b64 s[0:1], s[0:1], 19
	v_ashrrev_i32_e32 v139, 31, v138
	s_add_u32 s0, s4, s0
	v_lshlrev_b64 v[138:139], 10, v[138:139]
	s_addc_u32 s1, s5, s1
	v_lshl_add_u64 v[138:139], s[0:1], 0, v[138:139]
	v_lshl_add_u64 v[138:139], v[138:139], 0, v[132:133]
	global_store_dwordx4 v[138:139], v[28:31], off
	global_store_dwordx4 v[138:139], v[24:27], off offset:64
	global_store_dwordx4 v[138:139], v[92:95], off offset:512
	global_store_dwordx4 v[138:139], v[88:91], off offset:576
	v_add_co_u32_e32 v26, vcc, s58, v138
	v_lshl_add_u64 v[24:25], v[138:139], 0, s[18:19]
	s_nop 0
	v_addc_co_u32_e32 v27, vcc, 0, v139, vcc
	global_store_dwordx4 v[26:27], v[20:23], off
	global_store_dwordx4 v[24:25], v[16:19], off offset:64
	global_store_dwordx4 v[24:25], v[76:79], off offset:512
	global_store_dwordx4 v[24:25], v[72:75], off offset:576
	v_add_co_u32_e32 v18, vcc, s63, v138
	v_lshl_add_u64 v[16:17], v[138:139], 0, s[20:21]
	s_nop 0
	v_addc_co_u32_e32 v19, vcc, 0, v139, vcc
	global_store_dwordx4 v[18:19], v[12:15], off
	global_store_dwordx4 v[16:17], v[8:11], off offset:64
	global_store_dwordx4 v[16:17], v[60:63], off offset:512
	global_store_dwordx4 v[16:17], v[56:59], off offset:576
	v_add_co_u32_e32 v10, vcc, s65, v138
	v_lshl_add_u64 v[8:9], v[138:139], 0, s[22:23]
	s_nop 0
	v_addc_co_u32_e32 v11, vcc, 0, v139, vcc
	global_store_dwordx4 v[10:11], v[4:7], off
	global_store_dwordx4 v[8:9], v[0:3], off offset:64
	global_store_dwordx4 v[8:9], v[44:47], off offset:512
	global_store_dwordx4 v[8:9], v[40:43], off offset:576
	v_add_co_u32_e32 v2, vcc, s67, v138
	v_lshl_add_u64 v[0:1], v[138:139], 0, s[24:25]
	s_nop 0
	v_addc_co_u32_e32 v3, vcc, 0, v139, vcc
	global_store_dwordx4 v[2:3], v[84:87], off
	global_store_dwordx4 v[0:1], v[80:83], off offset:64
	global_store_dwordx4 v[0:1], v[124:127], off offset:512
	global_store_dwordx4 v[0:1], v[120:123], off offset:576
	v_add_co_u32_e32 v2, vcc, s68, v138
	v_lshl_add_u64 v[0:1], v[138:139], 0, s[26:27]
	s_nop 0
	v_addc_co_u32_e32 v3, vcc, 0, v139, vcc
	global_store_dwordx4 v[2:3], v[68:71], off
	global_store_dwordx4 v[0:1], v[64:67], off offset:64
	global_store_dwordx4 v[0:1], v[116:119], off offset:512
	global_store_dwordx4 v[0:1], v[112:115], off offset:576
	v_add_co_u32_e32 v2, vcc, s69, v138
	v_lshl_add_u64 v[0:1], v[138:139], 0, s[28:29]
	s_nop 0
	v_addc_co_u32_e32 v3, vcc, 0, v139, vcc
	global_store_dwordx4 v[2:3], v[52:55], off
	global_store_dwordx4 v[0:1], v[48:51], off offset:64
	global_store_dwordx4 v[0:1], v[108:111], off offset:512
	global_store_dwordx4 v[0:1], v[104:107], off offset:576
	v_add_co_u32_e32 v2, vcc, 0x2c000, v138
	s_mov_b32 s54, s72
	s_nop 0
	v_addc_co_u32_e32 v3, vcc, 0, v139, vcc
	v_readlane_b32 s72, v254, 3
	v_readlane_b32 s74, v254, 5
	s_and_b64 vcc, exec, s[36:37]
	s_mov_b32 s0, s34
	s_mov_b32 s53, s71
	s_mov_b64 s[6:7], s[40:41]
	s_mov_b64 s[4:5], s[38:39]
	v_readlane_b32 s73, v254, 4
	v_readlane_b32 s75, v254, 6
	v_lshl_add_u64 v[0:1], v[138:139], 0, s[30:31]
	global_store_dwordx4 v[2:3], v[36:39], off
	global_store_dwordx4 v[0:1], v[32:35], off offset:64
	global_store_dwordx4 v[0:1], v[100:103], off offset:512
	global_store_dwordx4 v[0:1], v[96:99], off offset:576
	s_cbranch_vccz .LBB0_575
	s_waitcnt vmcnt(0)
	s_cmpk_gt_u32 s48, 0xff
	s_cbranch_scc1 .LBB0_584
	s_barrier

.LBB0_920:
	ds_read_b128 v[132:135], v172
	ds_read_b128 v[136:139], v172 offset:1024
	ds_read_b128 v[152:155], v172 offset:2048
	ds_read_b128 v[156:159], v172 offset:3072
	s_mov_b32 m0, s48
	v_lshl_add_u64 v[168:169], v[120:121], 0, s[30:31]
	ds_read_b128 v[160:163], v173
	ds_read_b128 v[164:167], v173 offset:1024
	ds_read_b128 v[178:181], v173 offset:2048
	ds_read_b128 v[182:185], v173 offset:3072
	ds_read_b128 v[186:189], v173 offset:4096
	ds_read_b128 v[190:193], v173 offset:5120
	ds_read_b128 v[194:197], v173 offset:6144
	ds_read_b128 v[198:201], v173 offset:7168
	global_load_lds_dwordx4 v[168:169], off
	s_mov_b32 m0, s49
	v_lshl_add_u64 v[168:169], v[122:123], 0, s[30:31]
	global_load_lds_dwordx4 v[168:169], off
	s_waitcnt lgkmcnt(8)
	s_barrier
	s_waitcnt lgkmcnt(0)
	v_mfma_f32_16x16x32_bf16 v[116:119], v[132:135], v[160:163], v[116:119]
	s_add_i32 s19, s30, 0xfffc0080
	v_mfma_f32_16x16x32_bf16 v[112:115], v[152:155], v[160:163], v[112:115]
	s_cmp_eq_u32 s17, 12
	v_mfma_f32_16x16x32_bf16 v[100:103], v[132:135], v[178:181], v[100:103]
	s_cselect_b64 s[34:35], -1, 0
	v_mfma_f32_16x16x32_bf16 v[96:99], v[152:155], v[178:181], v[96:99]
	s_and_b64 s[60:61], s[34:35], exec
	v_mfma_f32_16x16x32_bf16 v[84:87], v[132:135], v[186:189], v[84:87]
	s_cselect_b32 s19, 0, s19
	v_mfma_f32_16x16x32_bf16 v[80:83], v[152:155], v[186:189], v[80:83]
	s_and_b64 s[34:35], s[28:29], s[34:35]
	v_mfma_f32_16x16x32_bf16 v[68:71], v[132:135], v[194:197], v[68:71]
	s_and_b64 s[34:35], s[34:35], exec
	v_mfma_f32_16x16x32_bf16 v[64:67], v[152:155], v[194:197], v[64:67]
	s_cselect_b32 s61, s21, s25
	v_mfma_f32_16x16x32_bf16 v[116:119], v[136:139], v[164:167], v[116:119]
	s_cselect_b32 s60, s20, s24
	v_mfma_f32_16x16x32_bf16 v[112:115], v[156:159], v[164:167], v[112:115]
	s_cselect_b32 s35, s23, s27
	v_mfma_f32_16x16x32_bf16 v[100:103], v[136:139], v[182:185], v[100:103]
	s_cselect_b32 s34, s22, s26
	v_mfma_f32_16x16x32_bf16 v[96:99], v[156:159], v[182:185], v[96:99]
	v_mfma_f32_16x16x32_bf16 v[84:87], v[136:139], v[190:193], v[84:87]
	v_mfma_f32_16x16x32_bf16 v[80:83], v[156:159], v[190:193], v[80:83]
	s_add_u32 s34, s34, s19
	v_mfma_f32_16x16x32_bf16 v[68:71], v[136:139], v[198:201], v[68:71]
	s_addc_u32 s35, s35, 0
	v_mfma_f32_16x16x32_bf16 v[64:67], v[156:159], v[198:201], v[64:67]
	s_barrier
	s_mov_b32 m0, s50
	v_lshl_add_u64 v[168:169], s[34:35], 0, v[144:145]
	ds_read_b128 v[202:205], v174
	ds_read_b128 v[206:209], v174 offset:1024
	ds_read_b128 v[210:213], v174 offset:2048
	ds_read_b128 v[214:217], v174 offset:3072
	global_load_lds_dwordx4 v[168:169], off
	s_mov_b32 m0, s51
	v_lshl_add_u64 v[218:219], s[34:35], 0, v[140:141]
	global_load_lds_dwordx4 v[218:219], off
	s_barrier
	s_waitcnt lgkmcnt(0)
	v_mfma_f32_16x16x32_bf16 v[128:131], v[202:205], v[160:163], v[128:131]
	v_mfma_f32_16x16x32_bf16 v[124:127], v[210:213], v[160:163], v[124:127]
	v_mfma_f32_16x16x32_bf16 v[108:111], v[202:205], v[178:181], v[108:111]
	v_mfma_f32_16x16x32_bf16 v[104:107], v[210:213], v[178:181], v[104:107]
	v_mfma_f32_16x16x32_bf16 v[92:95], v[202:205], v[186:189], v[92:95]
	v_mfma_f32_16x16x32_bf16 v[88:91], v[210:213], v[186:189], v[88:91]
	v_mfma_f32_16x16x32_bf16 v[76:79], v[202:205], v[194:197], v[76:79]
	v_mfma_f32_16x16x32_bf16 v[72:75], v[210:213], v[194:197], v[72:75]
	v_mfma_f32_16x16x32_bf16 v[128:131], v[206:209], v[164:167], v[128:131]
	v_mfma_f32_16x16x32_bf16 v[124:127], v[214:217], v[164:167], v[124:127]
	v_mfma_f32_16x16x32_bf16 v[108:111], v[206:209], v[182:185], v[108:111]
	v_mfma_f32_16x16x32_bf16 v[104:107], v[214:217], v[182:185], v[104:107]
	v_mfma_f32_16x16x32_bf16 v[92:95], v[206:209], v[190:193], v[92:95]
	v_mfma_f32_16x16x32_bf16 v[88:91], v[214:217], v[190:193], v[88:91]
	s_add_u32 s60, s60, s19
	v_mfma_f32_16x16x32_bf16 v[76:79], v[206:209], v[198:201], v[76:79]
	s_addc_u32 s61, s61, 0
	v_mfma_f32_16x16x32_bf16 v[72:75], v[214:217], v[198:201], v[72:75]
	s_mov_b32 m0, s41
	v_lshl_add_u64 v[222:223], s[60:61], 0, v[146:147]
	s_barrier
	ds_read_b128 v[160:163], v173 offset:16384
	ds_read_b128 v[164:167], v173 offset:17408
	ds_read_b128 v[178:181], v173 offset:18432
	ds_read_b128 v[182:185], v173 offset:19456
	ds_read_b128 v[186:189], v173 offset:20480
	ds_read_b128 v[190:193], v173 offset:21504
	ds_read_b128 v[194:197], v173 offset:22528
	ds_read_b128 v[198:201], v173 offset:23552
	global_load_lds_dwordx4 v[222:223], off
	s_mov_b32 m0, s42
	v_lshl_add_u64 v[224:225], s[60:61], 0, v[142:143]
	global_load_lds_dwordx4 v[224:225], off
	s_barrier
	s_waitcnt lgkmcnt(0)
	v_mfma_f32_16x16x32_bf16 v[52:55], v[132:135], v[160:163], v[52:55]
	v_mfma_f32_16x16x32_bf16 v[48:51], v[152:155], v[160:163], v[48:51]
	v_mfma_f32_16x16x32_bf16 v[36:39], v[132:135], v[178:181], v[36:39]
	v_mfma_f32_16x16x32_bf16 v[32:35], v[152:155], v[178:181], v[32:35]
	v_mfma_f32_16x16x32_bf16 v[20:23], v[132:135], v[186:189], v[20:23]
	v_mfma_f32_16x16x32_bf16 v[16:19], v[152:155], v[186:189], v[16:19]
	v_mfma_f32_16x16x32_bf16 v[4:7], v[132:135], v[194:197], v[4:7]
	v_mfma_f32_16x16x32_bf16 v[0:3], v[152:155], v[194:197], v[0:3]
	v_mfma_f32_16x16x32_bf16 v[52:55], v[136:139], v[164:167], v[52:55]
	v_mfma_f32_16x16x32_bf16 v[48:51], v[156:159], v[164:167], v[48:51]
	v_mfma_f32_16x16x32_bf16 v[36:39], v[136:139], v[182:185], v[36:39]
	v_mfma_f32_16x16x32_bf16 v[32:35], v[156:159], v[182:185], v[32:35]
	v_mfma_f32_16x16x32_bf16 v[20:23], v[136:139], v[190:193], v[20:23]
	v_mfma_f32_16x16x32_bf16 v[16:19], v[156:159], v[190:193], v[16:19]
	s_add_u32 s62, s34, 0x40000
	v_mfma_f32_16x16x32_bf16 v[4:7], v[136:139], v[198:201], v[4:7]
	s_addc_u32 s63, s35, 0
	v_mfma_f32_16x16x32_bf16 v[0:3], v[156:159], v[198:201], v[0:3]
	s_barrier
	s_mov_b32 m0, s52
	v_lshl_add_u64 v[132:133], s[62:63], 0, v[144:145]
	global_load_lds_dwordx4 v[132:133], off
	s_mov_b32 m0, s53
	v_lshl_add_u64 v[132:133], s[62:63], 0, v[140:141]
	global_load_lds_dwordx4 v[132:133], off
	s_waitcnt vmcnt(6)
	s_barrier
	v_mfma_f32_16x16x32_bf16 v[60:63], v[202:205], v[160:163], v[60:63]
	v_mfma_f32_16x16x32_bf16 v[56:59], v[210:213], v[160:163], v[56:59]
	v_mfma_f32_16x16x32_bf16 v[44:47], v[202:205], v[178:181], v[44:47]
	v_mfma_f32_16x16x32_bf16 v[40:43], v[210:213], v[178:181], v[40:43]
	v_mfma_f32_16x16x32_bf16 v[28:31], v[202:205], v[186:189], v[28:31]
	v_mfma_f32_16x16x32_bf16 v[24:27], v[210:213], v[186:189], v[24:27]
	v_mfma_f32_16x16x32_bf16 v[12:15], v[202:205], v[194:197], v[12:15]
	v_mfma_f32_16x16x32_bf16 v[8:11], v[210:213], v[194:197], v[8:11]
	v_mfma_f32_16x16x32_bf16 v[60:63], v[206:209], v[164:167], v[60:63]
	v_mfma_f32_16x16x32_bf16 v[56:59], v[214:217], v[164:167], v[56:59]
	v_mfma_f32_16x16x32_bf16 v[44:47], v[206:209], v[182:185], v[44:47]
	v_mfma_f32_16x16x32_bf16 v[40:43], v[214:217], v[182:185], v[40:43]
	v_mfma_f32_16x16x32_bf16 v[28:31], v[206:209], v[190:193], v[28:31]
	v_mfma_f32_16x16x32_bf16 v[24:27], v[214:217], v[190:193], v[24:27]
	s_add_u32 s60, s60, 0x40000
	v_mfma_f32_16x16x32_bf16 v[12:15], v[206:209], v[198:201], v[12:15]
	s_addc_u32 s61, s61, 0
	v_mfma_f32_16x16x32_bf16 v[8:11], v[214:217], v[198:201], v[8:11]
	s_barrier
	ds_read_b128 v[132:135], v176
	ds_read_b128 v[136:139], v176 offset:1024
	ds_read_b128 v[152:155], v176 offset:2048
	ds_read_b128 v[156:159], v176 offset:3072
	s_mov_b32 m0, s43
	v_lshl_add_u64 v[202:203], s[60:61], 0, v[146:147]
	ds_read_b128 v[160:163], v173 offset:32768
	ds_read_b128 v[164:167], v173 offset:33792
	ds_read_b128 v[178:181], v173 offset:34816
	ds_read_b128 v[182:185], v173 offset:35840
	ds_read_b128 v[186:189], v173 offset:36864
	ds_read_b128 v[190:193], v173 offset:37888
	ds_read_b128 v[194:197], v173 offset:38912
	ds_read_b128 v[198:201], v173 offset:39936
	global_load_lds_dwordx4 v[202:203], off
	s_mov_b32 m0, s44
	v_lshl_add_u64 v[202:203], s[60:61], 0, v[142:143]
	global_load_lds_dwordx4 v[202:203], off
	s_waitcnt lgkmcnt(8)
	s_barrier
	s_waitcnt lgkmcnt(0)
	v_mfma_f32_16x16x32_bf16 v[116:119], v[132:135], v[160:163], v[116:119]
	v_mfma_f32_16x16x32_bf16 v[112:115], v[152:155], v[160:163], v[112:115]
	v_mfma_f32_16x16x32_bf16 v[100:103], v[132:135], v[178:181], v[100:103]
	v_mfma_f32_16x16x32_bf16 v[96:99], v[152:155], v[178:181], v[96:99]
	v_mfma_f32_16x16x32_bf16 v[84:87], v[132:135], v[186:189], v[84:87]
	v_mfma_f32_16x16x32_bf16 v[80:83], v[152:155], v[186:189], v[80:83]
	v_mfma_f32_16x16x32_bf16 v[68:71], v[132:135], v[194:197], v[68:71]
	v_mfma_f32_16x16x32_bf16 v[64:67], v[152:155], v[194:197], v[64:67]
	v_mfma_f32_16x16x32_bf16 v[116:119], v[136:139], v[164:167], v[116:119]
	v_mfma_f32_16x16x32_bf16 v[112:115], v[156:159], v[164:167], v[112:115]
	v_mfma_f32_16x16x32_bf16 v[100:103], v[136:139], v[182:185], v[100:103]
	v_mfma_f32_16x16x32_bf16 v[96:99], v[156:159], v[182:185], v[96:99]
	v_mfma_f32_16x16x32_bf16 v[84:87], v[136:139], v[190:193], v[84:87]
	v_mfma_f32_16x16x32_bf16 v[80:83], v[156:159], v[190:193], v[80:83]
	v_mfma_f32_16x16x32_bf16 v[68:71], v[136:139], v[198:201], v[68:71]
	v_mfma_f32_16x16x32_bf16 v[64:67], v[156:159], v[198:201], v[64:67]
	s_barrier
	s_mov_b32 m0, s54
	v_lshl_add_u64 v[168:169], v[168:169], 0, s[6:7]
	ds_read_b128 v[202:205], v177
	ds_read_b128 v[206:209], v177 offset:1024
	ds_read_b128 v[210:213], v177 offset:2048
	ds_read_b128 v[214:217], v177 offset:3072
	global_load_lds_dwordx4 v[168:169], off
	s_mov_b32 m0, s55
	v_lshl_add_u64 v[168:169], v[218:219], 0, s[6:7]
	global_load_lds_dwordx4 v[168:169], off
	s_barrier
	s_waitcnt lgkmcnt(0)
	v_mfma_f32_16x16x32_bf16 v[128:131], v[202:205], v[160:163], v[128:131]
	v_mfma_f32_16x16x32_bf16 v[124:127], v[210:213], v[160:163], v[124:127]
	v_mfma_f32_16x16x32_bf16 v[108:111], v[202:205], v[178:181], v[108:111]
	v_mfma_f32_16x16x32_bf16 v[104:107], v[210:213], v[178:181], v[104:107]
	v_mfma_f32_16x16x32_bf16 v[92:95], v[202:205], v[186:189], v[92:95]
	v_mfma_f32_16x16x32_bf16 v[88:91], v[210:213], v[186:189], v[88:91]
	v_mfma_f32_16x16x32_bf16 v[76:79], v[202:205], v[194:197], v[76:79]
	v_mfma_f32_16x16x32_bf16 v[72:75], v[210:213], v[194:197], v[72:75]
	v_mfma_f32_16x16x32_bf16 v[128:131], v[206:209], v[164:167], v[128:131]
	v_mfma_f32_16x16x32_bf16 v[124:127], v[214:217], v[164:167], v[124:127]
	v_mfma_f32_16x16x32_bf16 v[108:111], v[206:209], v[182:185], v[108:111]
	v_mfma_f32_16x16x32_bf16 v[104:107], v[214:217], v[182:185], v[104:107]
	v_mfma_f32_16x16x32_bf16 v[92:95], v[206:209], v[190:193], v[92:95]
	v_mfma_f32_16x16x32_bf16 v[88:91], v[214:217], v[190:193], v[88:91]
	v_mfma_f32_16x16x32_bf16 v[76:79], v[206:209], v[198:201], v[76:79]
	v_mfma_f32_16x16x32_bf16 v[72:75], v[214:217], v[198:201], v[72:75]
	s_mov_b32 m0, s46
	v_lshl_add_u64 v[168:169], v[222:223], 0, s[6:7]
	s_barrier
	ds_read_b128 v[160:163], v173 offset:49152
	ds_read_b128 v[164:167], v173 offset:50176
	ds_read_b128 v[178:181], v173 offset:51200
	ds_read_b128 v[182:185], v173 offset:52224
	ds_read_b128 v[186:189], v173 offset:53248
	ds_read_b128 v[190:193], v173 offset:54272
	ds_read_b128 v[194:197], v173 offset:55296
	ds_read_b128 v[198:201], v173 offset:56320
	global_load_lds_dwordx4 v[168:169], off
	s_mov_b32 m0, s47
	v_lshl_add_u64 v[168:169], v[224:225], 0, s[6:7]
	global_load_lds_dwordx4 v[168:169], off
	s_barrier
;     ...
;         G_PAIR(0, 1);
; #pragma unroll 1
;         for (int t = 2; t < nt; t += 2) G_PAIR(t, 0);
	s_waitcnt lgkmcnt(0)
	v_mfma_f32_16x16x32_bf16 v[52:55], v[132:135], v[160:163], v[52:55]
	v_mfma_f32_16x16x32_bf16 v[48:51], v[152:155], v[160:163], v[48:51]
	v_mfma_f32_16x16x32_bf16 v[36:39], v[132:135], v[178:181], v[36:39]
	v_mfma_f32_16x16x32_bf16 v[32:35], v[152:155], v[178:181], v[32:35]
	v_mfma_f32_16x16x32_bf16 v[20:23], v[132:135], v[186:189], v[20:23]
	v_mfma_f32_16x16x32_bf16 v[16:19], v[152:155], v[186:189], v[16:19]
	v_mfma_f32_16x16x32_bf16 v[4:7], v[132:135], v[194:197], v[4:7]
	v_mfma_f32_16x16x32_bf16 v[0:3], v[152:155], v[194:197], v[0:3]
	v_mfma_f32_16x16x32_bf16 v[52:55], v[136:139], v[164:167], v[52:55]
	v_mfma_f32_16x16x32_bf16 v[48:51], v[156:159], v[164:167], v[48:51]
	v_mfma_f32_16x16x32_bf16 v[36:39], v[136:139], v[182:185], v[36:39]
	v_mfma_f32_16x16x32_bf16 v[32:35], v[156:159], v[182:185], v[32:35]
	v_mfma_f32_16x16x32_bf16 v[20:23], v[136:139], v[190:193], v[20:23]
	v_mfma_f32_16x16x32_bf16 v[16:19], v[156:159], v[190:193], v[16:19]
	s_add_u32 s34, s34, 0x40080
	v_mfma_f32_16x16x32_bf16 v[4:7], v[136:139], v[198:201], v[4:7]
	s_addc_u32 s35, s35, 0
	v_mfma_f32_16x16x32_bf16 v[0:3], v[156:159], v[198:201], v[0:3]
	s_barrier
	s_mov_b32 m0, s56
	v_lshl_add_u64 v[132:133], s[34:35], 0, v[144:145]
	global_load_lds_dwordx4 v[132:133], off
	s_mov_b32 m0, s57
	v_lshl_add_u64 v[132:133], s[34:35], 0, v[140:141]
	global_load_lds_dwordx4 v[132:133], off
	s_waitcnt vmcnt(6)
	s_barrier
	v_mfma_f32_16x16x32_bf16 v[60:63], v[202:205], v[160:163], v[60:63]
	v_mfma_f32_16x16x32_bf16 v[56:59], v[210:213], v[160:163], v[56:59]
	v_mfma_f32_16x16x32_bf16 v[44:47], v[202:205], v[178:181], v[44:47]
	v_mfma_f32_16x16x32_bf16 v[40:43], v[210:213], v[178:181], v[40:43]
	v_mfma_f32_16x16x32_bf16 v[28:31], v[202:205], v[186:189], v[28:31]
	v_mfma_f32_16x16x32_bf16 v[24:27], v[210:213], v[186:189], v[24:27]
	v_mfma_f32_16x16x32_bf16 v[12:15], v[202:205], v[194:197], v[12:15]
	v_mfma_f32_16x16x32_bf16 v[8:11], v[210:213], v[194:197], v[8:11]
	v_mfma_f32_16x16x32_bf16 v[60:63], v[206:209], v[164:167], v[60:63]
	v_mfma_f32_16x16x32_bf16 v[56:59], v[214:217], v[164:167], v[56:59]
	v_mfma_f32_16x16x32_bf16 v[44:47], v[206:209], v[182:185], v[44:47]
	v_mfma_f32_16x16x32_bf16 v[40:43], v[214:217], v[182:185], v[40:43]
	s_add_i32 s17, s17, 2
	v_mfma_f32_16x16x32_bf16 v[28:31], v[206:209], v[190:193], v[28:31]
	s_add_u32 s30, s30, 0x100
	v_mfma_f32_16x16x32_bf16 v[24:27], v[214:217], v[190:193], v[24:27]
	s_addc_u32 s31, s31, 0
	v_mfma_f32_16x16x32_bf16 v[12:15], v[206:209], v[198:201], v[12:15]
	s_cmp_gt_u32 s17, 13
	v_mfma_f32_16x16x32_bf16 v[8:11], v[214:217], v[198:201], v[8:11]
	s_cbranch_scc0 .Lrot_920
	s_barrier
; __device__ __forceinline__ unsigned pk2(float lo, float hi) { unsigned r; asm volatile("v_cvt_pk_bf16_f32 %0, %1, %2" : "=v"(r) : "v"(lo), "v"(hi)); return r; }
; __device__ __forceinline__ unsigned pk2(float lo, float hi) { return f2bf(lo) | (f2bf(hi) << 16); }
; __device__ __forceinline__ float fast_sigmoid(float z) { return __builtin_amdgcn_rcpf(1.0f + __expf(-z)); }
;     __device__ __forceinline__ void epi(const f32x4 (&acc)[2][2][4][2], const Unit& u, int wr, int wc, int fr, int fq) const {
;         const int row0 = u.pm * 256 + wr * 64 + fr, col0 = u.pn * 128 + wc * 32 + 8 * fq;
; #pragma unroll
;         for (int ai = 0; ai < 2; ++ai) {
;             u32x4 xo[4];
; #pragma unroll
;             for (int m = 0; m < 4; ++m) xo[m] = *(const u32x4*)(xb + (size_t)(row0 + ai * 128 + m * 16) * D + col0);
; #pragma unroll
;             for (int m = 0; m < 4; ++m) {
;                 const int row = row0 + ai * 128 + m * 16; const size_t off = (size_t)row * D + col0;
;                 const u32x4 o = xo[m]; const f32x4 a0v = acc[ai][0][m][0], a1v = acc[ai][0][m][1], b0v = acc[ai][1][m][0], b1v = acc[ai][1][m][1];
;                 const float v0 = bf_lo(o.x) + coef * a0v[0] * fast_sigmoid(b0v[0]), v1 = bf_hi(o.x) + coef * a0v[1] * fast_sigmoid(b0v[1]);
;                 const float v2 = bf_lo(o.y) + coef * a0v[2] * fast_sigmoid(b0v[2]), v3 = bf_hi(o.y) + coef * a0v[3] * fast_sigmoid(b0v[3]);
;                 const float v4 = bf_lo(o.z) + coef * a1v[0] * fast_sigmoid(b1v[0]), v5 = bf_hi(o.z) + coef * a1v[1] * fast_sigmoid(b1v[1]);
;                 const float v6 = bf_lo(o.w) + coef * a1v[2] * fast_sigmoid(b1v[2]), v7 = bf_hi(o.w) + coef * a1v[3] * fast_sigmoid(b1v[3]);
;                 u32x4 w; w.x = pk2(v0, v1); w.y = pk2(v2, v3); w.z = pk2(v4, v5); w.w = pk2(v6, v7);
;                 *(u32x4*)(xb + off) = w;
;                 float ss = ((v0 * v0 + v1 * v1) + (v2 * v2 + v3 * v3)) + ((v4 * v4 + v5 * v5) + (v6 * v6 + v7 * v7));
;                 ss += __shfl_xor(ss, 16); ss += __shfl_xor(ss, 32);
;                 if (fq == 0) rowss[(size_t)row * 32 + u.pn * 4 + wc] = ss;
;             }
	v_lshl_or_b32 v152, s59, 7, v171
	v_lshl_add_u32 v156, s8, 8, v170
	v_ashrrev_i32_e32 v153, 31, v152
	v_lshlrev_b64 v[182:183], 1, v[152:153]
	v_ashrrev_i32_e32 v157, 31, v156
	v_lshl_add_u64 v[154:155], s[0:1], 0, v[182:183]
	v_lshlrev_b64 v[184:185], 11, v[156:157]
	v_lshl_add_u64 v[120:121], v[154:155], 0, v[184:185]
	v_mov_b32_e32 v236, 0x40000
	v_mov_b32_e32 v237, 0
	v_lshl_add_u64 v[234:235], v[120:121], 0, v[236:237]
	v_mov_b32_e32 v236, 0x8000
	global_load_dwordx4 v[178:181], v[120:121], off
	v_or_b32_e32 v166, 16, v156
	v_or_b32_e32 v162, 32, v156
	v_or_b32_e32 v158, 48, v156
	v_ashrrev_i32_e32 v167, 31, v166
	v_ashrrev_i32_e32 v163, 31, v162
	v_ashrrev_i32_e32 v159, 31, v158
	v_lshlrev_b64 v[168:169], 11, v[166:167]
	v_lshlrev_b64 v[164:165], 11, v[162:163]
	v_lshlrev_b64 v[160:161], 11, v[158:159]
	v_lshl_add_u64 v[120:121], v[154:155], 0, v[168:169]
	v_lshl_add_u64 v[122:123], v[154:155], 0, v[164:165]
	v_lshl_add_u64 v[186:187], v[154:155], 0, v[160:161]
	global_load_dwordx4 v[136:139], v[120:121], off
	global_load_dwordx4 v[132:135], v[122:123], off
	s_nop 0
	global_load_dwordx4 v[120:123], v[186:187], off
	global_load_dwordx4 v[238:241], v[234:235], off
	v_lshl_add_u64 v[234:235], v[234:235], 0, v[236:237]
	global_load_dwordx4 v[242:245], v[234:235], off
	v_lshl_add_u64 v[234:235], v[234:235], 0, v[236:237]
	global_load_dwordx4 v[246:249], v[234:235], off
	v_lshl_add_u64 v[234:235], v[234:235], 0, v[236:237]
	global_load_dwordx4 v[250:253], v[234:235], off
	v_mul_f32_e32 v129, 0xbfb8aa3b, v129
	v_mul_f32_e32 v131, 0xbfb8aa3b, v131
	v_mul_f32_e32 v125, 0xbfb8aa3b, v125
	v_mul_f32_e32 v127, 0xbfb8aa3b, v127
	v_mul_f32_e32 v128, 0xbfb8aa3b, v128
	v_mul_f32_e32 v130, 0xbfb8aa3b, v130
	v_mul_f32_e32 v124, 0xbfb8aa3b, v124
	v_mul_f32_e32 v126, 0xbfb8aa3b, v126
	v_exp_f32_e32 v129, v129
	v_exp_f32_e32 v131, v131
	v_exp_f32_e32 v125, v125
	v_exp_f32_e32 v127, v127
	v_exp_f32_e32 v128, v128
	v_exp_f32_e32 v130, v130
	v_exp_f32_e32 v189, v124
	v_exp_f32_e32 v126, v126
	v_and_b32_e32 v187, 64, v175
	v_xor_b32_e32 v186, 16, v175
	v_add_u32_e32 v187, 64, v187
	v_cmp_lt_i32_e32 vcc, v186, v187
	v_add_f32_e32 v129, 1.0, v129
	v_add_f32_e32 v131, 1.0, v131
	v_add_f32_e32 v125, 1.0, v125
	v_add_f32_e32 v127, 1.0, v127
	v_cndmask_b32_e32 v124, v175, v186, vcc
	v_add_f32_e32 v128, 1.0, v128
	v_add_f32_e32 v130, 1.0, v130
	v_add_f32_e32 v186, 1.0, v189
	v_add_f32_e32 v126, 1.0, v126
	v_rcp_f32_e32 v129, v129
	v_rcp_f32_e32 v131, v131
	v_rcp_f32_e32 v125, v125
	v_rcp_f32_e32 v127, v127
	v_rcp_f32_e32 v128, v128
	v_rcp_f32_e32 v130, v130
	v_rcp_f32_e32 v186, v186
	v_rcp_f32_e32 v126, v126
	v_lshlrev_b32_e32 v124, 2, v124
	v_xor_b32_e32 v188, 32, v175
	v_cmp_lt_i32_e32 vcc, v188, v187
	s_lshl_b32 s24, s59, 2
	s_ashr_i32 s25, s24, 31
	s_waitcnt vmcnt(4)
	v_lshlrev_b32_e32 v189, 16, v178
	v_and_b32_e32 v178, 0xffff0000, v178
	v_lshlrev_b32_e32 v190, 16, v179
	v_and_b32_e32 v179, 0xffff0000, v179
	v_lshlrev_b32_e32 v191, 16, v180
	v_and_b32_e32 v180, 0xffff0000, v180
	v_lshlrev_b32_e32 v192, 16, v181
	v_and_b32_e32 v181, 0xffff0000, v181
	v_fmac_f32_e32 v178, v117, v129
	v_fmac_f32_e32 v179, v119, v131
	v_fmac_f32_e32 v180, v113, v125
	v_fmac_f32_e32 v181, v115, v127
	v_fmac_f32_e32 v189, v116, v128
	v_fmac_f32_e32 v190, v118, v130
	v_fmac_f32_e32 v191, v112, v186
	v_fmac_f32_e32 v192, v114, v126
	v_mul_f32_e32 v112, v178, v178
	v_mul_f32_e32 v113, v179, v179
	v_mul_f32_e32 v114, v180, v180
	v_mul_f32_e32 v115, v181, v181
	v_fmac_f32_e32 v112, v189, v189
	v_fmac_f32_e32 v113, v190, v190
	v_fmac_f32_e32 v114, v191, v191
	v_fmac_f32_e32 v115, v192, v192
	v_add_f32_e32 v112, v112, v113
	v_add_f32_e32 v113, v114, v115
	v_add_f32_e32 v112, v112, v113
	ds_bpermute_b32 v113, v124, v112
	v_lshl_add_u64 v[126:127], s[0:1], 0, v[184:185]
	v_lshl_add_u64 v[126:127], v[126:127], 0, v[182:183]
	v_cvt_pk_bf16_f32 v116, v189, v178
	v_cvt_pk_bf16_f32 v117, v190, v179
	s_waitcnt lgkmcnt(0)
	v_add_f32_e32 v113, v112, v113
	v_cndmask_b32_e32 v112, v175, v188, vcc
	v_lshlrev_b32_e32 v112, 2, v112
	ds_bpermute_b32 v114, v112, v113
	v_cvt_pk_bf16_f32 v118, v191, v180
	v_cvt_pk_bf16_f32 v119, v192, v181
	global_store_dwordx4 v[126:127], v[116:119], off
	s_and_saveexec_b64 s[26:27], s[4:5]
	s_cbranch_execz .LBB0_923
	v_lshlrev_b64 v[116:117], 7, v[156:157]
	v_lshl_add_u64 v[116:117], s[2:3], 0, v[116:117]
	v_lshl_add_u64 v[116:117], s[24:25], 2, v[116:117]
	s_lshl_b32 s8, s45, 2
	v_lshl_add_u64 v[116:117], v[116:117], 0, s[8:9]
	s_waitcnt lgkmcnt(0)
	v_add_f32_e32 v113, v113, v114
	global_store_dword v[116:117], v113, off

.LBB0_1906:
	ds_read_b128 v[134:137], v185
	ds_read_b128 v[138:141], v185 offset:1024
	ds_read_b128 v[142:145], v185 offset:2048
	ds_read_b128 v[146:149], v185 offset:3072
	s_mov_b32 m0, s45
	v_lshl_add_u64 v[150:151], v[128:129], 0, s[24:25]
	ds_read_b128 v[164:167], v186
	ds_read_b128 v[168:171], v186 offset:1024
	ds_read_b128 v[172:175], v186 offset:2048
	ds_read_b128 v[176:179], v186 offset:3072
	ds_read_b128 v[190:193], v186 offset:4096
	ds_read_b128 v[194:197], v186 offset:5120
	ds_read_b128 v[198:201], v186 offset:6144
	ds_read_b128 v[202:205], v186 offset:7168
	global_load_lds_dwordx4 v[150:151], off
	s_mov_b32 m0, s46
	v_lshl_add_u64 v[150:151], v[130:131], 0, s[24:25]
	global_load_lds_dwordx4 v[150:151], off
	s_waitcnt lgkmcnt(8)
	s_barrier
	s_waitcnt lgkmcnt(0)
	v_mfma_f32_16x16x32_bf16 v[116:119], v[134:137], v[164:167], v[116:119]
	s_add_i32 s26, s24, 0xfff50080
	v_mfma_f32_16x16x32_bf16 v[112:115], v[142:145], v[164:167], v[112:115]
	s_cmp_eq_u32 s58, 40
	v_mfma_f32_16x16x32_bf16 v[108:111], v[134:137], v[172:175], v[108:111]
	s_cselect_b32 s59, s19, s21
	v_mfma_f32_16x16x32_bf16 v[104:107], v[142:145], v[172:175], v[104:107]
	s_cselect_b32 s60, s18, s20
	v_mfma_f32_16x16x32_bf16 v[92:95], v[134:137], v[190:193], v[92:95]
	s_cselect_b32 s27, s7, s23
	v_mfma_f32_16x16x32_bf16 v[88:91], v[142:145], v[190:193], v[88:91]
	s_cselect_b32 s61, s6, s22
	v_mfma_f32_16x16x32_bf16 v[76:79], v[134:137], v[198:201], v[76:79]
	v_mfma_f32_16x16x32_bf16 v[72:75], v[142:145], v[198:201], v[72:75]
	v_mfma_f32_16x16x32_bf16 v[116:119], v[138:141], v[168:171], v[116:119]
	v_mfma_f32_16x16x32_bf16 v[112:115], v[146:149], v[168:171], v[112:115]
	v_mfma_f32_16x16x32_bf16 v[108:111], v[138:141], v[176:179], v[108:111]
	v_mfma_f32_16x16x32_bf16 v[104:107], v[146:149], v[176:179], v[104:107]
	v_mfma_f32_16x16x32_bf16 v[92:95], v[138:141], v[194:197], v[92:95]
	s_cselect_b32 s62, 0, s26
	v_mfma_f32_16x16x32_bf16 v[88:91], v[146:149], v[194:197], v[88:91]
	s_add_u32 s26, s61, s62
	v_mfma_f32_16x16x32_bf16 v[76:79], v[138:141], v[202:205], v[76:79]
	s_addc_u32 s27, s27, 0
	v_mfma_f32_16x16x32_bf16 v[72:75], v[146:149], v[202:205], v[72:75]
	s_barrier
	s_mov_b32 m0, s47
	v_lshl_add_u64 v[150:151], s[26:27], 0, v[154:155]
	ds_read_b128 v[206:209], v187
	ds_read_b128 v[210:213], v187 offset:1024
	ds_read_b128 v[214:217], v187 offset:2048
	ds_read_b128 v[222:225], v187 offset:3072
	global_load_lds_dwordx4 v[150:151], off
	s_mov_b32 m0, s48
	v_lshl_add_u64 v[180:181], s[26:27], 0, v[158:159]
	global_load_lds_dwordx4 v[180:181], off
	s_barrier
	s_waitcnt lgkmcnt(0)
	v_mfma_f32_16x16x32_bf16 v[124:127], v[206:209], v[164:167], v[124:127]
	v_mfma_f32_16x16x32_bf16 v[120:123], v[214:217], v[164:167], v[120:123]
	v_mfma_f32_16x16x32_bf16 v[100:103], v[206:209], v[172:175], v[100:103]
	v_mfma_f32_16x16x32_bf16 v[96:99], v[214:217], v[172:175], v[96:99]
	v_mfma_f32_16x16x32_bf16 v[84:87], v[206:209], v[190:193], v[84:87]
	v_mfma_f32_16x16x32_bf16 v[80:83], v[214:217], v[190:193], v[80:83]
	v_mfma_f32_16x16x32_bf16 v[68:71], v[206:209], v[198:201], v[68:71]
	v_mfma_f32_16x16x32_bf16 v[64:67], v[214:217], v[198:201], v[64:67]
	v_mfma_f32_16x16x32_bf16 v[124:127], v[210:213], v[168:171], v[124:127]
	v_mfma_f32_16x16x32_bf16 v[120:123], v[222:225], v[168:171], v[120:123]
	v_mfma_f32_16x16x32_bf16 v[100:103], v[210:213], v[176:179], v[100:103]
	v_mfma_f32_16x16x32_bf16 v[96:99], v[222:225], v[176:179], v[96:99]
	v_mfma_f32_16x16x32_bf16 v[84:87], v[210:213], v[194:197], v[84:87]
	v_mfma_f32_16x16x32_bf16 v[80:83], v[222:225], v[194:197], v[80:83]
	s_add_u32 s60, s60, s62
	v_mfma_f32_16x16x32_bf16 v[68:71], v[210:213], v[202:205], v[68:71]
	s_addc_u32 s61, s59, 0
	v_mfma_f32_16x16x32_bf16 v[64:67], v[222:225], v[202:205], v[64:67]
	s_mov_b32 m0, s37
	v_lshl_add_u64 v[218:219], s[60:61], 0, v[152:153]
	s_barrier
	ds_read_b128 v[164:167], v186 offset:16384
	ds_read_b128 v[168:171], v186 offset:17408
	ds_read_b128 v[172:175], v186 offset:18432
	ds_read_b128 v[176:179], v186 offset:19456
	ds_read_b128 v[190:193], v186 offset:20480
	ds_read_b128 v[194:197], v186 offset:21504
	ds_read_b128 v[198:201], v186 offset:22528
	ds_read_b128 v[202:205], v186 offset:23552
	global_load_lds_dwordx4 v[218:219], off
	s_mov_b32 m0, s38
	v_lshl_add_u64 v[226:227], s[60:61], 0, v[156:157]
	global_load_lds_dwordx4 v[226:227], off
	s_barrier
	s_waitcnt lgkmcnt(0)
	v_mfma_f32_16x16x32_bf16 v[52:55], v[134:137], v[164:167], v[52:55]
	v_mfma_f32_16x16x32_bf16 v[48:51], v[142:145], v[164:167], v[48:51]
	v_mfma_f32_16x16x32_bf16 v[44:47], v[134:137], v[172:175], v[44:47]
	v_mfma_f32_16x16x32_bf16 v[36:39], v[142:145], v[172:175], v[36:39]
	v_mfma_f32_16x16x32_bf16 v[28:31], v[134:137], v[190:193], v[28:31]
	v_mfma_f32_16x16x32_bf16 v[20:23], v[142:145], v[190:193], v[20:23]
	v_mfma_f32_16x16x32_bf16 v[12:15], v[134:137], v[198:201], v[12:15]
	v_mfma_f32_16x16x32_bf16 v[4:7], v[142:145], v[198:201], v[4:7]
	v_mfma_f32_16x16x32_bf16 v[52:55], v[138:141], v[168:171], v[52:55]
	v_mfma_f32_16x16x32_bf16 v[48:51], v[146:149], v[168:171], v[48:51]
	v_mfma_f32_16x16x32_bf16 v[44:47], v[138:141], v[176:179], v[44:47]
	v_mfma_f32_16x16x32_bf16 v[36:39], v[146:149], v[176:179], v[36:39]
	v_mfma_f32_16x16x32_bf16 v[28:31], v[138:141], v[194:197], v[28:31]
	v_mfma_f32_16x16x32_bf16 v[20:23], v[146:149], v[194:197], v[20:23]
	s_add_u32 s62, s26, 0xb0000
	v_mfma_f32_16x16x32_bf16 v[12:15], v[138:141], v[202:205], v[12:15]
	s_addc_u32 s63, s27, 0
	v_mfma_f32_16x16x32_bf16 v[4:7], v[146:149], v[202:205], v[4:7]
	s_barrier
	s_mov_b32 m0, s52
	v_lshl_add_u64 v[134:135], s[62:63], 0, v[154:155]
	global_load_lds_dwordx4 v[134:135], off
	s_mov_b32 m0, s53
	v_lshl_add_u64 v[134:135], s[62:63], 0, v[158:159]
	global_load_lds_dwordx4 v[134:135], off
	s_waitcnt vmcnt(6)
	s_barrier
	v_mfma_f32_16x16x32_bf16 v[60:63], v[206:209], v[164:167], v[60:63]
	v_mfma_f32_16x16x32_bf16 v[56:59], v[214:217], v[164:167], v[56:59]
	v_mfma_f32_16x16x32_bf16 v[40:43], v[206:209], v[172:175], v[40:43]
	v_mfma_f32_16x16x32_bf16 v[32:35], v[214:217], v[172:175], v[32:35]
	v_mfma_f32_16x16x32_bf16 v[24:27], v[206:209], v[190:193], v[24:27]
	v_mfma_f32_16x16x32_bf16 v[16:19], v[214:217], v[190:193], v[16:19]
	v_mfma_f32_16x16x32_bf16 v[8:11], v[206:209], v[198:201], v[8:11]
	v_mfma_f32_16x16x32_bf16 v[0:3], v[214:217], v[198:201], v[0:3]
	v_mfma_f32_16x16x32_bf16 v[60:63], v[210:213], v[168:171], v[60:63]
	v_mfma_f32_16x16x32_bf16 v[56:59], v[222:225], v[168:171], v[56:59]
	v_mfma_f32_16x16x32_bf16 v[40:43], v[210:213], v[176:179], v[40:43]
	v_mfma_f32_16x16x32_bf16 v[32:35], v[222:225], v[176:179], v[32:35]
	v_mfma_f32_16x16x32_bf16 v[24:27], v[210:213], v[194:197], v[24:27]
	v_mfma_f32_16x16x32_bf16 v[16:19], v[222:225], v[194:197], v[16:19]
	s_add_u32 s60, s60, 0xb0000
	v_mfma_f32_16x16x32_bf16 v[8:11], v[210:213], v[202:205], v[8:11]
	s_addc_u32 s61, s61, 0
	v_mfma_f32_16x16x32_bf16 v[0:3], v[222:225], v[202:205], v[0:3]
	s_barrier
	ds_read_b128 v[134:137], v132
	ds_read_b128 v[138:141], v132 offset:1024
	ds_read_b128 v[142:145], v132 offset:2048
	ds_read_b128 v[146:149], v132 offset:3072
	s_mov_b32 m0, s39
	v_lshl_add_u64 v[206:207], s[60:61], 0, v[152:153]
	ds_read_b128 v[164:167], v186 offset:32768
	ds_read_b128 v[168:171], v186 offset:33792
	ds_read_b128 v[172:175], v186 offset:34816
	ds_read_b128 v[176:179], v186 offset:35840
	ds_read_b128 v[190:193], v186 offset:36864
	ds_read_b128 v[194:197], v186 offset:37888
	ds_read_b128 v[198:201], v186 offset:38912
	ds_read_b128 v[202:205], v186 offset:39936
	global_load_lds_dwordx4 v[206:207], off
	s_mov_b32 m0, s40
	v_lshl_add_u64 v[206:207], s[60:61], 0, v[156:157]
	global_load_lds_dwordx4 v[206:207], off
	s_waitcnt lgkmcnt(8)
	s_barrier
	s_waitcnt lgkmcnt(0)
	v_mfma_f32_16x16x32_bf16 v[116:119], v[134:137], v[164:167], v[116:119]
	v_mfma_f32_16x16x32_bf16 v[112:115], v[142:145], v[164:167], v[112:115]
	v_mfma_f32_16x16x32_bf16 v[108:111], v[134:137], v[172:175], v[108:111]
	v_mfma_f32_16x16x32_bf16 v[104:107], v[142:145], v[172:175], v[104:107]
	v_mfma_f32_16x16x32_bf16 v[92:95], v[134:137], v[190:193], v[92:95]
	v_mfma_f32_16x16x32_bf16 v[88:91], v[142:145], v[190:193], v[88:91]
	v_mfma_f32_16x16x32_bf16 v[76:79], v[134:137], v[198:201], v[76:79]
	v_mfma_f32_16x16x32_bf16 v[72:75], v[142:145], v[198:201], v[72:75]
	v_mfma_f32_16x16x32_bf16 v[116:119], v[138:141], v[168:171], v[116:119]
	v_mfma_f32_16x16x32_bf16 v[112:115], v[146:149], v[168:171], v[112:115]
	v_mfma_f32_16x16x32_bf16 v[108:111], v[138:141], v[176:179], v[108:111]
	v_mfma_f32_16x16x32_bf16 v[104:107], v[146:149], v[176:179], v[104:107]
	v_mfma_f32_16x16x32_bf16 v[92:95], v[138:141], v[194:197], v[92:95]
	v_mfma_f32_16x16x32_bf16 v[88:91], v[146:149], v[194:197], v[88:91]
	v_mfma_f32_16x16x32_bf16 v[76:79], v[138:141], v[202:205], v[76:79]
	v_mfma_f32_16x16x32_bf16 v[72:75], v[146:149], v[202:205], v[72:75]
	s_barrier
	s_mov_b32 m0, s54
	v_lshl_add_u64 v[150:151], v[150:151], 0, s[10:11]
	ds_read_b128 v[206:209], v133
	ds_read_b128 v[210:213], v133 offset:1024
	ds_read_b128 v[214:217], v133 offset:2048
	ds_read_b128 v[222:225], v133 offset:3072
	global_load_lds_dwordx4 v[150:151], off
	s_mov_b32 m0, s55
	v_lshl_add_u64 v[150:151], v[180:181], 0, s[10:11]
	global_load_lds_dwordx4 v[150:151], off
	s_barrier
	s_waitcnt lgkmcnt(0)
	v_mfma_f32_16x16x32_bf16 v[124:127], v[206:209], v[164:167], v[124:127]
	v_mfma_f32_16x16x32_bf16 v[120:123], v[214:217], v[164:167], v[120:123]
	v_mfma_f32_16x16x32_bf16 v[100:103], v[206:209], v[172:175], v[100:103]
	v_mfma_f32_16x16x32_bf16 v[96:99], v[214:217], v[172:175], v[96:99]
	v_mfma_f32_16x16x32_bf16 v[84:87], v[206:209], v[190:193], v[84:87]
	v_mfma_f32_16x16x32_bf16 v[80:83], v[214:217], v[190:193], v[80:83]
	v_mfma_f32_16x16x32_bf16 v[68:71], v[206:209], v[198:201], v[68:71]
	v_mfma_f32_16x16x32_bf16 v[64:67], v[214:217], v[198:201], v[64:67]
	v_mfma_f32_16x16x32_bf16 v[124:127], v[210:213], v[168:171], v[124:127]
	v_mfma_f32_16x16x32_bf16 v[120:123], v[222:225], v[168:171], v[120:123]
	v_mfma_f32_16x16x32_bf16 v[100:103], v[210:213], v[176:179], v[100:103]
	v_mfma_f32_16x16x32_bf16 v[96:99], v[222:225], v[176:179], v[96:99]
	v_mfma_f32_16x16x32_bf16 v[84:87], v[210:213], v[194:197], v[84:87]
	v_mfma_f32_16x16x32_bf16 v[80:83], v[222:225], v[194:197], v[80:83]
	v_mfma_f32_16x16x32_bf16 v[68:71], v[210:213], v[202:205], v[68:71]
	v_mfma_f32_16x16x32_bf16 v[64:67], v[222:225], v[202:205], v[64:67]
	s_mov_b32 m0, s42
	v_lshl_add_u64 v[150:151], v[218:219], 0, s[10:11]
	s_barrier
	ds_read_b128 v[164:167], v186 offset:49152
	ds_read_b128 v[168:171], v186 offset:50176
	ds_read_b128 v[172:175], v186 offset:51200
	ds_read_b128 v[176:179], v186 offset:52224
	ds_read_b128 v[190:193], v186 offset:53248
	ds_read_b128 v[194:197], v186 offset:54272
	ds_read_b128 v[198:201], v186 offset:55296
	ds_read_b128 v[202:205], v186 offset:56320
	global_load_lds_dwordx4 v[150:151], off
	s_mov_b32 m0, s43
	v_lshl_add_u64 v[150:151], v[226:227], 0, s[10:11]
	global_load_lds_dwordx4 v[150:151], off
	s_barrier
;     ...
;         G_PAIR(0, 1);
; #pragma unroll 1
;         for (int t = 2; t < nt; t += 2) G_PAIR(t, 0);
	s_waitcnt lgkmcnt(0)
	v_mfma_f32_16x16x32_bf16 v[52:55], v[134:137], v[164:167], v[52:55]
	v_mfma_f32_16x16x32_bf16 v[48:51], v[142:145], v[164:167], v[48:51]
	v_mfma_f32_16x16x32_bf16 v[44:47], v[134:137], v[172:175], v[44:47]
	v_mfma_f32_16x16x32_bf16 v[36:39], v[142:145], v[172:175], v[36:39]
	v_mfma_f32_16x16x32_bf16 v[28:31], v[134:137], v[190:193], v[28:31]
	v_mfma_f32_16x16x32_bf16 v[20:23], v[142:145], v[190:193], v[20:23]
	v_mfma_f32_16x16x32_bf16 v[12:15], v[134:137], v[198:201], v[12:15]
	v_mfma_f32_16x16x32_bf16 v[4:7], v[142:145], v[198:201], v[4:7]
	v_mfma_f32_16x16x32_bf16 v[52:55], v[138:141], v[168:171], v[52:55]
	v_mfma_f32_16x16x32_bf16 v[48:51], v[146:149], v[168:171], v[48:51]
	v_mfma_f32_16x16x32_bf16 v[44:47], v[138:141], v[176:179], v[44:47]
	v_mfma_f32_16x16x32_bf16 v[36:39], v[146:149], v[176:179], v[36:39]
	v_mfma_f32_16x16x32_bf16 v[28:31], v[138:141], v[194:197], v[28:31]
	v_mfma_f32_16x16x32_bf16 v[20:23], v[146:149], v[194:197], v[20:23]
	s_add_u32 s26, s26, 0xb0080
	v_mfma_f32_16x16x32_bf16 v[12:15], v[138:141], v[202:205], v[12:15]
	s_addc_u32 s27, s27, 0
	v_mfma_f32_16x16x32_bf16 v[4:7], v[146:149], v[202:205], v[4:7]
	s_barrier
	s_mov_b32 m0, s56
	v_lshl_add_u64 v[134:135], s[26:27], 0, v[154:155]
	global_load_lds_dwordx4 v[134:135], off
	s_mov_b32 m0, s57
	v_lshl_add_u64 v[134:135], s[26:27], 0, v[158:159]
	global_load_lds_dwordx4 v[134:135], off
	s_waitcnt vmcnt(6)
	s_barrier
	v_mfma_f32_16x16x32_bf16 v[60:63], v[206:209], v[164:167], v[60:63]
	v_mfma_f32_16x16x32_bf16 v[56:59], v[214:217], v[164:167], v[56:59]
	v_mfma_f32_16x16x32_bf16 v[40:43], v[206:209], v[172:175], v[40:43]
	v_mfma_f32_16x16x32_bf16 v[32:35], v[214:217], v[172:175], v[32:35]
	v_mfma_f32_16x16x32_bf16 v[24:27], v[206:209], v[190:193], v[24:27]
	v_mfma_f32_16x16x32_bf16 v[16:19], v[214:217], v[190:193], v[16:19]
	v_mfma_f32_16x16x32_bf16 v[8:11], v[206:209], v[198:201], v[8:11]
	v_mfma_f32_16x16x32_bf16 v[0:3], v[214:217], v[198:201], v[0:3]
	v_mfma_f32_16x16x32_bf16 v[60:63], v[210:213], v[168:171], v[60:63]
	v_mfma_f32_16x16x32_bf16 v[56:59], v[222:225], v[168:171], v[56:59]
	v_mfma_f32_16x16x32_bf16 v[40:43], v[210:213], v[176:179], v[40:43]
	v_mfma_f32_16x16x32_bf16 v[32:35], v[222:225], v[176:179], v[32:35]
	s_add_i32 s58, s58, 2
	v_mfma_f32_16x16x32_bf16 v[24:27], v[210:213], v[194:197], v[24:27]
	s_add_u32 s24, s24, 0x100
	v_mfma_f32_16x16x32_bf16 v[16:19], v[222:225], v[194:197], v[16:19]
	s_addc_u32 s25, s25, 0
	v_mfma_f32_16x16x32_bf16 v[8:11], v[210:213], v[202:205], v[8:11]
	s_cmp_gt_u32 s58, 39
	v_mfma_f32_16x16x32_bf16 v[0:3], v[222:225], v[202:205], v[0:3]
	s_cbranch_scc0 .Lrot_1906
	s_barrier
	ds_read_b128 v[134:137], v185
	ds_read_b128 v[138:141], v185 offset:1024
	ds_read_b128 v[142:145], v185 offset:2048
	ds_read_b128 v[146:149], v185 offset:3072
	s_mov_b32 m0, s45
	v_lshl_add_u64 v[150:151], v[128:129], 0, s[24:25]
	ds_read_b128 v[164:167], v186
	ds_read_b128 v[168:171], v186 offset:1024
	ds_read_b128 v[172:175], v186 offset:2048
	ds_read_b128 v[176:179], v186 offset:3072
	ds_read_b128 v[190:193], v186 offset:4096
	ds_read_b128 v[194:197], v186 offset:5120
	ds_read_b128 v[198:201], v186 offset:6144
	ds_read_b128 v[202:205], v186 offset:7168
	global_load_lds_dwordx4 v[150:151], off
	s_mov_b32 m0, s46
	v_lshl_add_u64 v[150:151], v[130:131], 0, s[24:25]
	global_load_lds_dwordx4 v[150:151], off
	s_waitcnt lgkmcnt(8)
	s_barrier
	s_waitcnt lgkmcnt(0)
	v_mfma_f32_16x16x32_bf16 v[116:119], v[134:137], v[164:167], v[116:119]
	s_add_i32 s26, s24, 0xfff50080
	v_mfma_f32_16x16x32_bf16 v[112:115], v[142:145], v[164:167], v[112:115]
	s_cmp_eq_u32 s58, 40
	v_mfma_f32_16x16x32_bf16 v[108:111], v[134:137], v[172:175], v[108:111]
	s_cselect_b32 s59, s19, s21
	v_mfma_f32_16x16x32_bf16 v[104:107], v[142:145], v[172:175], v[104:107]
	s_cselect_b32 s60, s18, s20
	v_mfma_f32_16x16x32_bf16 v[92:95], v[134:137], v[190:193], v[92:95]
	s_cselect_b32 s27, s7, s23
	v_mfma_f32_16x16x32_bf16 v[88:91], v[142:145], v[190:193], v[88:91]
	s_cselect_b32 s61, s6, s22
	v_mfma_f32_16x16x32_bf16 v[76:79], v[134:137], v[198:201], v[76:79]
	v_mfma_f32_16x16x32_bf16 v[72:75], v[142:145], v[198:201], v[72:75]
	v_mfma_f32_16x16x32_bf16 v[116:119], v[138:141], v[168:171], v[116:119]
	v_mfma_f32_16x16x32_bf16 v[112:115], v[146:149], v[168:171], v[112:115]
	v_mfma_f32_16x16x32_bf16 v[108:111], v[138:141], v[176:179], v[108:111]
	v_mfma_f32_16x16x32_bf16 v[104:107], v[146:149], v[176:179], v[104:107]
	v_mfma_f32_16x16x32_bf16 v[92:95], v[138:141], v[194:197], v[92:95]
	v_mfma_f32_16x16x32_bf16 v[88:91], v[146:149], v[194:197], v[88:91]
	v_mfma_f32_16x16x32_bf16 v[76:79], v[138:141], v[202:205], v[76:79]
	v_mfma_f32_16x16x32_bf16 v[72:75], v[146:149], v[202:205], v[72:75]
	s_barrier
	s_cselect_b32 s62, 0, s26
	s_add_u32 s26, s61, s62
	s_addc_u32 s27, s27, 0
	s_mov_b32 m0, s47
	v_lshl_add_u64 v[150:151], s[26:27], 0, v[154:155]
	ds_read_b128 v[206:209], v187
	ds_read_b128 v[210:213], v187 offset:1024
	ds_read_b128 v[214:217], v187 offset:2048
	ds_read_b128 v[222:225], v187 offset:3072
	global_load_lds_dwordx4 v[150:151], off
	s_mov_b32 m0, s48
	v_lshl_add_u64 v[180:181], s[26:27], 0, v[158:159]
	global_load_lds_dwordx4 v[180:181], off
	s_barrier
;     __device__ __forceinline__ void epi(const f32x4 (&acc)[2][2][4][2], const Unit& u, int wr, int wc, int fr, int fq) const {
;     ...
;             u32x4 xo[4][2];
; #pragma unroll
;             for (int m = 0; m < 4; ++m)
; #pragma unroll
;                 for (int bj = 0; bj < 2; ++bj) xo[m][bj] = *(const u32x4*)(xb + (size_t)(row0 + ai * 128 + m * 16) * D + col0 + bj * 128);
	s_waitcnt lgkmcnt(0)
	v_mfma_f32_16x16x32_bf16 v[124:127], v[206:209], v[164:167], v[124:127]
	v_mfma_f32_16x16x32_bf16 v[120:123], v[214:217], v[164:167], v[120:123]
	v_mfma_f32_16x16x32_bf16 v[100:103], v[206:209], v[172:175], v[100:103]
	v_mfma_f32_16x16x32_bf16 v[96:99], v[214:217], v[172:175], v[96:99]
	v_mfma_f32_16x16x32_bf16 v[84:87], v[206:209], v[190:193], v[84:87]
	v_mfma_f32_16x16x32_bf16 v[80:83], v[214:217], v[190:193], v[80:83]
	v_mfma_f32_16x16x32_bf16 v[68:71], v[206:209], v[198:201], v[68:71]
	v_mfma_f32_16x16x32_bf16 v[64:67], v[214:217], v[198:201], v[64:67]
	v_mfma_f32_16x16x32_bf16 v[124:127], v[210:213], v[168:171], v[124:127]
	v_mfma_f32_16x16x32_bf16 v[120:123], v[222:225], v[168:171], v[120:123]
	v_mfma_f32_16x16x32_bf16 v[100:103], v[210:213], v[176:179], v[100:103]
	v_mfma_f32_16x16x32_bf16 v[96:99], v[222:225], v[176:179], v[96:99]
	v_mfma_f32_16x16x32_bf16 v[84:87], v[210:213], v[194:197], v[84:87]
	v_mfma_f32_16x16x32_bf16 v[80:83], v[222:225], v[194:197], v[80:83]
	v_mfma_f32_16x16x32_bf16 v[68:71], v[210:213], v[202:205], v[68:71]
	v_mfma_f32_16x16x32_bf16 v[64:67], v[222:225], v[202:205], v[64:67]
	s_add_u32 s60, s60, s62
	s_addc_u32 s61, s59, 0
	s_mov_b32 m0, s37
	v_lshl_add_u64 v[218:219], s[60:61], 0, v[152:153]
	s_barrier
	ds_read_b128 v[164:167], v186 offset:16384
	ds_read_b128 v[168:171], v186 offset:17408
	ds_read_b128 v[172:175], v186 offset:18432
	ds_read_b128 v[176:179], v186 offset:19456
	ds_read_b128 v[190:193], v186 offset:20480
	ds_read_b128 v[194:197], v186 offset:21504
	ds_read_b128 v[198:201], v186 offset:22528
	ds_read_b128 v[202:205], v186 offset:23552
	global_load_lds_dwordx4 v[218:219], off
	s_mov_b32 m0, s38
	v_lshl_add_u64 v[226:227], s[60:61], 0, v[156:157]
	global_load_lds_dwordx4 v[226:227], off
	s_barrier
	s_waitcnt lgkmcnt(0)
	v_mfma_f32_16x16x32_bf16 v[52:55], v[134:137], v[164:167], v[52:55]
	v_mfma_f32_16x16x32_bf16 v[48:51], v[142:145], v[164:167], v[48:51]
	v_mfma_f32_16x16x32_bf16 v[44:47], v[134:137], v[172:175], v[44:47]
	v_mfma_f32_16x16x32_bf16 v[36:39], v[142:145], v[172:175], v[36:39]
	v_mfma_f32_16x16x32_bf16 v[28:31], v[134:137], v[190:193], v[28:31]
	v_mfma_f32_16x16x32_bf16 v[20:23], v[142:145], v[190:193], v[20:23]
	v_mfma_f32_16x16x32_bf16 v[12:15], v[134:137], v[198:201], v[12:15]
	v_mfma_f32_16x16x32_bf16 v[4:7], v[142:145], v[198:201], v[4:7]
	v_mfma_f32_16x16x32_bf16 v[52:55], v[138:141], v[168:171], v[52:55]
	v_mfma_f32_16x16x32_bf16 v[48:51], v[146:149], v[168:171], v[48:51]
	v_mfma_f32_16x16x32_bf16 v[44:47], v[138:141], v[176:179], v[44:47]
	v_mfma_f32_16x16x32_bf16 v[36:39], v[146:149], v[176:179], v[36:39]
	v_mfma_f32_16x16x32_bf16 v[28:31], v[138:141], v[194:197], v[28:31]
	v_mfma_f32_16x16x32_bf16 v[20:23], v[146:149], v[194:197], v[20:23]
	v_mfma_f32_16x16x32_bf16 v[12:15], v[138:141], v[202:205], v[12:15]
	v_mfma_f32_16x16x32_bf16 v[4:7], v[146:149], v[202:205], v[4:7]
	s_barrier
	s_add_u32 s62, s26, 0xb0000
	s_addc_u32 s63, s27, 0
	s_mov_b32 m0, s52
	v_lshl_add_u64 v[134:135], s[62:63], 0, v[154:155]
	global_load_lds_dwordx4 v[134:135], off
	s_mov_b32 m0, s53
	v_lshl_add_u64 v[134:135], s[62:63], 0, v[158:159]
	global_load_lds_dwordx4 v[134:135], off
	s_waitcnt vmcnt(6)
	s_barrier
	v_mfma_f32_16x16x32_bf16 v[60:63], v[206:209], v[164:167], v[60:63]
	v_lshl_or_b32 v248, s30, 8, v184
	v_mfma_f32_16x16x32_bf16 v[56:59], v[214:217], v[164:167], v[56:59]
	v_lshl_add_u32 v250, s2, 8, v182
	v_mfma_f32_16x16x32_bf16 v[40:43], v[206:209], v[172:175], v[40:43]
	v_ashrrev_i32_e32 v249, 31, v248
	v_mfma_f32_16x16x32_bf16 v[32:35], v[214:217], v[172:175], v[32:35]
	v_lshlrev_b64 v[248:249], 1, v[248:249]
	v_mfma_f32_16x16x32_bf16 v[24:27], v[206:209], v[190:193], v[24:27]
	v_ashrrev_i32_e32 v251, 31, v250
	v_mfma_f32_16x16x32_bf16 v[16:19], v[214:217], v[190:193], v[16:19]
	v_lshl_add_u64 v[248:249], s[0:1], 0, v[248:249]
	v_mfma_f32_16x16x32_bf16 v[8:11], v[206:209], v[198:201], v[8:11]
	v_lshlrev_b64 v[250:251], 11, v[250:251]
	v_mfma_f32_16x16x32_bf16 v[0:3], v[214:217], v[198:201], v[0:3]
	v_lshl_add_u64 v[252:253], v[248:249], 0, v[250:251]
	v_mfma_f32_16x16x32_bf16 v[60:63], v[210:213], v[168:171], v[60:63]
	global_load_dwordx4 v[232:235], v[252:253], off
	v_mfma_f32_16x16x32_bf16 v[56:59], v[222:225], v[168:171], v[56:59]
	global_load_dwordx4 v[236:239], v[252:253], off offset:256
	v_mfma_f32_16x16x32_bf16 v[40:43], v[210:213], v[176:179], v[40:43]
	v_mov_b32_e32 v250, 0x8000
	v_mfma_f32_16x16x32_bf16 v[32:35], v[222:225], v[176:179], v[32:35]
	v_mov_b32_e32 v251, 0
	v_mfma_f32_16x16x32_bf16 v[24:27], v[210:213], v[194:197], v[24:27]
	v_lshl_add_u64 v[250:251], v[252:253], 0, v[250:251]
	v_mfma_f32_16x16x32_bf16 v[16:19], v[222:225], v[194:197], v[16:19]
	global_load_dwordx4 v[240:243], v[250:251], off
	v_mfma_f32_16x16x32_bf16 v[8:11], v[210:213], v[202:205], v[8:11]
	global_load_dwordx4 v[244:247], v[250:251], off offset:256
	v_mfma_f32_16x16x32_bf16 v[0:3], v[222:225], v[202:205], v[0:3]
	s_barrier
	ds_read_b128 v[134:137], v132
	ds_read_b128 v[138:141], v132 offset:1024
	ds_read_b128 v[142:145], v132 offset:2048
	ds_read_b128 v[146:149], v132 offset:3072
	s_add_u32 s60, s60, 0xb0000
	s_addc_u32 s61, s61, 0
	s_mov_b32 m0, s39
	v_lshl_add_u64 v[206:207], s[60:61], 0, v[152:153]
	ds_read_b128 v[164:167], v186 offset:32768
	ds_read_b128 v[168:171], v186 offset:33792
	ds_read_b128 v[172:175], v186 offset:34816
	ds_read_b128 v[176:179], v186 offset:35840
	ds_read_b128 v[190:193], v186 offset:36864
	ds_read_b128 v[194:197], v186 offset:37888
	ds_read_b128 v[198:201], v186 offset:38912
	ds_read_b128 v[202:205], v186 offset:39936
	global_load_lds_dwordx4 v[206:207], off
	s_mov_b32 m0, s40
	v_lshl_add_u64 v[206:207], s[60:61], 0, v[156:157]
	global_load_lds_dwordx4 v[206:207], off
	s_waitcnt lgkmcnt(8)
	s_barrier
;     ...
;         for (int t = 2; t < nt; t += 2) G_PAIR(t, 0);
	s_waitcnt lgkmcnt(0)
	v_mfma_f32_16x16x32_bf16 v[116:119], v[134:137], v[164:167], v[116:119]
	v_mfma_f32_16x16x32_bf16 v[112:115], v[142:145], v[164:167], v[112:115]
	v_mfma_f32_16x16x32_bf16 v[108:111], v[134:137], v[172:175], v[108:111]
	v_mfma_f32_16x16x32_bf16 v[104:107], v[142:145], v[172:175], v[104:107]
	v_mfma_f32_16x16x32_bf16 v[92:95], v[134:137], v[190:193], v[92:95]
	v_mfma_f32_16x16x32_bf16 v[88:91], v[142:145], v[190:193], v[88:91]
	v_mfma_f32_16x16x32_bf16 v[76:79], v[134:137], v[198:201], v[76:79]
	v_mfma_f32_16x16x32_bf16 v[72:75], v[142:145], v[198:201], v[72:75]
	v_mfma_f32_16x16x32_bf16 v[116:119], v[138:141], v[168:171], v[116:119]
	v_mfma_f32_16x16x32_bf16 v[112:115], v[146:149], v[168:171], v[112:115]
	v_mfma_f32_16x16x32_bf16 v[108:111], v[138:141], v[176:179], v[108:111]
	v_mfma_f32_16x16x32_bf16 v[104:107], v[146:149], v[176:179], v[104:107]
	v_mfma_f32_16x16x32_bf16 v[92:95], v[138:141], v[194:197], v[92:95]
	v_mfma_f32_16x16x32_bf16 v[88:91], v[146:149], v[194:197], v[88:91]
	v_mfma_f32_16x16x32_bf16 v[76:79], v[138:141], v[202:205], v[76:79]
	v_mfma_f32_16x16x32_bf16 v[72:75], v[146:149], v[202:205], v[72:75]
	s_barrier
	s_mov_b32 m0, s54
	v_lshl_add_u64 v[150:151], v[150:151], 0, s[10:11]
	ds_read_b128 v[206:209], v133
	ds_read_b128 v[210:213], v133 offset:1024
	ds_read_b128 v[214:217], v133 offset:2048
	ds_read_b128 v[222:225], v133 offset:3072
	global_load_lds_dwordx4 v[150:151], off
	s_mov_b32 m0, s55
	v_lshl_add_u64 v[150:151], v[180:181], 0, s[10:11]
	global_load_lds_dwordx4 v[150:151], off
	s_barrier
	s_waitcnt lgkmcnt(0)
	v_mfma_f32_16x16x32_bf16 v[124:127], v[206:209], v[164:167], v[124:127]
	v_mfma_f32_16x16x32_bf16 v[120:123], v[214:217], v[164:167], v[120:123]
	v_mfma_f32_16x16x32_bf16 v[100:103], v[206:209], v[172:175], v[100:103]
	v_mfma_f32_16x16x32_bf16 v[96:99], v[214:217], v[172:175], v[96:99]
	v_mfma_f32_16x16x32_bf16 v[84:87], v[206:209], v[190:193], v[84:87]
	v_mfma_f32_16x16x32_bf16 v[80:83], v[214:217], v[190:193], v[80:83]
	v_mfma_f32_16x16x32_bf16 v[68:71], v[206:209], v[198:201], v[68:71]
	v_mfma_f32_16x16x32_bf16 v[64:67], v[214:217], v[198:201], v[64:67]
	v_mfma_f32_16x16x32_bf16 v[124:127], v[210:213], v[168:171], v[124:127]
	v_mfma_f32_16x16x32_bf16 v[120:123], v[222:225], v[168:171], v[120:123]
	v_mfma_f32_16x16x32_bf16 v[100:103], v[210:213], v[176:179], v[100:103]
	v_mfma_f32_16x16x32_bf16 v[96:99], v[222:225], v[176:179], v[96:99]
	v_mfma_f32_16x16x32_bf16 v[84:87], v[210:213], v[194:197], v[84:87]
	v_mfma_f32_16x16x32_bf16 v[80:83], v[222:225], v[194:197], v[80:83]
	v_mfma_f32_16x16x32_bf16 v[68:71], v[210:213], v[202:205], v[68:71]
	v_mfma_f32_16x16x32_bf16 v[64:67], v[222:225], v[202:205], v[64:67]
	s_mov_b32 m0, s42
	v_lshl_add_u64 v[150:151], v[218:219], 0, s[10:11]
	s_barrier
	ds_read_b128 v[164:167], v186 offset:49152
	ds_read_b128 v[168:171], v186 offset:50176
	ds_read_b128 v[172:175], v186 offset:51200
	ds_read_b128 v[176:179], v186 offset:52224
	ds_read_b128 v[190:193], v186 offset:53248
	ds_read_b128 v[194:197], v186 offset:54272
	ds_read_b128 v[198:201], v186 offset:55296
	ds_read_b128 v[202:205], v186 offset:56320
	global_load_lds_dwordx4 v[150:151], off
	s_mov_b32 m0, s43
	v_lshl_add_u64 v[150:151], v[226:227], 0, s[10:11]
	global_load_lds_dwordx4 v[150:151], off
	s_barrier
	s_waitcnt lgkmcnt(0)
	v_mfma_f32_16x16x32_bf16 v[52:55], v[134:137], v[164:167], v[52:55]
	v_mfma_f32_16x16x32_bf16 v[48:51], v[142:145], v[164:167], v[48:51]
	v_mfma_f32_16x16x32_bf16 v[44:47], v[134:137], v[172:175], v[44:47]
	v_mfma_f32_16x16x32_bf16 v[36:39], v[142:145], v[172:175], v[36:39]
	v_mfma_f32_16x16x32_bf16 v[28:31], v[134:137], v[190:193], v[28:31]
	v_mfma_f32_16x16x32_bf16 v[20:23], v[142:145], v[190:193], v[20:23]
	v_mfma_f32_16x16x32_bf16 v[12:15], v[134:137], v[198:201], v[12:15]
	v_mfma_f32_16x16x32_bf16 v[4:7], v[142:145], v[198:201], v[4:7]
	v_mfma_f32_16x16x32_bf16 v[52:55], v[138:141], v[168:171], v[52:55]
	v_mfma_f32_16x16x32_bf16 v[48:51], v[146:149], v[168:171], v[48:51]
	v_mfma_f32_16x16x32_bf16 v[44:47], v[138:141], v[176:179], v[44:47]
	v_mfma_f32_16x16x32_bf16 v[36:39], v[146:149], v[176:179], v[36:39]
	v_mfma_f32_16x16x32_bf16 v[28:31], v[138:141], v[194:197], v[28:31]
	v_mfma_f32_16x16x32_bf16 v[20:23], v[146:149], v[194:197], v[20:23]
	v_mfma_f32_16x16x32_bf16 v[12:15], v[138:141], v[202:205], v[12:15]
	v_mfma_f32_16x16x32_bf16 v[4:7], v[146:149], v[202:205], v[4:7]
	s_barrier
	s_add_u32 s26, s26, 0xb0080
	s_addc_u32 s27, s27, 0
	s_mov_b32 m0, s56
	v_lshl_add_u64 v[134:135], s[26:27], 0, v[154:155]
	global_load_lds_dwordx4 v[134:135], off
	s_mov_b32 m0, s57
	v_lshl_add_u64 v[134:135], s[26:27], 0, v[158:159]
	global_load_lds_dwordx4 v[134:135], off
	s_waitcnt vmcnt(6)
	s_barrier
	v_mfma_f32_16x16x32_bf16 v[60:63], v[206:209], v[164:167], v[60:63]
	v_mfma_f32_16x16x32_bf16 v[56:59], v[214:217], v[164:167], v[56:59]
	v_mfma_f32_16x16x32_bf16 v[40:43], v[206:209], v[172:175], v[40:43]
	v_mfma_f32_16x16x32_bf16 v[32:35], v[214:217], v[172:175], v[32:35]
	v_mfma_f32_16x16x32_bf16 v[24:27], v[206:209], v[190:193], v[24:27]
	v_mfma_f32_16x16x32_bf16 v[16:19], v[214:217], v[190:193], v[16:19]
	v_mfma_f32_16x16x32_bf16 v[8:11], v[206:209], v[198:201], v[8:11]
	v_mfma_f32_16x16x32_bf16 v[0:3], v[214:217], v[198:201], v[0:3]
	v_mfma_f32_16x16x32_bf16 v[60:63], v[210:213], v[168:171], v[60:63]
	v_mfma_f32_16x16x32_bf16 v[56:59], v[222:225], v[168:171], v[56:59]
	v_mfma_f32_16x16x32_bf16 v[40:43], v[210:213], v[176:179], v[40:43]
	v_mfma_f32_16x16x32_bf16 v[32:35], v[222:225], v[176:179], v[32:35]
	v_mfma_f32_16x16x32_bf16 v[24:27], v[210:213], v[194:197], v[24:27]
	v_mfma_f32_16x16x32_bf16 v[16:19], v[222:225], v[194:197], v[16:19]
	v_mfma_f32_16x16x32_bf16 v[8:11], v[210:213], v[202:205], v[8:11]
	v_mfma_f32_16x16x32_bf16 v[0:3], v[222:225], v[202:205], v[0:3]
	s_add_i32 s58, s58, 2
	s_add_u32 s24, s24, 0x100
	s_addc_u32 s25, s25, 0
	s_cmp_gt_u32 s58, 41
	s_barrier
; __device__ __forceinline__ unsigned pk2(float lo, float hi) { unsigned r; asm volatile("v_cvt_pk_bf16_f32 %0, %1, %2" : "=v"(r) : "v"(lo), "v"(hi)); return r; }
; __device__ __forceinline__ unsigned pk2(float lo, float hi) { return f2bf(lo) | (f2bf(hi) << 16); }
;     __device__ __forceinline__ void epi(const f32x4 (&acc)[2][2][4][2], const Unit& u, int wr, int wc, int fr, int fq) const {
;     ...
;         ConvHost<3> ch; ch.begin(cj, u.g, 22, wr * 4 + wc, fq * 16 + fr);
;         const int row0 = u.pm * 256 + wr * 64 + fr, col0 = u.pn * 256 + wc * 32 + 8 * fq;
; #pragma unroll
;         for (int ai = 0; ai < 2; ++ai) {
;             u32x4 xo[4][2];
; #pragma unroll
;             for (int m = 0; m < 4; ++m)
; #pragma unroll
;                 for (int bj = 0; bj < 2; ++bj) xo[m][bj] = *(const u32x4*)(xb + (size_t)(row0 + ai * 128 + m * 16) * D + col0 + bj * 128);
; #pragma unroll
;             for (int m = 0; m < 4; ++m) {
;                 const int row = row0 + ai * 128 + m * 16; const size_t off = (size_t)row * D + col0; float ss = 0.f;
; #pragma unroll
;                 for (int bj = 0; bj < 2; ++bj) {
;                     const u32x4 o = xo[m][bj]; const f32x4 a0v = acc[ai][bj][m][0], a1v = acc[ai][bj][m][1];
;                     const float v0 = bf_lo(o.x) + coef * a0v[0], v1 = bf_hi(o.x) + coef * a0v[1], v2 = bf_lo(o.y) + coef * a0v[2], v3 = bf_hi(o.y) + coef * a0v[3];
;                     const float v4 = bf_lo(o.z) + coef * a1v[0], v5 = bf_hi(o.z) + coef * a1v[1], v6 = bf_lo(o.w) + coef * a1v[2], v7 = bf_hi(o.w) + coef * a1v[3];
;                     u32x4 w; w.x = pk2(v0, v1); w.y = pk2(v2, v3); w.z = pk2(v4, v5); w.w = pk2(v6, v7);
;                     *(u32x4*)(xb + off + bj * 128) = w;
;                     ss += ((v0 * v0 + v1 * v1) + (v2 * v2 + v3 * v3)) + ((v4 * v4 + v5 * v5) + (v6 * v6 + v7 * v7));
;                 }
;                 ss += __shfl_xor(ss, 16); ss += __shfl_xor(ss, 32);
;                 if (fq == 0) rowss[(size_t)row * 32 + u.pn * 4 + wc] = ss;
	v_lshl_or_b32 v164, s30, 8, v184
	v_lshl_add_u32 v168, s2, 8, v182
	v_ashrrev_i32_e32 v165, 31, v164
	v_lshlrev_b64 v[198:199], 1, v[164:165]
	v_ashrrev_i32_e32 v169, 31, v168
	v_lshl_add_u64 v[166:167], s[0:1], 0, v[198:199]
	v_lshlrev_b64 v[200:201], 11, v[168:169]
	v_lshl_add_u64 v[128:129], v[166:167], 0, v[200:201]
	v_mov_b32_e32 v218, 0x40000
	v_mov_b32_e32 v219, 0
	v_lshl_add_u64 v[216:217], v[128:129], 0, v[218:219]
	v_mov_b32_e32 v218, 0x8000
	s_waitcnt vmcnt(8)
	v_mov_b64_e32 v[190:191], v[232:233]
	v_mov_b64_e32 v[192:193], v[234:235]
	v_mov_b64_e32 v[194:195], v[236:237]
	v_mov_b64_e32 v[196:197], v[238:239]
	v_or_b32_e32 v178, 16, v168
	v_or_b32_e32 v174, 32, v168
	v_or_b32_e32 v170, 48, v168
	v_ashrrev_i32_e32 v179, 31, v178
	v_ashrrev_i32_e32 v175, 31, v174
	v_ashrrev_i32_e32 v171, 31, v170
	v_lshlrev_b64 v[180:181], 11, v[178:179]
	v_lshlrev_b64 v[176:177], 11, v[174:175]
	v_lshlrev_b64 v[172:173], 11, v[170:171]
	v_lshl_add_u64 v[128:129], v[166:167], 0, v[180:181]
	v_lshl_add_u64 v[130:131], v[166:167], 0, v[176:177]
	v_lshl_add_u64 v[202:203], v[166:167], 0, v[172:173]
	v_mov_b64_e32 v[148:149], v[240:241]
	v_mov_b64_e32 v[150:151], v[242:243]
	v_mov_b64_e32 v[144:145], v[244:245]
	v_mov_b64_e32 v[146:147], v[246:247]
	global_load_dwordx4 v[140:143], v[130:131], off
	global_load_dwordx4 v[136:139], v[130:131], off offset:256
	global_load_dwordx4 v[132:135], v[202:203], off
	s_nop 0
	global_load_dwordx4 v[128:131], v[202:203], off offset:256
	global_load_dwordx4 v[222:225], v[216:217], off
	global_load_dwordx4 v[226:229], v[216:217], off offset:256
	v_lshl_add_u64 v[216:217], v[216:217], 0, v[218:219]
	global_load_dwordx4 v[230:233], v[216:217], off
	global_load_dwordx4 v[234:237], v[216:217], off offset:256
	v_lshl_add_u64 v[216:217], v[216:217], 0, v[218:219]
	global_load_dwordx4 v[238:241], v[216:217], off
	global_load_dwordx4 v[242:245], v[216:217], off offset:256
	v_lshl_add_u64 v[216:217], v[216:217], 0, v[218:219]
	global_load_dwordx4 v[246:249], v[216:217], off
	global_load_dwordx4 v[250:253], v[216:217], off offset:256
	v_and_b32_e32 v202, 64, v188
	v_xor_b32_e32 v189, 16, v188
	v_add_u32_e32 v202, 64, v202
	v_cmp_lt_i32_e32 vcc, v189, v202
	v_lshlrev_b32_e32 v203, 16, v190
	v_and_b32_e32 v190, 0xffff0000, v190
	v_lshlrev_b32_e32 v204, 16, v191
	v_and_b32_e32 v191, 0xffff0000, v191
	v_lshlrev_b32_e32 v205, 16, v192
	v_and_b32_e32 v192, 0xffff0000, v192
	v_lshlrev_b32_e32 v206, 16, v193
	v_and_b32_e32 v193, 0xffff0000, v193
	v_lshlrev_b32_e32 v207, 16, v194
	v_and_b32_e32 v194, 0xffff0000, v194
	v_lshlrev_b32_e32 v208, 16, v195
	v_and_b32_e32 v195, 0xffff0000, v195
	v_lshlrev_b32_e32 v209, 16, v196
	v_and_b32_e32 v196, 0xffff0000, v196
	v_lshlrev_b32_e32 v210, 16, v197
	v_and_b32_e32 v197, 0xffff0000, v197
	v_fmac_f32_e32 v190, 0.5, v117
	v_fmac_f32_e32 v191, 0.5, v119
	v_fmac_f32_e32 v192, 0.5, v113
	v_fmac_f32_e32 v193, 0.5, v115
	v_fmac_f32_e32 v194, 0.5, v125
	v_fmac_f32_e32 v195, 0.5, v127
	v_fmac_f32_e32 v196, 0.5, v121
	v_fmac_f32_e32 v197, 0.5, v123
	v_fmac_f32_e32 v203, 0.5, v116
	v_fmac_f32_e32 v204, 0.5, v118
	v_fmac_f32_e32 v205, 0.5, v112
	v_fmac_f32_e32 v206, 0.5, v114
	v_fmac_f32_e32 v207, 0.5, v124
	v_fmac_f32_e32 v208, 0.5, v126
	v_fmac_f32_e32 v209, 0.5, v120
	v_fmac_f32_e32 v210, 0.5, v122
	v_mul_f32_e32 v112, v190, v190
	v_mul_f32_e32 v113, v191, v191
	v_mul_f32_e32 v118, v192, v192
	v_mul_f32_e32 v119, v193, v193
	v_mul_f32_e32 v120, v194, v194
	v_mul_f32_e32 v121, v195, v195
	v_mul_f32_e32 v122, v196, v196
	v_mul_f32_e32 v123, v197, v197
	v_fmac_f32_e32 v112, v203, v203
	v_fmac_f32_e32 v113, v204, v204
	v_fmac_f32_e32 v118, v205, v205
	v_fmac_f32_e32 v119, v206, v206
	v_fmac_f32_e32 v120, v207, v207
	v_fmac_f32_e32 v121, v208, v208
	v_fmac_f32_e32 v122, v209, v209
	v_fmac_f32_e32 v123, v210, v210
	v_add_f32_e32 v112, v112, v113
	v_add_f32_e32 v113, v118, v119
	v_add_f32_e32 v118, v120, v121
	v_add_f32_e32 v119, v122, v123
	v_cndmask_b32_e32 v189, v188, v189, vcc
	v_add_f32_e32 v112, v112, v113
	v_add_f32_e32 v113, v118, v119
	v_add_f32_e32 v113, v112, v113
	v_lshlrev_b32_e32 v112, 2, v189
	ds_bpermute_b32 v122, v112, v113
	v_lshl_add_u64 v[118:119], s[0:1], 0, v[200:201]
	v_cvt_pk_bf16_f32 v114, v203, v190
	v_lshl_add_u64 v[120:121], v[118:119], 0, v[198:199]
	v_cvt_pk_bf16_f32 v115, v204, v191
	v_cvt_pk_bf16_f32 v116, v205, v192
	v_cvt_pk_bf16_f32 v117, v206, v193
	global_store_dwordx4 v[120:121], v[114:117], off
	s_waitcnt lgkmcnt(0)
	s_nop 0
	v_add_f32_e32 v114, v113, v122
	v_xor_b32_e32 v113, 32, v188
	v_cmp_lt_i32_e32 vcc, v113, v202
	v_cvt_pk_bf16_f32 v116, v207, v194
	v_cvt_pk_bf16_f32 v117, v208, v195
	v_cvt_pk_bf16_f32 v118, v209, v196
	v_cvt_pk_bf16_f32 v119, v210, v197
	global_store_dwordx4 v[120:121], v[116:119], off offset:256
	s_nop 0
	v_cndmask_b32_e32 v113, v188, v113, vcc
	v_lshlrev_b32_e32 v113, 2, v113
	ds_bpermute_b32 v115, v113, v114
	s_and_saveexec_b64 s[20:21], s[4:5]
	s_cbranch_execz .LBB0_1909
	s_waitcnt lgkmcnt(0)
	v_add_f32_e32 v116, v114, v115
	s_lshl_b32 s22, s30, 2
	v_lshlrev_b64 v[114:115], 7, v[168:169]
	s_ashr_i32 s23, s22, 31
	v_lshl_add_u64 v[114:115], s[8:9], 0, v[114:115]
	v_lshl_add_u64 v[114:115], s[22:23], 2, v[114:115]
	s_lshl_b32 s2, s41, 2
	v_lshl_add_u64 v[114:115], v[114:115], 0, s[2:3]
	global_store_dword v[114:115], v116, off
